# K-loop MFMA issue order v2: accumulator pairs back to back, tiles in a snake over the fragment grid, k order alternating (each MFMA shares its accumulator or one operand fragment with its predecessor)
# speedup vs baseline: 1.0181x; 1.0074x over previous
.LBB0_140:
	s_ashr_i32 s37, s36, 31
	s_lshl_b64 s[42:43], s[36:37], 19
	s_add_u32 s42, s62, s42
	s_addc_u32 s43, s63, s43
	s_and_b64 s[44:45], s[0:1], exec
	s_cselect_b32 s37, s43, s49
	s_cselect_b32 s77, s42, s48
	s_ashr_i32 s39, s38, 31
	s_lshl_b64 s[44:45], s[38:39], 19
	s_add_u32 s44, s54, s44
	s_addc_u32 s45, s55, s45
	s_and_b64 s[52:53], s[0:1], exec
	s_cselect_b32 s39, s45, s51
	s_cselect_b32 s78, s44, s50
	s_add_u32 s48, s48, 0x40080
	s_addc_u32 s49, s49, 0
	s_add_u32 s79, s50, 0x100
	s_addc_u32 s80, s51, 0
	s_mov_b32 s81, -2
	ds_read_b128 v[150:153], v147
	ds_read_b128 v[154:157], v147 offset:1024
	ds_read_b128 v[158:161], v147 offset:2048
	ds_read_b128 v[162:165], v147 offset:3072
	ds_read_b128 v[166:169], v148
	ds_read_b128 v[170:173], v148 offset:1024
	ds_read_b128 v[174:177], v148 offset:2048
	ds_read_b128 v[178:181], v148 offset:3072
	s_add_u32 s50, s48, 0xfffc0080
	s_addc_u32 s51, s49, -1
	s_cmp_eq_u32 s81, 12
	s_cselect_b32 s53, s37, s51
	s_cselect_b32 s52, s77, s50
	s_cselect_b32 s51, s39, s80
	s_cselect_b32 s50, s78, s79
	v_lshl_add_u64 v[214:215], s[48:49], 0, v[136:137]
	s_add_i32 m0, s47, 0xc000
	ds_read_b128 v[182:185], v149
	ds_read_b128 v[186:189], v149 offset:1024
	ds_read_b128 v[190:193], v149 offset:2048
	ds_read_b128 v[194:197], v149 offset:3072
	ds_read_b128 v[198:201], v149 offset:4096
	ds_read_b128 v[202:205], v149 offset:5120
	ds_read_b128 v[206:209], v149 offset:6144
	ds_read_b128 v[210:213], v149 offset:7168
	global_load_lds_dwordx4 v[214:215], off
	v_lshl_add_u64 v[214:215], s[48:49], 0, v[138:139]
	s_add_i32 m0, s47, 0xe000
	s_nop 0
	global_load_lds_dwordx4 v[214:215], off
	s_waitcnt vmcnt(8)
	s_waitcnt lgkmcnt(0)
	s_setprio 1
	s_barrier
	v_mfma_f32_16x16x32_bf16 v[124:127], v[150:153], v[182:185], 0
	v_mfma_f32_16x16x32_bf16 v[124:127], v[154:157], v[186:189], v[124:127]
	v_mfma_f32_16x16x32_bf16 v[116:119], v[162:165], v[186:189], 0
	v_mfma_f32_16x16x32_bf16 v[116:119], v[158:161], v[182:185], v[116:119]
	v_mfma_f32_16x16x32_bf16 v[100:103], v[158:161], v[190:193], 0
	v_mfma_f32_16x16x32_bf16 v[100:103], v[162:165], v[194:197], v[100:103]
	v_mfma_f32_16x16x32_bf16 v[108:111], v[154:157], v[194:197], 0
	v_mfma_f32_16x16x32_bf16 v[108:111], v[150:153], v[190:193], v[108:111]
	v_mfma_f32_16x16x32_bf16 v[92:95], v[150:153], v[198:201], 0
	v_mfma_f32_16x16x32_bf16 v[92:95], v[154:157], v[202:205], v[92:95]
	v_mfma_f32_16x16x32_bf16 v[84:87], v[162:165], v[202:205], 0
	v_mfma_f32_16x16x32_bf16 v[84:87], v[158:161], v[198:201], v[84:87]
	v_mfma_f32_16x16x32_bf16 v[68:71], v[158:161], v[206:209], 0
	v_mfma_f32_16x16x32_bf16 v[68:71], v[162:165], v[210:213], v[68:71]
	v_mfma_f32_16x16x32_bf16 v[76:79], v[154:157], v[210:213], 0
	v_mfma_f32_16x16x32_bf16 v[76:79], v[150:153], v[206:209], v[76:79]
	v_mfma_f32_16x16x32_bf16 v[72:75], v[166:169], v[206:209], 0
	v_mfma_f32_16x16x32_bf16 v[72:75], v[170:173], v[210:213], v[72:75]
	v_mfma_f32_16x16x32_bf16 v[64:67], v[178:181], v[210:213], 0
	v_mfma_f32_16x16x32_bf16 v[64:67], v[174:177], v[206:209], v[64:67]
	v_mfma_f32_16x16x32_bf16 v[80:83], v[174:177], v[198:201], 0
	v_mfma_f32_16x16x32_bf16 v[80:83], v[178:181], v[202:205], v[80:83]
	v_mfma_f32_16x16x32_bf16 v[88:91], v[170:173], v[202:205], 0
	v_mfma_f32_16x16x32_bf16 v[88:91], v[166:169], v[198:201], v[88:91]
	v_mfma_f32_16x16x32_bf16 v[104:107], v[166:169], v[190:193], 0
	v_mfma_f32_16x16x32_bf16 v[104:107], v[170:173], v[194:197], v[104:107]
	v_mfma_f32_16x16x32_bf16 v[96:99], v[178:181], v[194:197], 0
	v_mfma_f32_16x16x32_bf16 v[96:99], v[174:177], v[190:193], v[96:99]
	v_mfma_f32_16x16x32_bf16 v[112:115], v[174:177], v[182:185], 0
	v_mfma_f32_16x16x32_bf16 v[112:115], v[178:181], v[186:189], v[112:115]
	v_mfma_f32_16x16x32_bf16 v[120:123], v[170:173], v[186:189], 0
	v_mfma_f32_16x16x32_bf16 v[120:123], v[166:169], v[182:185], v[120:123]
	s_barrier
	s_setprio 0
	s_add_i32 s82, s73, s56
	v_lshl_add_u64 v[214:215], s[50:51], 0, v[132:133]
	s_mov_b32 m0, s82
	ds_read_b128 v[182:185], v149 offset:16384
	ds_read_b128 v[186:189], v149 offset:17408
	ds_read_b128 v[190:193], v149 offset:18432
	ds_read_b128 v[194:197], v149 offset:19456
	ds_read_b128 v[198:201], v149 offset:20480
	ds_read_b128 v[202:205], v149 offset:21504
	ds_read_b128 v[206:209], v149 offset:22528
	ds_read_b128 v[210:213], v149 offset:23552
	global_load_lds_dwordx4 v[214:215], off
	s_add_i32 m0, s82, 0x2000
	s_add_u32 s88, s50, 0x40000
	v_lshl_add_u64 v[216:217], s[50:51], 0, v[128:129]
	s_addc_u32 s89, s51, 0
	s_add_i32 s82, s74, s56
	global_load_lds_dwordx4 v[216:217], off
	v_lshl_add_u64 v[218:219], s[88:89], 0, v[132:133]
	s_mov_b32 m0, s82
	v_lshl_add_u64 v[220:221], s[52:53], 0, v[130:131]
	global_load_lds_dwordx4 v[218:219], off
	v_lshl_add_u64 v[218:219], s[88:89], 0, v[128:129]
	s_add_i32 m0, s82, 0x2000
	s_nop 0
	global_load_lds_dwordx4 v[218:219], off
	v_lshl_add_u64 v[218:219], s[52:53], 0, v[134:135]
	s_mov_b32 m0, s47
	s_nop 0
	global_load_lds_dwordx4 v[218:219], off
	s_mov_b32 m0, s59
	s_nop 0
	global_load_lds_dwordx4 v[220:221], off
	s_waitcnt vmcnt(8)
	s_waitcnt lgkmcnt(0)
	s_setprio 1
	s_barrier
	v_mfma_f32_16x16x32_bf16 v[60:63], v[150:153], v[182:185], 0
	v_mfma_f32_16x16x32_bf16 v[60:63], v[154:157], v[186:189], v[60:63]
	v_mfma_f32_16x16x32_bf16 v[52:55], v[162:165], v[186:189], 0
	v_mfma_f32_16x16x32_bf16 v[52:55], v[158:161], v[182:185], v[52:55]
	v_mfma_f32_16x16x32_bf16 v[36:39], v[158:161], v[190:193], 0
	v_mfma_f32_16x16x32_bf16 v[36:39], v[162:165], v[194:197], v[36:39]
	v_mfma_f32_16x16x32_bf16 v[44:47], v[154:157], v[194:197], 0
	v_mfma_f32_16x16x32_bf16 v[44:47], v[150:153], v[190:193], v[44:47]
	v_mfma_f32_16x16x32_bf16 v[28:31], v[150:153], v[198:201], 0
	v_mfma_f32_16x16x32_bf16 v[28:31], v[154:157], v[202:205], v[28:31]
	v_mfma_f32_16x16x32_bf16 v[20:23], v[162:165], v[202:205], 0
	v_mfma_f32_16x16x32_bf16 v[20:23], v[158:161], v[198:201], v[20:23]
	v_mfma_f32_16x16x32_bf16 v[4:7], v[158:161], v[206:209], 0
	v_mfma_f32_16x16x32_bf16 v[4:7], v[162:165], v[210:213], v[4:7]
	v_mfma_f32_16x16x32_bf16 v[12:15], v[154:157], v[210:213], 0
	v_mfma_f32_16x16x32_bf16 v[12:15], v[150:153], v[206:209], v[12:15]
	v_mfma_f32_16x16x32_bf16 v[8:11], v[166:169], v[206:209], 0
	v_mfma_f32_16x16x32_bf16 v[8:11], v[170:173], v[210:213], v[8:11]
	v_mfma_f32_16x16x32_bf16 v[0:3], v[178:181], v[210:213], 0
	v_mfma_f32_16x16x32_bf16 v[0:3], v[174:177], v[206:209], v[0:3]
	v_mfma_f32_16x16x32_bf16 v[16:19], v[174:177], v[198:201], 0
	v_mfma_f32_16x16x32_bf16 v[16:19], v[178:181], v[202:205], v[16:19]
	v_mfma_f32_16x16x32_bf16 v[24:27], v[170:173], v[202:205], 0
	v_mfma_f32_16x16x32_bf16 v[24:27], v[166:169], v[198:201], v[24:27]
	v_mfma_f32_16x16x32_bf16 v[40:43], v[166:169], v[190:193], 0
	v_mfma_f32_16x16x32_bf16 v[40:43], v[170:173], v[194:197], v[40:43]
	v_mfma_f32_16x16x32_bf16 v[32:35], v[178:181], v[194:197], 0
	v_mfma_f32_16x16x32_bf16 v[32:35], v[174:177], v[190:193], v[32:35]
	v_mfma_f32_16x16x32_bf16 v[48:51], v[174:177], v[182:185], 0
	v_mfma_f32_16x16x32_bf16 v[48:51], v[178:181], v[186:189], v[48:51]
	v_mfma_f32_16x16x32_bf16 v[56:59], v[170:173], v[186:189], 0
	v_mfma_f32_16x16x32_bf16 v[56:59], v[166:169], v[182:185], v[56:59]
	s_barrier
	s_setprio 0
	s_add_i32 s82, 0, 0x18000
	s_add_i32 s85, 0, 0x1c000
	v_add_u32_e32 v162, s82, v145
	v_add_u32_e32 v178, s85, v145
	ds_read_b128 v[150:153], v162
	ds_read_b128 v[154:157], v162 offset:1024
	ds_read_b128 v[158:161], v162 offset:2048
	ds_read_b128 v[162:165], v162 offset:3072
	ds_read_b128 v[166:169], v178
	ds_read_b128 v[170:173], v178 offset:1024
	ds_read_b128 v[174:177], v178 offset:2048
	ds_read_b128 v[178:181], v178 offset:3072
	s_add_u32 s52, s52, 0x40000
	s_addc_u32 s53, s53, 0
	s_mov_b32 m0, s66
	v_lshl_add_u64 v[222:223], s[52:53], 0, v[134:135]
	ds_read_b128 v[182:185], v149 offset:32768
	ds_read_b128 v[186:189], v149 offset:33792
	ds_read_b128 v[190:193], v149 offset:34816
	ds_read_b128 v[194:197], v149 offset:35840
	ds_read_b128 v[198:201], v149 offset:36864
	ds_read_b128 v[202:205], v149 offset:37888
	ds_read_b128 v[206:209], v149 offset:38912
	ds_read_b128 v[210:213], v149 offset:39936
	global_load_lds_dwordx4 v[222:223], off
	v_lshl_add_u64 v[222:223], s[52:53], 0, v[130:131]
	s_mov_b32 m0, s67
	s_nop 0
	global_load_lds_dwordx4 v[222:223], off
	s_waitcnt vmcnt(8)
	s_waitcnt lgkmcnt(0)
	s_setprio 1
	s_barrier
	v_mfma_f32_16x16x32_bf16 v[124:127], v[150:153], v[182:185], v[124:127]
	v_mfma_f32_16x16x32_bf16 v[124:127], v[154:157], v[186:189], v[124:127]
	v_mfma_f32_16x16x32_bf16 v[116:119], v[162:165], v[186:189], v[116:119]
	v_mfma_f32_16x16x32_bf16 v[116:119], v[158:161], v[182:185], v[116:119]
	v_mfma_f32_16x16x32_bf16 v[100:103], v[158:161], v[190:193], v[100:103]
	v_mfma_f32_16x16x32_bf16 v[100:103], v[162:165], v[194:197], v[100:103]
	v_mfma_f32_16x16x32_bf16 v[108:111], v[154:157], v[194:197], v[108:111]
	v_mfma_f32_16x16x32_bf16 v[108:111], v[150:153], v[190:193], v[108:111]
	v_mfma_f32_16x16x32_bf16 v[92:95], v[150:153], v[198:201], v[92:95]
	v_mfma_f32_16x16x32_bf16 v[92:95], v[154:157], v[202:205], v[92:95]
	v_mfma_f32_16x16x32_bf16 v[84:87], v[162:165], v[202:205], v[84:87]
	v_mfma_f32_16x16x32_bf16 v[84:87], v[158:161], v[198:201], v[84:87]
	v_mfma_f32_16x16x32_bf16 v[68:71], v[158:161], v[206:209], v[68:71]
	v_mfma_f32_16x16x32_bf16 v[68:71], v[162:165], v[210:213], v[68:71]
	v_mfma_f32_16x16x32_bf16 v[76:79], v[154:157], v[210:213], v[76:79]
	v_mfma_f32_16x16x32_bf16 v[76:79], v[150:153], v[206:209], v[76:79]
	v_mfma_f32_16x16x32_bf16 v[72:75], v[166:169], v[206:209], v[72:75]
	v_mfma_f32_16x16x32_bf16 v[72:75], v[170:173], v[210:213], v[72:75]
	v_mfma_f32_16x16x32_bf16 v[64:67], v[178:181], v[210:213], v[64:67]
	v_mfma_f32_16x16x32_bf16 v[64:67], v[174:177], v[206:209], v[64:67]
	v_mfma_f32_16x16x32_bf16 v[80:83], v[174:177], v[198:201], v[80:83]
	v_mfma_f32_16x16x32_bf16 v[80:83], v[178:181], v[202:205], v[80:83]
	v_mfma_f32_16x16x32_bf16 v[88:91], v[170:173], v[202:205], v[88:91]
	v_mfma_f32_16x16x32_bf16 v[88:91], v[166:169], v[198:201], v[88:91]
	v_mfma_f32_16x16x32_bf16 v[104:107], v[166:169], v[190:193], v[104:107]
	v_mfma_f32_16x16x32_bf16 v[104:107], v[170:173], v[194:197], v[104:107]
	v_mfma_f32_16x16x32_bf16 v[96:99], v[178:181], v[194:197], v[96:99]
	v_mfma_f32_16x16x32_bf16 v[96:99], v[174:177], v[190:193], v[96:99]
	v_mfma_f32_16x16x32_bf16 v[112:115], v[174:177], v[182:185], v[112:115]
	v_mfma_f32_16x16x32_bf16 v[112:115], v[178:181], v[186:189], v[112:115]
	v_mfma_f32_16x16x32_bf16 v[120:123], v[170:173], v[186:189], v[120:123]
	v_mfma_f32_16x16x32_bf16 v[120:123], v[166:169], v[182:185], v[120:123]
	s_barrier
	s_setprio 0
	s_add_i32 s52, s82, s56
	v_lshl_add_u64 v[214:215], v[214:215], 0, s[10:11]
	s_mov_b32 m0, s52
	ds_read_b128 v[182:185], v149 offset:49152
	ds_read_b128 v[186:189], v149 offset:50176
	ds_read_b128 v[190:193], v149 offset:51200
	ds_read_b128 v[194:197], v149 offset:52224
	ds_read_b128 v[198:201], v149 offset:53248
	ds_read_b128 v[202:205], v149 offset:54272
	ds_read_b128 v[206:209], v149 offset:55296
	ds_read_b128 v[210:213], v149 offset:56320
	global_load_lds_dwordx4 v[214:215], off
	s_add_i32 m0, s52, 0x2000
	s_add_u32 s50, s50, 0x40080
	v_lshl_add_u64 v[214:215], v[216:217], 0, s[10:11]
	s_addc_u32 s51, s51, 0
	s_add_i32 s52, s85, s56
	global_load_lds_dwordx4 v[214:215], off
	v_lshl_add_u64 v[214:215], s[50:51], 0, v[132:133]
	s_mov_b32 m0, s52
	s_nop 0
	global_load_lds_dwordx4 v[214:215], off
	v_lshl_add_u64 v[214:215], s[50:51], 0, v[128:129]
	s_add_i32 m0, s52, 0x2000
	s_nop 0
	global_load_lds_dwordx4 v[214:215], off
	v_lshl_add_u64 v[214:215], v[218:219], 0, s[10:11]
	s_mov_b32 m0, s69
	s_nop 0
	global_load_lds_dwordx4 v[214:215], off
	v_lshl_add_u64 v[214:215], v[220:221], 0, s[10:11]
	s_mov_b32 m0, s70
	s_nop 0
	global_load_lds_dwordx4 v[214:215], off
	s_waitcnt vmcnt(8)
	s_waitcnt lgkmcnt(0)
	s_setprio 1
	s_barrier
	v_mfma_f32_16x16x32_bf16 v[60:63], v[150:153], v[182:185], v[60:63]
	v_mfma_f32_16x16x32_bf16 v[60:63], v[154:157], v[186:189], v[60:63]
	v_mfma_f32_16x16x32_bf16 v[52:55], v[162:165], v[186:189], v[52:55]
	v_mfma_f32_16x16x32_bf16 v[52:55], v[158:161], v[182:185], v[52:55]
	v_mfma_f32_16x16x32_bf16 v[36:39], v[158:161], v[190:193], v[36:39]
	v_mfma_f32_16x16x32_bf16 v[36:39], v[162:165], v[194:197], v[36:39]
	v_mfma_f32_16x16x32_bf16 v[44:47], v[154:157], v[194:197], v[44:47]
	v_mfma_f32_16x16x32_bf16 v[44:47], v[150:153], v[190:193], v[44:47]
	v_mfma_f32_16x16x32_bf16 v[28:31], v[150:153], v[198:201], v[28:31]
	v_mfma_f32_16x16x32_bf16 v[28:31], v[154:157], v[202:205], v[28:31]
	v_mfma_f32_16x16x32_bf16 v[20:23], v[162:165], v[202:205], v[20:23]
	v_mfma_f32_16x16x32_bf16 v[20:23], v[158:161], v[198:201], v[20:23]
	v_mfma_f32_16x16x32_bf16 v[4:7], v[158:161], v[206:209], v[4:7]
	v_mfma_f32_16x16x32_bf16 v[4:7], v[162:165], v[210:213], v[4:7]
	v_mfma_f32_16x16x32_bf16 v[12:15], v[154:157], v[210:213], v[12:15]
	v_mfma_f32_16x16x32_bf16 v[12:15], v[150:153], v[206:209], v[12:15]
	v_mfma_f32_16x16x32_bf16 v[8:11], v[166:169], v[206:209], v[8:11]
	v_mfma_f32_16x16x32_bf16 v[8:11], v[170:173], v[210:213], v[8:11]
	v_mfma_f32_16x16x32_bf16 v[0:3], v[178:181], v[210:213], v[0:3]
	v_mfma_f32_16x16x32_bf16 v[0:3], v[174:177], v[206:209], v[0:3]
	v_mfma_f32_16x16x32_bf16 v[16:19], v[174:177], v[198:201], v[16:19]
	v_mfma_f32_16x16x32_bf16 v[16:19], v[178:181], v[202:205], v[16:19]
	v_mfma_f32_16x16x32_bf16 v[24:27], v[170:173], v[202:205], v[24:27]
	v_mfma_f32_16x16x32_bf16 v[24:27], v[166:169], v[198:201], v[24:27]
	v_mfma_f32_16x16x32_bf16 v[40:43], v[166:169], v[190:193], v[40:43]
	v_mfma_f32_16x16x32_bf16 v[40:43], v[170:173], v[194:197], v[40:43]
	v_mfma_f32_16x16x32_bf16 v[32:35], v[178:181], v[194:197], v[32:35]
	v_mfma_f32_16x16x32_bf16 v[32:35], v[174:177], v[190:193], v[32:35]
	v_mfma_f32_16x16x32_bf16 v[48:51], v[174:177], v[182:185], v[48:51]
	v_mfma_f32_16x16x32_bf16 v[48:51], v[178:181], v[186:189], v[48:51]
	v_mfma_f32_16x16x32_bf16 v[56:59], v[170:173], v[186:189], v[56:59]
	v_mfma_f32_16x16x32_bf16 v[56:59], v[166:169], v[182:185], v[56:59]
	s_barrier
	s_setprio 0
	s_add_i32 s81, s81, 2
	s_add_u32 s48, s48, 0x100
	s_addc_u32 s49, s49, 0
	s_add_u32 s79, s79, 0x100
	s_addc_u32 s80, s80, 0
	s_cmp_gt_u32 s81, 13
.LBB0_141:
	ds_read_b128 v[150:153], v147
	ds_read_b128 v[154:157], v147 offset:1024
	ds_read_b128 v[158:161], v147 offset:2048
	ds_read_b128 v[162:165], v147 offset:3072
	ds_read_b128 v[166:169], v148
	ds_read_b128 v[170:173], v148 offset:1024
	ds_read_b128 v[174:177], v148 offset:2048
	ds_read_b128 v[178:181], v148 offset:3072
	s_add_u32 s50, s48, 0xfffc0080
	s_addc_u32 s51, s49, -1
	s_cmp_eq_u32 s81, 12
	s_cselect_b32 s53, s37, s51
	s_cselect_b32 s52, s77, s50
	s_cselect_b32 s51, s39, s80
	s_cselect_b32 s50, s78, s79
	v_lshl_add_u64 v[214:215], s[48:49], 0, v[136:137]
	s_add_i32 m0, s47, 0xc000
	ds_read_b128 v[182:185], v149
	ds_read_b128 v[186:189], v149 offset:1024
	ds_read_b128 v[190:193], v149 offset:2048
	ds_read_b128 v[194:197], v149 offset:3072
	ds_read_b128 v[198:201], v149 offset:4096
	ds_read_b128 v[202:205], v149 offset:5120
	ds_read_b128 v[206:209], v149 offset:6144
	ds_read_b128 v[210:213], v149 offset:7168
	global_load_lds_dwordx4 v[214:215], off
	v_lshl_add_u64 v[214:215], s[48:49], 0, v[138:139]
	s_add_i32 m0, s47, 0xe000
	s_nop 0
	global_load_lds_dwordx4 v[214:215], off
	s_waitcnt vmcnt(8)
	s_waitcnt lgkmcnt(0)
	s_setprio 1
	s_barrier
	v_mfma_f32_16x16x32_bf16 v[124:127], v[150:153], v[182:185], v[124:127]
	v_mfma_f32_16x16x32_bf16 v[124:127], v[154:157], v[186:189], v[124:127]
	v_mfma_f32_16x16x32_bf16 v[116:119], v[162:165], v[186:189], v[116:119]
	v_mfma_f32_16x16x32_bf16 v[116:119], v[158:161], v[182:185], v[116:119]
	v_mfma_f32_16x16x32_bf16 v[100:103], v[158:161], v[190:193], v[100:103]
	v_mfma_f32_16x16x32_bf16 v[100:103], v[162:165], v[194:197], v[100:103]
	v_mfma_f32_16x16x32_bf16 v[108:111], v[154:157], v[194:197], v[108:111]
	v_mfma_f32_16x16x32_bf16 v[108:111], v[150:153], v[190:193], v[108:111]
	v_mfma_f32_16x16x32_bf16 v[92:95], v[150:153], v[198:201], v[92:95]
	v_mfma_f32_16x16x32_bf16 v[92:95], v[154:157], v[202:205], v[92:95]
	v_mfma_f32_16x16x32_bf16 v[84:87], v[162:165], v[202:205], v[84:87]
	v_mfma_f32_16x16x32_bf16 v[84:87], v[158:161], v[198:201], v[84:87]
	v_mfma_f32_16x16x32_bf16 v[68:71], v[158:161], v[206:209], v[68:71]
	v_mfma_f32_16x16x32_bf16 v[68:71], v[162:165], v[210:213], v[68:71]
	v_mfma_f32_16x16x32_bf16 v[76:79], v[154:157], v[210:213], v[76:79]
	v_mfma_f32_16x16x32_bf16 v[76:79], v[150:153], v[206:209], v[76:79]
	v_mfma_f32_16x16x32_bf16 v[72:75], v[166:169], v[206:209], v[72:75]
	v_mfma_f32_16x16x32_bf16 v[72:75], v[170:173], v[210:213], v[72:75]
	v_mfma_f32_16x16x32_bf16 v[64:67], v[178:181], v[210:213], v[64:67]
	v_mfma_f32_16x16x32_bf16 v[64:67], v[174:177], v[206:209], v[64:67]
	v_mfma_f32_16x16x32_bf16 v[80:83], v[174:177], v[198:201], v[80:83]
	v_mfma_f32_16x16x32_bf16 v[80:83], v[178:181], v[202:205], v[80:83]
	v_mfma_f32_16x16x32_bf16 v[88:91], v[170:173], v[202:205], v[88:91]
	v_mfma_f32_16x16x32_bf16 v[88:91], v[166:169], v[198:201], v[88:91]
	v_mfma_f32_16x16x32_bf16 v[104:107], v[166:169], v[190:193], v[104:107]
	v_mfma_f32_16x16x32_bf16 v[104:107], v[170:173], v[194:197], v[104:107]
	v_mfma_f32_16x16x32_bf16 v[96:99], v[178:181], v[194:197], v[96:99]
	v_mfma_f32_16x16x32_bf16 v[96:99], v[174:177], v[190:193], v[96:99]
	v_mfma_f32_16x16x32_bf16 v[112:115], v[174:177], v[182:185], v[112:115]
	v_mfma_f32_16x16x32_bf16 v[112:115], v[178:181], v[186:189], v[112:115]
	v_mfma_f32_16x16x32_bf16 v[120:123], v[170:173], v[186:189], v[120:123]
	v_mfma_f32_16x16x32_bf16 v[120:123], v[166:169], v[182:185], v[120:123]
	s_barrier
	s_setprio 0
	s_add_i32 s82, s73, s56
	v_lshl_add_u64 v[214:215], s[50:51], 0, v[132:133]
	s_mov_b32 m0, s82
	ds_read_b128 v[182:185], v149 offset:16384
	ds_read_b128 v[186:189], v149 offset:17408
	ds_read_b128 v[190:193], v149 offset:18432
	ds_read_b128 v[194:197], v149 offset:19456
	ds_read_b128 v[198:201], v149 offset:20480
	ds_read_b128 v[202:205], v149 offset:21504
	ds_read_b128 v[206:209], v149 offset:22528
	ds_read_b128 v[210:213], v149 offset:23552
	global_load_lds_dwordx4 v[214:215], off
	s_add_i32 m0, s82, 0x2000
	s_add_u32 s88, s50, 0x40000
	v_lshl_add_u64 v[216:217], s[50:51], 0, v[128:129]
	s_addc_u32 s89, s51, 0
	s_add_i32 s82, s74, s56
	global_load_lds_dwordx4 v[216:217], off
	v_lshl_add_u64 v[218:219], s[88:89], 0, v[132:133]
	s_mov_b32 m0, s82
	v_lshl_add_u64 v[220:221], s[52:53], 0, v[130:131]
	global_load_lds_dwordx4 v[218:219], off
	v_lshl_add_u64 v[218:219], s[88:89], 0, v[128:129]
	s_add_i32 m0, s82, 0x2000
	s_nop 0
	global_load_lds_dwordx4 v[218:219], off
	v_lshl_add_u64 v[218:219], s[52:53], 0, v[134:135]
	s_mov_b32 m0, s47
	s_nop 0
	global_load_lds_dwordx4 v[218:219], off
	s_mov_b32 m0, s59
	s_nop 0
	global_load_lds_dwordx4 v[220:221], off
	s_waitcnt vmcnt(8)
	s_waitcnt lgkmcnt(0)
	s_setprio 1
	s_barrier
	v_mfma_f32_16x16x32_bf16 v[60:63], v[150:153], v[182:185], v[60:63]
	v_mfma_f32_16x16x32_bf16 v[60:63], v[154:157], v[186:189], v[60:63]
	v_mfma_f32_16x16x32_bf16 v[52:55], v[162:165], v[186:189], v[52:55]
	v_mfma_f32_16x16x32_bf16 v[52:55], v[158:161], v[182:185], v[52:55]
	v_mfma_f32_16x16x32_bf16 v[36:39], v[158:161], v[190:193], v[36:39]
	v_mfma_f32_16x16x32_bf16 v[36:39], v[162:165], v[194:197], v[36:39]
	v_mfma_f32_16x16x32_bf16 v[44:47], v[154:157], v[194:197], v[44:47]
	v_mfma_f32_16x16x32_bf16 v[44:47], v[150:153], v[190:193], v[44:47]
	v_mfma_f32_16x16x32_bf16 v[28:31], v[150:153], v[198:201], v[28:31]
	v_mfma_f32_16x16x32_bf16 v[28:31], v[154:157], v[202:205], v[28:31]
	v_mfma_f32_16x16x32_bf16 v[20:23], v[162:165], v[202:205], v[20:23]
	v_mfma_f32_16x16x32_bf16 v[20:23], v[158:161], v[198:201], v[20:23]
	v_mfma_f32_16x16x32_bf16 v[4:7], v[158:161], v[206:209], v[4:7]
	v_mfma_f32_16x16x32_bf16 v[4:7], v[162:165], v[210:213], v[4:7]
	v_mfma_f32_16x16x32_bf16 v[12:15], v[154:157], v[210:213], v[12:15]
	v_mfma_f32_16x16x32_bf16 v[12:15], v[150:153], v[206:209], v[12:15]
	v_mfma_f32_16x16x32_bf16 v[8:11], v[166:169], v[206:209], v[8:11]
	v_mfma_f32_16x16x32_bf16 v[8:11], v[170:173], v[210:213], v[8:11]
	v_mfma_f32_16x16x32_bf16 v[0:3], v[178:181], v[210:213], v[0:3]
	v_mfma_f32_16x16x32_bf16 v[0:3], v[174:177], v[206:209], v[0:3]
	v_mfma_f32_16x16x32_bf16 v[16:19], v[174:177], v[198:201], v[16:19]
	v_mfma_f32_16x16x32_bf16 v[16:19], v[178:181], v[202:205], v[16:19]
	v_mfma_f32_16x16x32_bf16 v[24:27], v[170:173], v[202:205], v[24:27]
	v_mfma_f32_16x16x32_bf16 v[24:27], v[166:169], v[198:201], v[24:27]
	v_mfma_f32_16x16x32_bf16 v[40:43], v[166:169], v[190:193], v[40:43]
	v_mfma_f32_16x16x32_bf16 v[40:43], v[170:173], v[194:197], v[40:43]
	v_mfma_f32_16x16x32_bf16 v[32:35], v[178:181], v[194:197], v[32:35]
	v_mfma_f32_16x16x32_bf16 v[32:35], v[174:177], v[190:193], v[32:35]
	v_mfma_f32_16x16x32_bf16 v[48:51], v[174:177], v[182:185], v[48:51]
	v_mfma_f32_16x16x32_bf16 v[48:51], v[178:181], v[186:189], v[48:51]
	v_mfma_f32_16x16x32_bf16 v[56:59], v[170:173], v[186:189], v[56:59]
	v_mfma_f32_16x16x32_bf16 v[56:59], v[166:169], v[182:185], v[56:59]
	s_barrier
	s_setprio 0
	s_add_i32 s82, 0, 0x18000
	s_add_i32 s85, 0, 0x1c000
	v_add_u32_e32 v162, s82, v145
	v_add_u32_e32 v178, s85, v145
	ds_read_b128 v[150:153], v162
	ds_read_b128 v[154:157], v162 offset:1024
	ds_read_b128 v[158:161], v162 offset:2048
	ds_read_b128 v[162:165], v162 offset:3072
	ds_read_b128 v[166:169], v178
	ds_read_b128 v[170:173], v178 offset:1024
	ds_read_b128 v[174:177], v178 offset:2048
	ds_read_b128 v[178:181], v178 offset:3072
	s_add_u32 s52, s52, 0x40000
	s_addc_u32 s53, s53, 0
	s_mov_b32 m0, s66
	v_lshl_add_u64 v[222:223], s[52:53], 0, v[134:135]
	ds_read_b128 v[182:185], v149 offset:32768
	ds_read_b128 v[186:189], v149 offset:33792
	ds_read_b128 v[190:193], v149 offset:34816
	ds_read_b128 v[194:197], v149 offset:35840
	ds_read_b128 v[198:201], v149 offset:36864
	ds_read_b128 v[202:205], v149 offset:37888
	ds_read_b128 v[206:209], v149 offset:38912
	ds_read_b128 v[210:213], v149 offset:39936
	global_load_lds_dwordx4 v[222:223], off
	v_lshl_add_u64 v[222:223], s[52:53], 0, v[130:131]
	s_mov_b32 m0, s67
	s_nop 0
	global_load_lds_dwordx4 v[222:223], off
	s_waitcnt vmcnt(8)
	s_waitcnt lgkmcnt(0)
	s_setprio 1
	s_barrier
	v_mfma_f32_16x16x32_bf16 v[124:127], v[150:153], v[182:185], v[124:127]
	v_mfma_f32_16x16x32_bf16 v[124:127], v[154:157], v[186:189], v[124:127]
	v_mfma_f32_16x16x32_bf16 v[116:119], v[162:165], v[186:189], v[116:119]
	v_mfma_f32_16x16x32_bf16 v[116:119], v[158:161], v[182:185], v[116:119]
	v_mfma_f32_16x16x32_bf16 v[100:103], v[158:161], v[190:193], v[100:103]
	v_mfma_f32_16x16x32_bf16 v[100:103], v[162:165], v[194:197], v[100:103]
	v_mfma_f32_16x16x32_bf16 v[108:111], v[154:157], v[194:197], v[108:111]
	v_mfma_f32_16x16x32_bf16 v[108:111], v[150:153], v[190:193], v[108:111]
	v_mfma_f32_16x16x32_bf16 v[92:95], v[150:153], v[198:201], v[92:95]
	v_mfma_f32_16x16x32_bf16 v[92:95], v[154:157], v[202:205], v[92:95]
	v_mfma_f32_16x16x32_bf16 v[84:87], v[162:165], v[202:205], v[84:87]
	v_mfma_f32_16x16x32_bf16 v[84:87], v[158:161], v[198:201], v[84:87]
	v_mfma_f32_16x16x32_bf16 v[68:71], v[158:161], v[206:209], v[68:71]
	v_mfma_f32_16x16x32_bf16 v[68:71], v[162:165], v[210:213], v[68:71]
	v_mfma_f32_16x16x32_bf16 v[76:79], v[154:157], v[210:213], v[76:79]
	v_mfma_f32_16x16x32_bf16 v[76:79], v[150:153], v[206:209], v[76:79]
	v_mfma_f32_16x16x32_bf16 v[72:75], v[166:169], v[206:209], v[72:75]
	v_mfma_f32_16x16x32_bf16 v[72:75], v[170:173], v[210:213], v[72:75]
	v_mfma_f32_16x16x32_bf16 v[64:67], v[178:181], v[210:213], v[64:67]
	v_mfma_f32_16x16x32_bf16 v[64:67], v[174:177], v[206:209], v[64:67]
	v_mfma_f32_16x16x32_bf16 v[80:83], v[174:177], v[198:201], v[80:83]
	v_mfma_f32_16x16x32_bf16 v[80:83], v[178:181], v[202:205], v[80:83]
	v_mfma_f32_16x16x32_bf16 v[88:91], v[170:173], v[202:205], v[88:91]
	v_mfma_f32_16x16x32_bf16 v[88:91], v[166:169], v[198:201], v[88:91]
	v_mfma_f32_16x16x32_bf16 v[104:107], v[166:169], v[190:193], v[104:107]
	v_mfma_f32_16x16x32_bf16 v[104:107], v[170:173], v[194:197], v[104:107]
	v_mfma_f32_16x16x32_bf16 v[96:99], v[178:181], v[194:197], v[96:99]
	v_mfma_f32_16x16x32_bf16 v[96:99], v[174:177], v[190:193], v[96:99]
	v_mfma_f32_16x16x32_bf16 v[112:115], v[174:177], v[182:185], v[112:115]
	v_mfma_f32_16x16x32_bf16 v[112:115], v[178:181], v[186:189], v[112:115]
	v_mfma_f32_16x16x32_bf16 v[120:123], v[170:173], v[186:189], v[120:123]
	v_mfma_f32_16x16x32_bf16 v[120:123], v[166:169], v[182:185], v[120:123]
	s_barrier
	s_setprio 0
	s_add_i32 s52, s82, s56
	v_lshl_add_u64 v[214:215], v[214:215], 0, s[10:11]
	s_mov_b32 m0, s52
	ds_read_b128 v[182:185], v149 offset:49152
	ds_read_b128 v[186:189], v149 offset:50176
	ds_read_b128 v[190:193], v149 offset:51200
	ds_read_b128 v[194:197], v149 offset:52224
	ds_read_b128 v[198:201], v149 offset:53248
	ds_read_b128 v[202:205], v149 offset:54272
	ds_read_b128 v[206:209], v149 offset:55296
	ds_read_b128 v[210:213], v149 offset:56320
	global_load_lds_dwordx4 v[214:215], off
	s_add_i32 m0, s52, 0x2000
	s_add_u32 s50, s50, 0x40080
	v_lshl_add_u64 v[214:215], v[216:217], 0, s[10:11]
	s_addc_u32 s51, s51, 0
	s_add_i32 s52, s85, s56
	global_load_lds_dwordx4 v[214:215], off
	v_lshl_add_u64 v[214:215], s[50:51], 0, v[132:133]
	s_mov_b32 m0, s52
	s_nop 0
	global_load_lds_dwordx4 v[214:215], off
	v_lshl_add_u64 v[214:215], s[50:51], 0, v[128:129]
	s_add_i32 m0, s52, 0x2000
	s_nop 0
	global_load_lds_dwordx4 v[214:215], off
	v_lshl_add_u64 v[214:215], v[218:219], 0, s[10:11]
	s_mov_b32 m0, s69
	s_nop 0
	global_load_lds_dwordx4 v[214:215], off
	v_lshl_add_u64 v[214:215], v[220:221], 0, s[10:11]
	s_mov_b32 m0, s70
	s_nop 0
	global_load_lds_dwordx4 v[214:215], off
	s_waitcnt vmcnt(8)
	s_waitcnt lgkmcnt(0)
	s_setprio 1
	s_barrier
	v_mfma_f32_16x16x32_bf16 v[60:63], v[150:153], v[182:185], v[60:63]
	v_mfma_f32_16x16x32_bf16 v[60:63], v[154:157], v[186:189], v[60:63]
	v_mfma_f32_16x16x32_bf16 v[52:55], v[162:165], v[186:189], v[52:55]
	v_mfma_f32_16x16x32_bf16 v[52:55], v[158:161], v[182:185], v[52:55]
	v_mfma_f32_16x16x32_bf16 v[36:39], v[158:161], v[190:193], v[36:39]
	v_mfma_f32_16x16x32_bf16 v[36:39], v[162:165], v[194:197], v[36:39]
	v_mfma_f32_16x16x32_bf16 v[44:47], v[154:157], v[194:197], v[44:47]
	v_mfma_f32_16x16x32_bf16 v[44:47], v[150:153], v[190:193], v[44:47]
	v_mfma_f32_16x16x32_bf16 v[28:31], v[150:153], v[198:201], v[28:31]
	v_mfma_f32_16x16x32_bf16 v[28:31], v[154:157], v[202:205], v[28:31]
	v_mfma_f32_16x16x32_bf16 v[20:23], v[162:165], v[202:205], v[20:23]
	v_mfma_f32_16x16x32_bf16 v[20:23], v[158:161], v[198:201], v[20:23]
	v_mfma_f32_16x16x32_bf16 v[4:7], v[158:161], v[206:209], v[4:7]
	v_mfma_f32_16x16x32_bf16 v[4:7], v[162:165], v[210:213], v[4:7]
	v_mfma_f32_16x16x32_bf16 v[12:15], v[154:157], v[210:213], v[12:15]
	v_mfma_f32_16x16x32_bf16 v[12:15], v[150:153], v[206:209], v[12:15]
	v_mfma_f32_16x16x32_bf16 v[8:11], v[166:169], v[206:209], v[8:11]
	v_mfma_f32_16x16x32_bf16 v[8:11], v[170:173], v[210:213], v[8:11]
	v_mfma_f32_16x16x32_bf16 v[0:3], v[178:181], v[210:213], v[0:3]
	v_mfma_f32_16x16x32_bf16 v[0:3], v[174:177], v[206:209], v[0:3]
	v_mfma_f32_16x16x32_bf16 v[16:19], v[174:177], v[198:201], v[16:19]
	v_mfma_f32_16x16x32_bf16 v[16:19], v[178:181], v[202:205], v[16:19]
	v_mfma_f32_16x16x32_bf16 v[24:27], v[170:173], v[202:205], v[24:27]
	v_mfma_f32_16x16x32_bf16 v[24:27], v[166:169], v[198:201], v[24:27]
	v_mfma_f32_16x16x32_bf16 v[40:43], v[166:169], v[190:193], v[40:43]
	v_mfma_f32_16x16x32_bf16 v[40:43], v[170:173], v[194:197], v[40:43]
	v_mfma_f32_16x16x32_bf16 v[32:35], v[178:181], v[194:197], v[32:35]
	v_mfma_f32_16x16x32_bf16 v[32:35], v[174:177], v[190:193], v[32:35]
	v_mfma_f32_16x16x32_bf16 v[48:51], v[174:177], v[182:185], v[48:51]
	v_mfma_f32_16x16x32_bf16 v[48:51], v[178:181], v[186:189], v[48:51]
	v_mfma_f32_16x16x32_bf16 v[56:59], v[170:173], v[186:189], v[56:59]
	v_mfma_f32_16x16x32_bf16 v[56:59], v[166:169], v[182:185], v[56:59]
	s_barrier
	s_setprio 0
	s_add_i32 s81, s81, 2
	s_add_u32 s48, s48, 0x100
	s_addc_u32 s49, s49, 0
	s_add_u32 s79, s79, 0x100
	s_addc_u32 s80, s80, 0
	s_cmp_gt_u32 s81, 13
	s_cbranch_scc0 .LBB0_141
	s_and_b64 vcc, exec, s[26:27]
	s_cbranch_vccz .LBB0_144
	s_barrier

.LBB0_220:
	s_add_u32 s95, s52, 0x100
	s_addc_u32 s96, s53, 0
	s_mov_b32 s97, -2
	ds_read_b128 v[88:91], v233
	ds_read_b128 v[92:95], v233 offset:1024
	ds_read_b128 v[112:115], v233 offset:2048
	ds_read_b128 v[116:119], v233 offset:3072
	ds_read_b128 v[132:135], v234
	ds_read_b128 v[136:139], v234 offset:1024
	ds_read_b128 v[152:155], v234 offset:2048
	ds_read_b128 v[156:159], v234 offset:3072
	s_add_u32 s52, s50, 0x100
	s_addc_u32 s53, s51, 0
	s_cmp_eq_u32 s97, 40
	s_cselect_b32 s57, s9, s53
	s_cselect_b32 s56, s8, s52
	s_cselect_b32 s55, s41, s96
	s_cselect_b32 s54, s40, s95
	v_lshl_add_u64 v[216:217], s[50:51], 0, v[196:197]
	s_add_i32 m0, s67, 0xc000
	ds_read_b128 v[160:163], v235
	ds_read_b128 v[164:167], v235 offset:1024
	ds_read_b128 v[168:171], v235 offset:2048
	ds_read_b128 v[172:175], v235 offset:3072
	ds_read_b128 v[176:179], v235 offset:4096
	ds_read_b128 v[180:183], v235 offset:5120
	ds_read_b128 v[208:211], v235 offset:6144
	ds_read_b128 v[212:215], v235 offset:7168
	global_load_lds_dwordx4 v[216:217], off
	v_lshl_add_u64 v[216:217], s[50:51], 0, v[198:199]
	s_add_i32 m0, s67, 0xe000
	s_nop 0
	global_load_lds_dwordx4 v[216:217], off
	s_waitcnt vmcnt(8)
	s_waitcnt lgkmcnt(0)
	s_setprio 1
	s_barrier
	v_mfma_f32_16x16x32_bf16 v[148:151], v[88:91], v[160:163], 0
	v_mfma_f32_16x16x32_bf16 v[148:151], v[92:95], v[164:167], v[148:151]
	v_mfma_f32_16x16x32_bf16 v[144:147], v[116:119], v[164:167], 0
	v_mfma_f32_16x16x32_bf16 v[144:147], v[112:115], v[160:163], v[144:147]
	v_mfma_f32_16x16x32_bf16 v[120:123], v[112:115], v[168:171], 0
	v_mfma_f32_16x16x32_bf16 v[120:123], v[116:119], v[172:175], v[120:123]
	v_mfma_f32_16x16x32_bf16 v[124:127], v[92:95], v[172:175], 0
	v_mfma_f32_16x16x32_bf16 v[124:127], v[88:91], v[168:171], v[124:127]
	v_mfma_f32_16x16x32_bf16 v[100:103], v[88:91], v[176:179], 0
	v_mfma_f32_16x16x32_bf16 v[100:103], v[92:95], v[180:183], v[100:103]
	v_mfma_f32_16x16x32_bf16 v[96:99], v[116:119], v[180:183], 0
	v_mfma_f32_16x16x32_bf16 v[96:99], v[112:115], v[176:179], v[96:99]
	v_mfma_f32_16x16x32_bf16 v[72:75], v[112:115], v[208:211], 0
	v_mfma_f32_16x16x32_bf16 v[72:75], v[116:119], v[212:215], v[72:75]
	v_mfma_f32_16x16x32_bf16 v[76:79], v[92:95], v[212:215], 0
	v_mfma_f32_16x16x32_bf16 v[76:79], v[88:91], v[208:211], v[76:79]
	v_mfma_f32_16x16x32_bf16 v[68:71], v[132:135], v[208:211], 0
	v_mfma_f32_16x16x32_bf16 v[68:71], v[136:139], v[212:215], v[68:71]
	v_mfma_f32_16x16x32_bf16 v[64:67], v[156:159], v[212:215], 0
	v_mfma_f32_16x16x32_bf16 v[64:67], v[152:155], v[208:211], v[64:67]
	v_mfma_f32_16x16x32_bf16 v[80:83], v[152:155], v[176:179], 0
	v_mfma_f32_16x16x32_bf16 v[80:83], v[156:159], v[180:183], v[80:83]
	v_mfma_f32_16x16x32_bf16 v[84:87], v[136:139], v[180:183], 0
	v_mfma_f32_16x16x32_bf16 v[84:87], v[132:135], v[176:179], v[84:87]
	v_mfma_f32_16x16x32_bf16 v[108:111], v[132:135], v[168:171], 0
	v_mfma_f32_16x16x32_bf16 v[108:111], v[136:139], v[172:175], v[108:111]
	v_mfma_f32_16x16x32_bf16 v[104:107], v[156:159], v[172:175], 0
	v_mfma_f32_16x16x32_bf16 v[104:107], v[152:155], v[168:171], v[104:107]
	v_mfma_f32_16x16x32_bf16 v[128:131], v[152:155], v[160:163], 0
	v_mfma_f32_16x16x32_bf16 v[128:131], v[156:159], v[164:167], v[128:131]
	v_mfma_f32_16x16x32_bf16 v[140:143], v[136:139], v[164:167], 0
	v_mfma_f32_16x16x32_bf16 v[140:143], v[132:135], v[160:163], v[140:143]
	s_barrier
	s_setprio 0
	s_add_i32 s50, s82, s66
	v_lshl_add_u64 v[216:217], s[54:55], 0, v[186:187]
	s_mov_b32 m0, s50
	ds_read_b128 v[160:163], v235 offset:16384
	ds_read_b128 v[164:167], v235 offset:17408
	ds_read_b128 v[168:171], v235 offset:18432
	ds_read_b128 v[172:175], v235 offset:19456
	ds_read_b128 v[176:179], v235 offset:20480
	ds_read_b128 v[180:183], v235 offset:21504
	ds_read_b128 v[208:211], v235 offset:22528
	ds_read_b128 v[212:215], v235 offset:23552
	global_load_lds_dwordx4 v[216:217], off
	s_add_i32 m0, s50, 0x2000
	s_add_u32 s50, s54, 0xb0000
	v_lshl_add_u64 v[218:219], s[54:55], 0, v[190:191]
	s_addc_u32 s51, s55, 0
	s_add_i32 vcc_lo, s85, s66
	global_load_lds_dwordx4 v[218:219], off
	v_lshl_add_u64 v[220:221], s[50:51], 0, v[186:187]
	s_mov_b32 m0, vcc_lo
	v_lshl_add_u64 v[222:223], s[56:57], 0, v[188:189]
	global_load_lds_dwordx4 v[220:221], off
	v_lshl_add_u64 v[220:221], s[50:51], 0, v[190:191]
	s_add_i32 m0, vcc_lo, 0x2000
	s_nop 0
	global_load_lds_dwordx4 v[220:221], off
	v_lshl_add_u64 v[220:221], s[56:57], 0, v[184:185]
	s_mov_b32 m0, s67
	s_nop 0
	global_load_lds_dwordx4 v[220:221], off
	s_mov_b32 m0, s68
	s_nop 0
	global_load_lds_dwordx4 v[222:223], off
	s_waitcnt vmcnt(8)
	s_waitcnt lgkmcnt(0)
	s_setprio 1
	s_barrier
	v_mfma_f32_16x16x32_bf16 v[60:63], v[88:91], v[160:163], 0
	v_mfma_f32_16x16x32_bf16 v[60:63], v[92:95], v[164:167], v[60:63]
	v_mfma_f32_16x16x32_bf16 v[56:59], v[116:119], v[164:167], 0
	v_mfma_f32_16x16x32_bf16 v[56:59], v[112:115], v[160:163], v[56:59]
	v_mfma_f32_16x16x32_bf16 v[40:43], v[112:115], v[168:171], 0
	v_mfma_f32_16x16x32_bf16 v[40:43], v[116:119], v[172:175], v[40:43]
	v_mfma_f32_16x16x32_bf16 v[44:47], v[92:95], v[172:175], 0
	v_mfma_f32_16x16x32_bf16 v[44:47], v[88:91], v[168:171], v[44:47]
	v_mfma_f32_16x16x32_bf16 v[28:31], v[88:91], v[176:179], 0
	v_mfma_f32_16x16x32_bf16 v[28:31], v[92:95], v[180:183], v[28:31]
	v_mfma_f32_16x16x32_bf16 v[24:27], v[116:119], v[180:183], 0
	v_mfma_f32_16x16x32_bf16 v[24:27], v[112:115], v[176:179], v[24:27]
	v_mfma_f32_16x16x32_bf16 v[8:11], v[112:115], v[208:211], 0
	v_mfma_f32_16x16x32_bf16 v[8:11], v[116:119], v[212:215], v[8:11]
	v_mfma_f32_16x16x32_bf16 v[12:15], v[92:95], v[212:215], 0
	v_mfma_f32_16x16x32_bf16 v[12:15], v[88:91], v[208:211], v[12:15]
	v_mfma_f32_16x16x32_bf16 v[4:7], v[132:135], v[208:211], 0
	v_mfma_f32_16x16x32_bf16 v[4:7], v[136:139], v[212:215], v[4:7]
	v_mfma_f32_16x16x32_bf16 v[0:3], v[156:159], v[212:215], 0
	v_mfma_f32_16x16x32_bf16 v[0:3], v[152:155], v[208:211], v[0:3]
	v_mfma_f32_16x16x32_bf16 v[16:19], v[152:155], v[176:179], 0
	v_mfma_f32_16x16x32_bf16 v[16:19], v[156:159], v[180:183], v[16:19]
	v_mfma_f32_16x16x32_bf16 v[20:23], v[136:139], v[180:183], 0
	v_mfma_f32_16x16x32_bf16 v[20:23], v[132:135], v[176:179], v[20:23]
	v_mfma_f32_16x16x32_bf16 v[36:39], v[132:135], v[168:171], 0
	v_mfma_f32_16x16x32_bf16 v[36:39], v[136:139], v[172:175], v[36:39]
	v_mfma_f32_16x16x32_bf16 v[32:35], v[156:159], v[172:175], 0
	v_mfma_f32_16x16x32_bf16 v[32:35], v[152:155], v[168:171], v[32:35]
	v_mfma_f32_16x16x32_bf16 v[48:51], v[152:155], v[160:163], 0
	v_mfma_f32_16x16x32_bf16 v[48:51], v[156:159], v[164:167], v[48:51]
	v_mfma_f32_16x16x32_bf16 v[52:55], v[136:139], v[164:167], 0
	v_mfma_f32_16x16x32_bf16 v[52:55], v[132:135], v[160:163], v[52:55]
	s_barrier
	s_setprio 0
	s_add_i32 vcc_lo, 0, 0x18000
	s_add_i32 vcc_hi, 0, 0x1c000
	v_add_u32_e32 v116, vcc_lo, v230
	v_add_u32_e32 v156, vcc_hi, v230
	ds_read_b128 v[88:91], v116
	ds_read_b128 v[92:95], v116 offset:1024
	ds_read_b128 v[112:115], v116 offset:2048
	ds_read_b128 v[116:119], v116 offset:3072
	ds_read_b128 v[132:135], v156
	ds_read_b128 v[136:139], v156 offset:1024
	ds_read_b128 v[152:155], v156 offset:2048
	ds_read_b128 v[156:159], v156 offset:3072
	s_add_u32 s50, s56, 0xb0000
	s_addc_u32 s51, s57, 0
	s_mov_b32 m0, s69
	v_lshl_add_u64 v[224:225], s[50:51], 0, v[184:185]
	ds_read_b128 v[160:163], v235 offset:32768
	ds_read_b128 v[164:167], v235 offset:33792
	ds_read_b128 v[168:171], v235 offset:34816
	ds_read_b128 v[172:175], v235 offset:35840
	ds_read_b128 v[176:179], v235 offset:36864
	ds_read_b128 v[180:183], v235 offset:37888
	ds_read_b128 v[208:211], v235 offset:38912
	ds_read_b128 v[212:215], v235 offset:39936
	global_load_lds_dwordx4 v[224:225], off
	v_lshl_add_u64 v[224:225], s[50:51], 0, v[188:189]
	s_mov_b32 m0, s70
	s_nop 0
	global_load_lds_dwordx4 v[224:225], off
	s_waitcnt vmcnt(8)
	s_waitcnt lgkmcnt(0)
	s_setprio 1
	s_barrier
	v_mfma_f32_16x16x32_bf16 v[148:151], v[88:91], v[160:163], v[148:151]
	v_mfma_f32_16x16x32_bf16 v[148:151], v[92:95], v[164:167], v[148:151]
	v_mfma_f32_16x16x32_bf16 v[144:147], v[116:119], v[164:167], v[144:147]
	v_mfma_f32_16x16x32_bf16 v[144:147], v[112:115], v[160:163], v[144:147]
	v_mfma_f32_16x16x32_bf16 v[120:123], v[112:115], v[168:171], v[120:123]
	v_mfma_f32_16x16x32_bf16 v[120:123], v[116:119], v[172:175], v[120:123]
	v_mfma_f32_16x16x32_bf16 v[124:127], v[92:95], v[172:175], v[124:127]
	v_mfma_f32_16x16x32_bf16 v[124:127], v[88:91], v[168:171], v[124:127]
	v_mfma_f32_16x16x32_bf16 v[100:103], v[88:91], v[176:179], v[100:103]
	v_mfma_f32_16x16x32_bf16 v[100:103], v[92:95], v[180:183], v[100:103]
	v_mfma_f32_16x16x32_bf16 v[96:99], v[116:119], v[180:183], v[96:99]
	v_mfma_f32_16x16x32_bf16 v[96:99], v[112:115], v[176:179], v[96:99]
	v_mfma_f32_16x16x32_bf16 v[72:75], v[112:115], v[208:211], v[72:75]
	v_mfma_f32_16x16x32_bf16 v[72:75], v[116:119], v[212:215], v[72:75]
	v_mfma_f32_16x16x32_bf16 v[76:79], v[92:95], v[212:215], v[76:79]
	v_mfma_f32_16x16x32_bf16 v[76:79], v[88:91], v[208:211], v[76:79]
	v_mfma_f32_16x16x32_bf16 v[68:71], v[132:135], v[208:211], v[68:71]
	v_mfma_f32_16x16x32_bf16 v[68:71], v[136:139], v[212:215], v[68:71]
	v_mfma_f32_16x16x32_bf16 v[64:67], v[156:159], v[212:215], v[64:67]
	v_mfma_f32_16x16x32_bf16 v[64:67], v[152:155], v[208:211], v[64:67]
	v_mfma_f32_16x16x32_bf16 v[80:83], v[152:155], v[176:179], v[80:83]
	v_mfma_f32_16x16x32_bf16 v[80:83], v[156:159], v[180:183], v[80:83]
	v_mfma_f32_16x16x32_bf16 v[84:87], v[136:139], v[180:183], v[84:87]
	v_mfma_f32_16x16x32_bf16 v[84:87], v[132:135], v[176:179], v[84:87]
	v_mfma_f32_16x16x32_bf16 v[108:111], v[132:135], v[168:171], v[108:111]
	v_mfma_f32_16x16x32_bf16 v[108:111], v[136:139], v[172:175], v[108:111]
	v_mfma_f32_16x16x32_bf16 v[104:107], v[156:159], v[172:175], v[104:107]
	v_mfma_f32_16x16x32_bf16 v[104:107], v[152:155], v[168:171], v[104:107]
	v_mfma_f32_16x16x32_bf16 v[128:131], v[152:155], v[160:163], v[128:131]
	v_mfma_f32_16x16x32_bf16 v[128:131], v[156:159], v[164:167], v[128:131]
	v_mfma_f32_16x16x32_bf16 v[140:143], v[136:139], v[164:167], v[140:143]
	v_mfma_f32_16x16x32_bf16 v[140:143], v[132:135], v[160:163], v[140:143]
	s_barrier
	s_setprio 0
	s_add_i32 s50, vcc_lo, s66
	v_lshl_add_u64 v[216:217], v[216:217], 0, s[46:47]
	s_mov_b32 m0, s50
	ds_read_b128 v[160:163], v235 offset:49152
	ds_read_b128 v[164:167], v235 offset:50176
	ds_read_b128 v[168:171], v235 offset:51200
	ds_read_b128 v[172:175], v235 offset:52224
	ds_read_b128 v[176:179], v235 offset:53248
	ds_read_b128 v[180:183], v235 offset:54272
	ds_read_b128 v[208:211], v235 offset:55296
	ds_read_b128 v[212:215], v235 offset:56320
	global_load_lds_dwordx4 v[216:217], off
	s_add_i32 m0, s50, 0x2000
	s_add_u32 s50, s54, 0xb0080
	v_lshl_add_u64 v[216:217], v[218:219], 0, s[46:47]
	s_addc_u32 s51, s55, 0
	s_add_i32 s54, vcc_hi, s66
	global_load_lds_dwordx4 v[216:217], off
	v_lshl_add_u64 v[216:217], s[50:51], 0, v[186:187]
	s_mov_b32 m0, s54
	s_nop 0
	global_load_lds_dwordx4 v[216:217], off
	v_lshl_add_u64 v[216:217], s[50:51], 0, v[190:191]
	s_add_i32 m0, s54, 0x2000
	s_nop 0
	global_load_lds_dwordx4 v[216:217], off
	v_lshl_add_u64 v[216:217], v[220:221], 0, s[46:47]
	s_mov_b32 m0, s74
	s_nop 0
	global_load_lds_dwordx4 v[216:217], off
	v_lshl_add_u64 v[216:217], v[222:223], 0, s[46:47]
	s_mov_b32 m0, s75
	s_nop 0
	global_load_lds_dwordx4 v[216:217], off
	s_waitcnt vmcnt(8)
	s_waitcnt lgkmcnt(0)
	s_setprio 1
	s_barrier
	v_mfma_f32_16x16x32_bf16 v[60:63], v[88:91], v[160:163], v[60:63]
	v_mfma_f32_16x16x32_bf16 v[60:63], v[92:95], v[164:167], v[60:63]
	v_mfma_f32_16x16x32_bf16 v[56:59], v[116:119], v[164:167], v[56:59]
	v_mfma_f32_16x16x32_bf16 v[56:59], v[112:115], v[160:163], v[56:59]
	v_mfma_f32_16x16x32_bf16 v[40:43], v[112:115], v[168:171], v[40:43]
	v_mfma_f32_16x16x32_bf16 v[40:43], v[116:119], v[172:175], v[40:43]
	v_mfma_f32_16x16x32_bf16 v[44:47], v[92:95], v[172:175], v[44:47]
	v_mfma_f32_16x16x32_bf16 v[44:47], v[88:91], v[168:171], v[44:47]
	v_mfma_f32_16x16x32_bf16 v[28:31], v[88:91], v[176:179], v[28:31]
	v_mfma_f32_16x16x32_bf16 v[28:31], v[92:95], v[180:183], v[28:31]
	v_mfma_f32_16x16x32_bf16 v[24:27], v[116:119], v[180:183], v[24:27]
	v_mfma_f32_16x16x32_bf16 v[24:27], v[112:115], v[176:179], v[24:27]
	v_mfma_f32_16x16x32_bf16 v[8:11], v[112:115], v[208:211], v[8:11]
	v_mfma_f32_16x16x32_bf16 v[8:11], v[116:119], v[212:215], v[8:11]
	v_mfma_f32_16x16x32_bf16 v[12:15], v[92:95], v[212:215], v[12:15]
	v_mfma_f32_16x16x32_bf16 v[12:15], v[88:91], v[208:211], v[12:15]
	v_mfma_f32_16x16x32_bf16 v[4:7], v[132:135], v[208:211], v[4:7]
	v_mfma_f32_16x16x32_bf16 v[4:7], v[136:139], v[212:215], v[4:7]
	v_mfma_f32_16x16x32_bf16 v[0:3], v[156:159], v[212:215], v[0:3]
	v_mfma_f32_16x16x32_bf16 v[0:3], v[152:155], v[208:211], v[0:3]
	v_mfma_f32_16x16x32_bf16 v[16:19], v[152:155], v[176:179], v[16:19]
	v_mfma_f32_16x16x32_bf16 v[16:19], v[156:159], v[180:183], v[16:19]
	v_mfma_f32_16x16x32_bf16 v[20:23], v[136:139], v[180:183], v[20:23]
	v_mfma_f32_16x16x32_bf16 v[20:23], v[132:135], v[176:179], v[20:23]
	v_mfma_f32_16x16x32_bf16 v[36:39], v[132:135], v[168:171], v[36:39]
	v_mfma_f32_16x16x32_bf16 v[36:39], v[136:139], v[172:175], v[36:39]
	v_mfma_f32_16x16x32_bf16 v[32:35], v[156:159], v[172:175], v[32:35]
	v_mfma_f32_16x16x32_bf16 v[32:35], v[152:155], v[168:171], v[32:35]
	v_mfma_f32_16x16x32_bf16 v[48:51], v[152:155], v[160:163], v[48:51]
	v_mfma_f32_16x16x32_bf16 v[48:51], v[156:159], v[164:167], v[48:51]
	v_mfma_f32_16x16x32_bf16 v[52:55], v[136:139], v[164:167], v[52:55]
	v_mfma_f32_16x16x32_bf16 v[52:55], v[132:135], v[160:163], v[52:55]
	s_barrier
	s_setprio 0
	s_add_i32 s97, s97, 2
	s_add_u32 s95, s95, 0x100
	s_addc_u32 s96, s96, 0
	s_cmp_gt_u32 s97, 41
	s_mov_b64 s[50:51], s[52:53]
.LBB0_221:
	ds_read_b128 v[88:91], v233
	ds_read_b128 v[92:95], v233 offset:1024
	ds_read_b128 v[112:115], v233 offset:2048
	ds_read_b128 v[116:119], v233 offset:3072
	ds_read_b128 v[132:135], v234
	ds_read_b128 v[136:139], v234 offset:1024
	ds_read_b128 v[152:155], v234 offset:2048
	ds_read_b128 v[156:159], v234 offset:3072
	s_add_u32 s52, s50, 0x100
	s_addc_u32 s53, s51, 0
	s_cmp_eq_u32 s97, 40
	s_cselect_b32 s57, s9, s53
	s_cselect_b32 s56, s8, s52
	s_cselect_b32 s55, s41, s96
	s_cselect_b32 s54, s40, s95
	v_lshl_add_u64 v[216:217], s[50:51], 0, v[196:197]
	s_add_i32 m0, s67, 0xc000
	ds_read_b128 v[160:163], v235
	ds_read_b128 v[164:167], v235 offset:1024
	ds_read_b128 v[168:171], v235 offset:2048
	ds_read_b128 v[172:175], v235 offset:3072
	ds_read_b128 v[176:179], v235 offset:4096
	ds_read_b128 v[180:183], v235 offset:5120
	ds_read_b128 v[208:211], v235 offset:6144
	ds_read_b128 v[212:215], v235 offset:7168
	global_load_lds_dwordx4 v[216:217], off
	v_lshl_add_u64 v[216:217], s[50:51], 0, v[198:199]
	s_add_i32 m0, s67, 0xe000
	s_nop 0
	global_load_lds_dwordx4 v[216:217], off
	s_waitcnt vmcnt(8)
	s_waitcnt lgkmcnt(0)
	s_setprio 1
	s_barrier
	v_mfma_f32_16x16x32_bf16 v[148:151], v[88:91], v[160:163], v[148:151]
	v_mfma_f32_16x16x32_bf16 v[148:151], v[92:95], v[164:167], v[148:151]
	v_mfma_f32_16x16x32_bf16 v[144:147], v[116:119], v[164:167], v[144:147]
	v_mfma_f32_16x16x32_bf16 v[144:147], v[112:115], v[160:163], v[144:147]
	v_mfma_f32_16x16x32_bf16 v[120:123], v[112:115], v[168:171], v[120:123]
	v_mfma_f32_16x16x32_bf16 v[120:123], v[116:119], v[172:175], v[120:123]
	v_mfma_f32_16x16x32_bf16 v[124:127], v[92:95], v[172:175], v[124:127]
	v_mfma_f32_16x16x32_bf16 v[124:127], v[88:91], v[168:171], v[124:127]
	v_mfma_f32_16x16x32_bf16 v[100:103], v[88:91], v[176:179], v[100:103]
	v_mfma_f32_16x16x32_bf16 v[100:103], v[92:95], v[180:183], v[100:103]
	v_mfma_f32_16x16x32_bf16 v[96:99], v[116:119], v[180:183], v[96:99]
	v_mfma_f32_16x16x32_bf16 v[96:99], v[112:115], v[176:179], v[96:99]
	v_mfma_f32_16x16x32_bf16 v[72:75], v[112:115], v[208:211], v[72:75]
	v_mfma_f32_16x16x32_bf16 v[72:75], v[116:119], v[212:215], v[72:75]
	v_mfma_f32_16x16x32_bf16 v[76:79], v[92:95], v[212:215], v[76:79]
	v_mfma_f32_16x16x32_bf16 v[76:79], v[88:91], v[208:211], v[76:79]
	v_mfma_f32_16x16x32_bf16 v[68:71], v[132:135], v[208:211], v[68:71]
	v_mfma_f32_16x16x32_bf16 v[68:71], v[136:139], v[212:215], v[68:71]
	v_mfma_f32_16x16x32_bf16 v[64:67], v[156:159], v[212:215], v[64:67]
	v_mfma_f32_16x16x32_bf16 v[64:67], v[152:155], v[208:211], v[64:67]
	v_mfma_f32_16x16x32_bf16 v[80:83], v[152:155], v[176:179], v[80:83]
	v_mfma_f32_16x16x32_bf16 v[80:83], v[156:159], v[180:183], v[80:83]
	v_mfma_f32_16x16x32_bf16 v[84:87], v[136:139], v[180:183], v[84:87]
	v_mfma_f32_16x16x32_bf16 v[84:87], v[132:135], v[176:179], v[84:87]
	v_mfma_f32_16x16x32_bf16 v[108:111], v[132:135], v[168:171], v[108:111]
	v_mfma_f32_16x16x32_bf16 v[108:111], v[136:139], v[172:175], v[108:111]
	v_mfma_f32_16x16x32_bf16 v[104:107], v[156:159], v[172:175], v[104:107]
	v_mfma_f32_16x16x32_bf16 v[104:107], v[152:155], v[168:171], v[104:107]
	v_mfma_f32_16x16x32_bf16 v[128:131], v[152:155], v[160:163], v[128:131]
	v_mfma_f32_16x16x32_bf16 v[128:131], v[156:159], v[164:167], v[128:131]
	v_mfma_f32_16x16x32_bf16 v[140:143], v[136:139], v[164:167], v[140:143]
	v_mfma_f32_16x16x32_bf16 v[140:143], v[132:135], v[160:163], v[140:143]
	s_barrier
	s_setprio 0
	s_add_i32 s50, s82, s66
	v_lshl_add_u64 v[216:217], s[54:55], 0, v[186:187]
	s_mov_b32 m0, s50
	ds_read_b128 v[160:163], v235 offset:16384
	ds_read_b128 v[164:167], v235 offset:17408
	ds_read_b128 v[168:171], v235 offset:18432
	ds_read_b128 v[172:175], v235 offset:19456
	ds_read_b128 v[176:179], v235 offset:20480
	ds_read_b128 v[180:183], v235 offset:21504
	ds_read_b128 v[208:211], v235 offset:22528
	ds_read_b128 v[212:215], v235 offset:23552
	global_load_lds_dwordx4 v[216:217], off
	s_add_i32 m0, s50, 0x2000
	s_add_u32 s50, s54, 0xb0000
	v_lshl_add_u64 v[218:219], s[54:55], 0, v[190:191]
	s_addc_u32 s51, s55, 0
	s_add_i32 vcc_lo, s85, s66
	global_load_lds_dwordx4 v[218:219], off
	v_lshl_add_u64 v[220:221], s[50:51], 0, v[186:187]
	s_mov_b32 m0, vcc_lo
	v_lshl_add_u64 v[222:223], s[56:57], 0, v[188:189]
	global_load_lds_dwordx4 v[220:221], off
	v_lshl_add_u64 v[220:221], s[50:51], 0, v[190:191]
	s_add_i32 m0, vcc_lo, 0x2000
	s_nop 0
	global_load_lds_dwordx4 v[220:221], off
	v_lshl_add_u64 v[220:221], s[56:57], 0, v[184:185]
	s_mov_b32 m0, s67
	s_nop 0
	global_load_lds_dwordx4 v[220:221], off
	s_mov_b32 m0, s68
	s_nop 0
	global_load_lds_dwordx4 v[222:223], off
	s_waitcnt vmcnt(8)
	s_waitcnt lgkmcnt(0)
	s_setprio 1
	s_barrier
	v_mfma_f32_16x16x32_bf16 v[60:63], v[88:91], v[160:163], v[60:63]
	v_mfma_f32_16x16x32_bf16 v[60:63], v[92:95], v[164:167], v[60:63]
	v_mfma_f32_16x16x32_bf16 v[56:59], v[116:119], v[164:167], v[56:59]
	v_mfma_f32_16x16x32_bf16 v[56:59], v[112:115], v[160:163], v[56:59]
	v_mfma_f32_16x16x32_bf16 v[40:43], v[112:115], v[168:171], v[40:43]
	v_mfma_f32_16x16x32_bf16 v[40:43], v[116:119], v[172:175], v[40:43]
	v_mfma_f32_16x16x32_bf16 v[44:47], v[92:95], v[172:175], v[44:47]
	v_mfma_f32_16x16x32_bf16 v[44:47], v[88:91], v[168:171], v[44:47]
	v_mfma_f32_16x16x32_bf16 v[28:31], v[88:91], v[176:179], v[28:31]
	v_mfma_f32_16x16x32_bf16 v[28:31], v[92:95], v[180:183], v[28:31]
	v_mfma_f32_16x16x32_bf16 v[24:27], v[116:119], v[180:183], v[24:27]
	v_mfma_f32_16x16x32_bf16 v[24:27], v[112:115], v[176:179], v[24:27]
	v_mfma_f32_16x16x32_bf16 v[8:11], v[112:115], v[208:211], v[8:11]
	v_mfma_f32_16x16x32_bf16 v[8:11], v[116:119], v[212:215], v[8:11]
	v_mfma_f32_16x16x32_bf16 v[12:15], v[92:95], v[212:215], v[12:15]
	v_mfma_f32_16x16x32_bf16 v[12:15], v[88:91], v[208:211], v[12:15]
	v_mfma_f32_16x16x32_bf16 v[4:7], v[132:135], v[208:211], v[4:7]
	v_mfma_f32_16x16x32_bf16 v[4:7], v[136:139], v[212:215], v[4:7]
	v_mfma_f32_16x16x32_bf16 v[0:3], v[156:159], v[212:215], v[0:3]
	v_mfma_f32_16x16x32_bf16 v[0:3], v[152:155], v[208:211], v[0:3]
	v_mfma_f32_16x16x32_bf16 v[16:19], v[152:155], v[176:179], v[16:19]
	v_mfma_f32_16x16x32_bf16 v[16:19], v[156:159], v[180:183], v[16:19]
	v_mfma_f32_16x16x32_bf16 v[20:23], v[136:139], v[180:183], v[20:23]
	v_mfma_f32_16x16x32_bf16 v[20:23], v[132:135], v[176:179], v[20:23]
	v_mfma_f32_16x16x32_bf16 v[36:39], v[132:135], v[168:171], v[36:39]
	v_mfma_f32_16x16x32_bf16 v[36:39], v[136:139], v[172:175], v[36:39]
	v_mfma_f32_16x16x32_bf16 v[32:35], v[156:159], v[172:175], v[32:35]
	v_mfma_f32_16x16x32_bf16 v[32:35], v[152:155], v[168:171], v[32:35]
	v_mfma_f32_16x16x32_bf16 v[48:51], v[152:155], v[160:163], v[48:51]
	v_mfma_f32_16x16x32_bf16 v[48:51], v[156:159], v[164:167], v[48:51]
	v_mfma_f32_16x16x32_bf16 v[52:55], v[136:139], v[164:167], v[52:55]
	v_mfma_f32_16x16x32_bf16 v[52:55], v[132:135], v[160:163], v[52:55]
	s_barrier
	s_setprio 0
	s_add_i32 vcc_lo, 0, 0x18000
	s_add_i32 vcc_hi, 0, 0x1c000
	v_add_u32_e32 v116, vcc_lo, v230
	v_add_u32_e32 v156, vcc_hi, v230
	ds_read_b128 v[88:91], v116
	ds_read_b128 v[92:95], v116 offset:1024
	ds_read_b128 v[112:115], v116 offset:2048
	ds_read_b128 v[116:119], v116 offset:3072
	ds_read_b128 v[132:135], v156
	ds_read_b128 v[136:139], v156 offset:1024
	ds_read_b128 v[152:155], v156 offset:2048
	ds_read_b128 v[156:159], v156 offset:3072
	s_add_u32 s50, s56, 0xb0000
	s_addc_u32 s51, s57, 0
	s_mov_b32 m0, s69
	v_lshl_add_u64 v[224:225], s[50:51], 0, v[184:185]
	ds_read_b128 v[160:163], v235 offset:32768
	ds_read_b128 v[164:167], v235 offset:33792
	ds_read_b128 v[168:171], v235 offset:34816
	ds_read_b128 v[172:175], v235 offset:35840
	ds_read_b128 v[176:179], v235 offset:36864
	ds_read_b128 v[180:183], v235 offset:37888
	ds_read_b128 v[208:211], v235 offset:38912
	ds_read_b128 v[212:215], v235 offset:39936
	global_load_lds_dwordx4 v[224:225], off
	v_lshl_add_u64 v[224:225], s[50:51], 0, v[188:189]
	s_mov_b32 m0, s70
	s_nop 0
	global_load_lds_dwordx4 v[224:225], off
	s_waitcnt vmcnt(8)
	s_waitcnt lgkmcnt(0)
	s_setprio 1
	s_barrier
	v_mfma_f32_16x16x32_bf16 v[148:151], v[88:91], v[160:163], v[148:151]
	v_mfma_f32_16x16x32_bf16 v[148:151], v[92:95], v[164:167], v[148:151]
	v_mfma_f32_16x16x32_bf16 v[144:147], v[116:119], v[164:167], v[144:147]
	v_mfma_f32_16x16x32_bf16 v[144:147], v[112:115], v[160:163], v[144:147]
	v_mfma_f32_16x16x32_bf16 v[120:123], v[112:115], v[168:171], v[120:123]
	v_mfma_f32_16x16x32_bf16 v[120:123], v[116:119], v[172:175], v[120:123]
	v_mfma_f32_16x16x32_bf16 v[124:127], v[92:95], v[172:175], v[124:127]
	v_mfma_f32_16x16x32_bf16 v[124:127], v[88:91], v[168:171], v[124:127]
	v_mfma_f32_16x16x32_bf16 v[100:103], v[88:91], v[176:179], v[100:103]
	v_mfma_f32_16x16x32_bf16 v[100:103], v[92:95], v[180:183], v[100:103]
	v_mfma_f32_16x16x32_bf16 v[96:99], v[116:119], v[180:183], v[96:99]
	v_mfma_f32_16x16x32_bf16 v[96:99], v[112:115], v[176:179], v[96:99]
	v_mfma_f32_16x16x32_bf16 v[72:75], v[112:115], v[208:211], v[72:75]
	v_mfma_f32_16x16x32_bf16 v[72:75], v[116:119], v[212:215], v[72:75]
	v_mfma_f32_16x16x32_bf16 v[76:79], v[92:95], v[212:215], v[76:79]
	v_mfma_f32_16x16x32_bf16 v[76:79], v[88:91], v[208:211], v[76:79]
	v_mfma_f32_16x16x32_bf16 v[68:71], v[132:135], v[208:211], v[68:71]
	v_mfma_f32_16x16x32_bf16 v[68:71], v[136:139], v[212:215], v[68:71]
	v_mfma_f32_16x16x32_bf16 v[64:67], v[156:159], v[212:215], v[64:67]
	v_mfma_f32_16x16x32_bf16 v[64:67], v[152:155], v[208:211], v[64:67]
	v_mfma_f32_16x16x32_bf16 v[80:83], v[152:155], v[176:179], v[80:83]
	v_mfma_f32_16x16x32_bf16 v[80:83], v[156:159], v[180:183], v[80:83]
	v_mfma_f32_16x16x32_bf16 v[84:87], v[136:139], v[180:183], v[84:87]
	v_mfma_f32_16x16x32_bf16 v[84:87], v[132:135], v[176:179], v[84:87]
	v_mfma_f32_16x16x32_bf16 v[108:111], v[132:135], v[168:171], v[108:111]
	v_mfma_f32_16x16x32_bf16 v[108:111], v[136:139], v[172:175], v[108:111]
	v_mfma_f32_16x16x32_bf16 v[104:107], v[156:159], v[172:175], v[104:107]
	v_mfma_f32_16x16x32_bf16 v[104:107], v[152:155], v[168:171], v[104:107]
	v_mfma_f32_16x16x32_bf16 v[128:131], v[152:155], v[160:163], v[128:131]
	v_mfma_f32_16x16x32_bf16 v[128:131], v[156:159], v[164:167], v[128:131]
	v_mfma_f32_16x16x32_bf16 v[140:143], v[136:139], v[164:167], v[140:143]
	v_mfma_f32_16x16x32_bf16 v[140:143], v[132:135], v[160:163], v[140:143]
	s_barrier
	s_setprio 0
	s_add_i32 s50, vcc_lo, s66
	v_lshl_add_u64 v[216:217], v[216:217], 0, s[46:47]
	s_mov_b32 m0, s50
	ds_read_b128 v[160:163], v235 offset:49152
	ds_read_b128 v[164:167], v235 offset:50176
	ds_read_b128 v[168:171], v235 offset:51200
	ds_read_b128 v[172:175], v235 offset:52224
	ds_read_b128 v[176:179], v235 offset:53248
	ds_read_b128 v[180:183], v235 offset:54272
	ds_read_b128 v[208:211], v235 offset:55296
	ds_read_b128 v[212:215], v235 offset:56320
	global_load_lds_dwordx4 v[216:217], off
	s_add_i32 m0, s50, 0x2000
	s_add_u32 s50, s54, 0xb0080
	v_lshl_add_u64 v[216:217], v[218:219], 0, s[46:47]
	s_addc_u32 s51, s55, 0
	s_add_i32 s54, vcc_hi, s66
	global_load_lds_dwordx4 v[216:217], off
	v_lshl_add_u64 v[216:217], s[50:51], 0, v[186:187]
	s_mov_b32 m0, s54
	s_nop 0
	global_load_lds_dwordx4 v[216:217], off
	v_lshl_add_u64 v[216:217], s[50:51], 0, v[190:191]
	s_add_i32 m0, s54, 0x2000
	s_nop 0
	global_load_lds_dwordx4 v[216:217], off
	v_lshl_add_u64 v[216:217], v[220:221], 0, s[46:47]
	s_mov_b32 m0, s74
	s_nop 0
	global_load_lds_dwordx4 v[216:217], off
	v_lshl_add_u64 v[216:217], v[222:223], 0, s[46:47]
	s_mov_b32 m0, s75
	s_nop 0
	global_load_lds_dwordx4 v[216:217], off
	s_waitcnt vmcnt(8)
	s_waitcnt lgkmcnt(0)
	s_setprio 1
	s_barrier
	v_mfma_f32_16x16x32_bf16 v[60:63], v[88:91], v[160:163], v[60:63]
	v_mfma_f32_16x16x32_bf16 v[60:63], v[92:95], v[164:167], v[60:63]
	v_mfma_f32_16x16x32_bf16 v[56:59], v[116:119], v[164:167], v[56:59]
	v_mfma_f32_16x16x32_bf16 v[56:59], v[112:115], v[160:163], v[56:59]
	v_mfma_f32_16x16x32_bf16 v[40:43], v[112:115], v[168:171], v[40:43]
	v_mfma_f32_16x16x32_bf16 v[40:43], v[116:119], v[172:175], v[40:43]
	v_mfma_f32_16x16x32_bf16 v[44:47], v[92:95], v[172:175], v[44:47]
	v_mfma_f32_16x16x32_bf16 v[44:47], v[88:91], v[168:171], v[44:47]
	v_mfma_f32_16x16x32_bf16 v[28:31], v[88:91], v[176:179], v[28:31]
	v_mfma_f32_16x16x32_bf16 v[28:31], v[92:95], v[180:183], v[28:31]
	v_mfma_f32_16x16x32_bf16 v[24:27], v[116:119], v[180:183], v[24:27]
	v_mfma_f32_16x16x32_bf16 v[24:27], v[112:115], v[176:179], v[24:27]
	v_mfma_f32_16x16x32_bf16 v[8:11], v[112:115], v[208:211], v[8:11]
	v_mfma_f32_16x16x32_bf16 v[8:11], v[116:119], v[212:215], v[8:11]
	v_mfma_f32_16x16x32_bf16 v[12:15], v[92:95], v[212:215], v[12:15]
	v_mfma_f32_16x16x32_bf16 v[12:15], v[88:91], v[208:211], v[12:15]
	v_mfma_f32_16x16x32_bf16 v[4:7], v[132:135], v[208:211], v[4:7]
	v_mfma_f32_16x16x32_bf16 v[4:7], v[136:139], v[212:215], v[4:7]
	v_mfma_f32_16x16x32_bf16 v[0:3], v[156:159], v[212:215], v[0:3]
	v_mfma_f32_16x16x32_bf16 v[0:3], v[152:155], v[208:211], v[0:3]
	v_mfma_f32_16x16x32_bf16 v[16:19], v[152:155], v[176:179], v[16:19]
	v_mfma_f32_16x16x32_bf16 v[16:19], v[156:159], v[180:183], v[16:19]
	v_mfma_f32_16x16x32_bf16 v[20:23], v[136:139], v[180:183], v[20:23]
	v_mfma_f32_16x16x32_bf16 v[20:23], v[132:135], v[176:179], v[20:23]
	v_mfma_f32_16x16x32_bf16 v[36:39], v[132:135], v[168:171], v[36:39]
	v_mfma_f32_16x16x32_bf16 v[36:39], v[136:139], v[172:175], v[36:39]
	v_mfma_f32_16x16x32_bf16 v[32:35], v[156:159], v[172:175], v[32:35]
	v_mfma_f32_16x16x32_bf16 v[32:35], v[152:155], v[168:171], v[32:35]
	v_mfma_f32_16x16x32_bf16 v[48:51], v[152:155], v[160:163], v[48:51]
	v_mfma_f32_16x16x32_bf16 v[48:51], v[156:159], v[164:167], v[48:51]
	v_mfma_f32_16x16x32_bf16 v[52:55], v[136:139], v[164:167], v[52:55]
	v_mfma_f32_16x16x32_bf16 v[52:55], v[132:135], v[160:163], v[52:55]
	s_barrier
	s_setprio 0
	s_add_i32 s97, s97, 2
	s_add_u32 s95, s95, 0x100
	s_addc_u32 s96, s96, 0
	s_cmp_gt_u32 s97, 41
	s_mov_b64 s[50:51], s[52:53]
	s_cbranch_scc0 .LBB0_221
	s_and_b64 vcc, exec, s[48:49]
	s_cbranch_vccz .LBB0_224
	s_barrier

.LBB0_312:
	s_ashr_i32 s43, s42, 31
	s_lshl_b64 s[46:47], s[42:43], 19
	s_add_u32 s46, s62, s46
	s_addc_u32 s47, s63, s47
	s_and_b64 s[48:49], s[4:5], exec
	s_cselect_b32 s10, s47, s53
	s_cselect_b32 s43, s46, s52
	s_ashr_i32 s45, s44, 31
	s_lshl_b64 s[48:49], s[44:45], 19
	s_add_u32 s48, s70, s48
	s_addc_u32 s49, s71, s49
	s_and_b64 s[56:57], s[4:5], exec
	s_cselect_b32 s45, s49, s55
	s_cselect_b32 s51, s48, s54
	s_add_u32 s52, s52, 0x40080
	s_addc_u32 s53, s53, 0
	s_add_u32 s67, s54, 0x100
	s_addc_u32 s68, s55, 0
	s_mov_b32 s69, -2
	ds_read_b128 v[128:131], v179
	ds_read_b128 v[132:135], v179 offset:1024
	ds_read_b128 v[136:139], v179 offset:2048
	ds_read_b128 v[140:143], v179 offset:3072
	ds_read_b128 v[188:191], v181
	ds_read_b128 v[192:195], v181 offset:1024
	ds_read_b128 v[196:199], v181 offset:2048
	ds_read_b128 v[200:203], v181 offset:3072
	s_add_u32 s54, s52, 0xfffc0080
	s_addc_u32 s55, s53, -1
	s_cmp_eq_u32 s69, 12
	s_cselect_b32 s57, s10, s55
	s_cselect_b32 s56, s43, s54
	s_cselect_b32 s55, s45, s68
	s_cselect_b32 s54, s51, s67
	v_lshl_add_u64 v[238:239], s[52:53], 0, v[162:163]
	s_add_i32 m0, s75, 0xc000
	ds_read_b128 v[204:207], v183
	ds_read_b128 v[208:211], v183 offset:1024
	ds_read_b128 v[212:215], v183 offset:2048
	ds_read_b128 v[216:219], v183 offset:3072
	ds_read_b128 v[220:223], v183 offset:4096
	ds_read_b128 v[224:227], v183 offset:5120
	ds_read_b128 v[230:233], v183 offset:6144
	ds_read_b128 v[234:237], v183 offset:7168
	global_load_lds_dwordx4 v[238:239], off
	v_lshl_add_u64 v[238:239], s[52:53], 0, v[164:165]
	s_add_i32 m0, s75, 0xe000
	s_nop 0
	global_load_lds_dwordx4 v[238:239], off
	s_waitcnt vmcnt(8)
	s_waitcnt lgkmcnt(0)
	s_setprio 1
	s_barrier
	v_mfma_f32_16x16x32_bf16 v[124:127], v[128:131], v[204:207], 0
	v_mfma_f32_16x16x32_bf16 v[124:127], v[132:135], v[208:211], v[124:127]
	v_mfma_f32_16x16x32_bf16 v[120:123], v[140:143], v[208:211], 0
	v_mfma_f32_16x16x32_bf16 v[120:123], v[136:139], v[204:207], v[120:123]
	v_mfma_f32_16x16x32_bf16 v[104:107], v[136:139], v[212:215], 0
	v_mfma_f32_16x16x32_bf16 v[104:107], v[140:143], v[216:219], v[104:107]
	v_mfma_f32_16x16x32_bf16 v[108:111], v[132:135], v[216:219], 0
	v_mfma_f32_16x16x32_bf16 v[108:111], v[128:131], v[212:215], v[108:111]
	v_mfma_f32_16x16x32_bf16 v[92:95], v[128:131], v[220:223], 0
	v_mfma_f32_16x16x32_bf16 v[92:95], v[132:135], v[224:227], v[92:95]
	v_mfma_f32_16x16x32_bf16 v[88:91], v[140:143], v[224:227], 0
	v_mfma_f32_16x16x32_bf16 v[88:91], v[136:139], v[220:223], v[88:91]
	v_mfma_f32_16x16x32_bf16 v[72:75], v[136:139], v[230:233], 0
	v_mfma_f32_16x16x32_bf16 v[72:75], v[140:143], v[234:237], v[72:75]
	v_mfma_f32_16x16x32_bf16 v[76:79], v[132:135], v[234:237], 0
	v_mfma_f32_16x16x32_bf16 v[76:79], v[128:131], v[230:233], v[76:79]
	v_mfma_f32_16x16x32_bf16 v[68:71], v[188:191], v[230:233], 0
	v_mfma_f32_16x16x32_bf16 v[68:71], v[192:195], v[234:237], v[68:71]
	v_mfma_f32_16x16x32_bf16 v[64:67], v[200:203], v[234:237], 0
	v_mfma_f32_16x16x32_bf16 v[64:67], v[196:199], v[230:233], v[64:67]
	v_mfma_f32_16x16x32_bf16 v[80:83], v[196:199], v[220:223], 0
	v_mfma_f32_16x16x32_bf16 v[80:83], v[200:203], v[224:227], v[80:83]
	v_mfma_f32_16x16x32_bf16 v[84:87], v[192:195], v[224:227], 0
	v_mfma_f32_16x16x32_bf16 v[84:87], v[188:191], v[220:223], v[84:87]
	v_mfma_f32_16x16x32_bf16 v[100:103], v[188:191], v[212:215], 0
	v_mfma_f32_16x16x32_bf16 v[100:103], v[192:195], v[216:219], v[100:103]
	v_mfma_f32_16x16x32_bf16 v[96:99], v[200:203], v[216:219], 0
	v_mfma_f32_16x16x32_bf16 v[96:99], v[196:199], v[212:215], v[96:99]
	v_mfma_f32_16x16x32_bf16 v[112:115], v[196:199], v[204:207], 0
	v_mfma_f32_16x16x32_bf16 v[112:115], v[200:203], v[208:211], v[112:115]
	v_mfma_f32_16x16x32_bf16 v[116:119], v[192:195], v[208:211], 0
	v_mfma_f32_16x16x32_bf16 v[116:119], v[188:191], v[204:207], v[116:119]
	s_barrier
	s_setprio 0
	s_add_i32 vcc_lo, s92, s72
	v_lshl_add_u64 v[238:239], s[54:55], 0, v[148:149]
	s_mov_b32 m0, vcc_lo
	ds_read_b128 v[204:207], v183 offset:16384
	ds_read_b128 v[208:211], v183 offset:17408
	ds_read_b128 v[212:215], v183 offset:18432
	ds_read_b128 v[216:219], v183 offset:19456
	ds_read_b128 v[220:223], v183 offset:20480
	ds_read_b128 v[224:227], v183 offset:21504
	ds_read_b128 v[230:233], v183 offset:22528
	ds_read_b128 v[234:237], v183 offset:23552
	global_load_lds_dwordx4 v[238:239], off
	s_add_i32 m0, vcc_lo, 0x2000
	s_add_u32 vcc_lo, s54, 0x40000
	v_lshl_add_u64 v[240:241], s[54:55], 0, v[144:145]
	s_addc_u32 vcc_hi, s55, 0
	s_add_i32 s83, s93, s72
	global_load_lds_dwordx4 v[240:241], off
	v_lshl_add_u64 v[242:243], vcc, 0, v[148:149]
	s_mov_b32 m0, s83
	v_lshl_add_u64 v[244:245], s[56:57], 0, v[146:147]
	global_load_lds_dwordx4 v[242:243], off
	v_lshl_add_u64 v[242:243], vcc, 0, v[144:145]
	s_add_i32 m0, s83, 0x2000
	s_nop 0
	global_load_lds_dwordx4 v[242:243], off
	v_lshl_add_u64 v[242:243], s[56:57], 0, v[150:151]
	s_mov_b32 m0, s75
	s_nop 0
	global_load_lds_dwordx4 v[242:243], off
	s_mov_b32 m0, s76
	s_nop 0
	global_load_lds_dwordx4 v[244:245], off
	s_waitcnt vmcnt(8)
	s_waitcnt lgkmcnt(0)
	s_setprio 1
	s_barrier
	v_mfma_f32_16x16x32_bf16 v[60:63], v[128:131], v[204:207], 0
	v_mfma_f32_16x16x32_bf16 v[60:63], v[132:135], v[208:211], v[60:63]
	v_mfma_f32_16x16x32_bf16 v[56:59], v[140:143], v[208:211], 0
	v_mfma_f32_16x16x32_bf16 v[56:59], v[136:139], v[204:207], v[56:59]
	v_mfma_f32_16x16x32_bf16 v[40:43], v[136:139], v[212:215], 0
	v_mfma_f32_16x16x32_bf16 v[40:43], v[140:143], v[216:219], v[40:43]
	v_mfma_f32_16x16x32_bf16 v[44:47], v[132:135], v[216:219], 0
	v_mfma_f32_16x16x32_bf16 v[44:47], v[128:131], v[212:215], v[44:47]
	v_mfma_f32_16x16x32_bf16 v[28:31], v[128:131], v[220:223], 0
	v_mfma_f32_16x16x32_bf16 v[28:31], v[132:135], v[224:227], v[28:31]
	v_mfma_f32_16x16x32_bf16 v[24:27], v[140:143], v[224:227], 0
	v_mfma_f32_16x16x32_bf16 v[24:27], v[136:139], v[220:223], v[24:27]
	v_mfma_f32_16x16x32_bf16 v[8:11], v[136:139], v[230:233], 0
	v_mfma_f32_16x16x32_bf16 v[8:11], v[140:143], v[234:237], v[8:11]
	v_mfma_f32_16x16x32_bf16 v[12:15], v[132:135], v[234:237], 0
	v_mfma_f32_16x16x32_bf16 v[12:15], v[128:131], v[230:233], v[12:15]
	v_mfma_f32_16x16x32_bf16 v[4:7], v[188:191], v[230:233], 0
	v_mfma_f32_16x16x32_bf16 v[4:7], v[192:195], v[234:237], v[4:7]
	v_mfma_f32_16x16x32_bf16 v[0:3], v[200:203], v[234:237], 0
	v_mfma_f32_16x16x32_bf16 v[0:3], v[196:199], v[230:233], v[0:3]
	v_mfma_f32_16x16x32_bf16 v[16:19], v[196:199], v[220:223], 0
	v_mfma_f32_16x16x32_bf16 v[16:19], v[200:203], v[224:227], v[16:19]
	v_mfma_f32_16x16x32_bf16 v[20:23], v[192:195], v[224:227], 0
	v_mfma_f32_16x16x32_bf16 v[20:23], v[188:191], v[220:223], v[20:23]
	v_mfma_f32_16x16x32_bf16 v[36:39], v[188:191], v[212:215], 0
	v_mfma_f32_16x16x32_bf16 v[36:39], v[192:195], v[216:219], v[36:39]
	v_mfma_f32_16x16x32_bf16 v[32:35], v[200:203], v[216:219], 0
	v_mfma_f32_16x16x32_bf16 v[32:35], v[196:199], v[212:215], v[32:35]
	v_mfma_f32_16x16x32_bf16 v[48:51], v[196:199], v[204:207], 0
	v_mfma_f32_16x16x32_bf16 v[48:51], v[200:203], v[208:211], v[48:51]
	v_mfma_f32_16x16x32_bf16 v[52:55], v[192:195], v[208:211], 0
	v_mfma_f32_16x16x32_bf16 v[52:55], v[188:191], v[204:207], v[52:55]
	s_barrier
	s_setprio 0
	s_add_i32 s83, 0, 0x18000
	s_add_i32 vcc_lo, 0, 0x1c000
	v_add_u32_e32 v140, s83, v157
	v_add_u32_e32 v171, vcc_lo, v157
	ds_read_b128 v[128:131], v140
	ds_read_b128 v[132:135], v140 offset:1024
	ds_read_b128 v[136:139], v140 offset:2048
	ds_read_b128 v[140:143], v140 offset:3072
	ds_read_b128 v[188:191], v171
	ds_read_b128 v[192:195], v171 offset:1024
	ds_read_b128 v[196:199], v171 offset:2048
	ds_read_b128 v[200:203], v171 offset:3072
	s_add_u32 s56, s56, 0x40000
	s_addc_u32 s57, s57, 0
	s_mov_b32 m0, s77
	v_lshl_add_u64 v[246:247], s[56:57], 0, v[150:151]
	ds_read_b128 v[204:207], v183 offset:32768
	ds_read_b128 v[208:211], v183 offset:33792
	ds_read_b128 v[212:215], v183 offset:34816
	ds_read_b128 v[216:219], v183 offset:35840
	ds_read_b128 v[220:223], v183 offset:36864
	ds_read_b128 v[224:227], v183 offset:37888
	ds_read_b128 v[230:233], v183 offset:38912
	ds_read_b128 v[234:237], v183 offset:39936
	global_load_lds_dwordx4 v[246:247], off
	v_lshl_add_u64 v[246:247], s[56:57], 0, v[146:147]
	s_mov_b32 m0, s78
	s_nop 0
	global_load_lds_dwordx4 v[246:247], off
	s_waitcnt vmcnt(8)
	s_waitcnt lgkmcnt(0)
	s_setprio 1
	s_barrier
	v_mfma_f32_16x16x32_bf16 v[124:127], v[128:131], v[204:207], v[124:127]
	v_mfma_f32_16x16x32_bf16 v[124:127], v[132:135], v[208:211], v[124:127]
	v_mfma_f32_16x16x32_bf16 v[120:123], v[140:143], v[208:211], v[120:123]
	v_mfma_f32_16x16x32_bf16 v[120:123], v[136:139], v[204:207], v[120:123]
	v_mfma_f32_16x16x32_bf16 v[104:107], v[136:139], v[212:215], v[104:107]
	v_mfma_f32_16x16x32_bf16 v[104:107], v[140:143], v[216:219], v[104:107]
	v_mfma_f32_16x16x32_bf16 v[108:111], v[132:135], v[216:219], v[108:111]
	v_mfma_f32_16x16x32_bf16 v[108:111], v[128:131], v[212:215], v[108:111]
	v_mfma_f32_16x16x32_bf16 v[92:95], v[128:131], v[220:223], v[92:95]
	v_mfma_f32_16x16x32_bf16 v[92:95], v[132:135], v[224:227], v[92:95]
	v_mfma_f32_16x16x32_bf16 v[88:91], v[140:143], v[224:227], v[88:91]
	v_mfma_f32_16x16x32_bf16 v[88:91], v[136:139], v[220:223], v[88:91]
	v_mfma_f32_16x16x32_bf16 v[72:75], v[136:139], v[230:233], v[72:75]
	v_mfma_f32_16x16x32_bf16 v[72:75], v[140:143], v[234:237], v[72:75]
	v_mfma_f32_16x16x32_bf16 v[76:79], v[132:135], v[234:237], v[76:79]
	v_mfma_f32_16x16x32_bf16 v[76:79], v[128:131], v[230:233], v[76:79]
	v_mfma_f32_16x16x32_bf16 v[68:71], v[188:191], v[230:233], v[68:71]
	v_mfma_f32_16x16x32_bf16 v[68:71], v[192:195], v[234:237], v[68:71]
	v_mfma_f32_16x16x32_bf16 v[64:67], v[200:203], v[234:237], v[64:67]
	v_mfma_f32_16x16x32_bf16 v[64:67], v[196:199], v[230:233], v[64:67]
	v_mfma_f32_16x16x32_bf16 v[80:83], v[196:199], v[220:223], v[80:83]
	v_mfma_f32_16x16x32_bf16 v[80:83], v[200:203], v[224:227], v[80:83]
	v_mfma_f32_16x16x32_bf16 v[84:87], v[192:195], v[224:227], v[84:87]
	v_mfma_f32_16x16x32_bf16 v[84:87], v[188:191], v[220:223], v[84:87]
	v_mfma_f32_16x16x32_bf16 v[100:103], v[188:191], v[212:215], v[100:103]
	v_mfma_f32_16x16x32_bf16 v[100:103], v[192:195], v[216:219], v[100:103]
	v_mfma_f32_16x16x32_bf16 v[96:99], v[200:203], v[216:219], v[96:99]
	v_mfma_f32_16x16x32_bf16 v[96:99], v[196:199], v[212:215], v[96:99]
	v_mfma_f32_16x16x32_bf16 v[112:115], v[196:199], v[204:207], v[112:115]
	v_mfma_f32_16x16x32_bf16 v[112:115], v[200:203], v[208:211], v[112:115]
	v_mfma_f32_16x16x32_bf16 v[116:119], v[192:195], v[208:211], v[116:119]
	v_mfma_f32_16x16x32_bf16 v[116:119], v[188:191], v[204:207], v[116:119]
	s_barrier
	s_setprio 0
	s_add_i32 s56, s83, s72
	v_lshl_add_u64 v[238:239], v[238:239], 0, s[38:39]
	s_mov_b32 m0, s56
	ds_read_b128 v[204:207], v183 offset:49152
	ds_read_b128 v[208:211], v183 offset:50176
	ds_read_b128 v[212:215], v183 offset:51200
	ds_read_b128 v[216:219], v183 offset:52224
	ds_read_b128 v[220:223], v183 offset:53248
	ds_read_b128 v[224:227], v183 offset:54272
	ds_read_b128 v[230:233], v183 offset:55296
	ds_read_b128 v[234:237], v183 offset:56320
	global_load_lds_dwordx4 v[238:239], off
	s_add_i32 m0, s56, 0x2000
	s_add_u32 s54, s54, 0x40080
	v_lshl_add_u64 v[238:239], v[240:241], 0, s[38:39]
	s_addc_u32 s55, s55, 0
	s_add_i32 s56, vcc_lo, s72
	global_load_lds_dwordx4 v[238:239], off
	v_lshl_add_u64 v[238:239], s[54:55], 0, v[148:149]
	s_mov_b32 m0, s56
	s_nop 0
	global_load_lds_dwordx4 v[238:239], off
	v_lshl_add_u64 v[238:239], s[54:55], 0, v[144:145]
	s_add_i32 m0, s56, 0x2000
	s_nop 0
	global_load_lds_dwordx4 v[238:239], off
	v_lshl_add_u64 v[238:239], v[242:243], 0, s[38:39]
	s_mov_b32 m0, s87
	s_nop 0
	global_load_lds_dwordx4 v[238:239], off
	v_lshl_add_u64 v[238:239], v[244:245], 0, s[38:39]
	s_mov_b32 m0, s88
	s_nop 0
	global_load_lds_dwordx4 v[238:239], off
	s_waitcnt vmcnt(8)
	s_waitcnt lgkmcnt(0)
	s_setprio 1
	s_barrier
	v_mfma_f32_16x16x32_bf16 v[60:63], v[128:131], v[204:207], v[60:63]
	v_mfma_f32_16x16x32_bf16 v[60:63], v[132:135], v[208:211], v[60:63]
	v_mfma_f32_16x16x32_bf16 v[56:59], v[140:143], v[208:211], v[56:59]
	v_mfma_f32_16x16x32_bf16 v[56:59], v[136:139], v[204:207], v[56:59]
	v_mfma_f32_16x16x32_bf16 v[40:43], v[136:139], v[212:215], v[40:43]
	v_mfma_f32_16x16x32_bf16 v[40:43], v[140:143], v[216:219], v[40:43]
	v_mfma_f32_16x16x32_bf16 v[44:47], v[132:135], v[216:219], v[44:47]
	v_mfma_f32_16x16x32_bf16 v[44:47], v[128:131], v[212:215], v[44:47]
	v_mfma_f32_16x16x32_bf16 v[28:31], v[128:131], v[220:223], v[28:31]
	v_mfma_f32_16x16x32_bf16 v[28:31], v[132:135], v[224:227], v[28:31]
	v_mfma_f32_16x16x32_bf16 v[24:27], v[140:143], v[224:227], v[24:27]
	v_mfma_f32_16x16x32_bf16 v[24:27], v[136:139], v[220:223], v[24:27]
	v_mfma_f32_16x16x32_bf16 v[8:11], v[136:139], v[230:233], v[8:11]
	v_mfma_f32_16x16x32_bf16 v[8:11], v[140:143], v[234:237], v[8:11]
	v_mfma_f32_16x16x32_bf16 v[12:15], v[132:135], v[234:237], v[12:15]
	v_mfma_f32_16x16x32_bf16 v[12:15], v[128:131], v[230:233], v[12:15]
	v_mfma_f32_16x16x32_bf16 v[4:7], v[188:191], v[230:233], v[4:7]
	v_mfma_f32_16x16x32_bf16 v[4:7], v[192:195], v[234:237], v[4:7]
	v_mfma_f32_16x16x32_bf16 v[0:3], v[200:203], v[234:237], v[0:3]
	v_mfma_f32_16x16x32_bf16 v[0:3], v[196:199], v[230:233], v[0:3]
	v_mfma_f32_16x16x32_bf16 v[16:19], v[196:199], v[220:223], v[16:19]
	v_mfma_f32_16x16x32_bf16 v[16:19], v[200:203], v[224:227], v[16:19]
	v_mfma_f32_16x16x32_bf16 v[20:23], v[192:195], v[224:227], v[20:23]
	v_mfma_f32_16x16x32_bf16 v[20:23], v[188:191], v[220:223], v[20:23]
	v_mfma_f32_16x16x32_bf16 v[36:39], v[188:191], v[212:215], v[36:39]
	v_mfma_f32_16x16x32_bf16 v[36:39], v[192:195], v[216:219], v[36:39]
	v_mfma_f32_16x16x32_bf16 v[32:35], v[200:203], v[216:219], v[32:35]
	v_mfma_f32_16x16x32_bf16 v[32:35], v[196:199], v[212:215], v[32:35]
	v_mfma_f32_16x16x32_bf16 v[48:51], v[196:199], v[204:207], v[48:51]
	v_mfma_f32_16x16x32_bf16 v[48:51], v[200:203], v[208:211], v[48:51]
	v_mfma_f32_16x16x32_bf16 v[52:55], v[192:195], v[208:211], v[52:55]
	v_mfma_f32_16x16x32_bf16 v[52:55], v[188:191], v[204:207], v[52:55]
	s_barrier
	s_setprio 0
	s_add_i32 s69, s69, 2
	s_add_u32 s52, s52, 0x100
	s_addc_u32 s53, s53, 0
	s_add_u32 s67, s67, 0x100
	s_addc_u32 s68, s68, 0
	s_cmp_gt_u32 s69, 13
.LBB0_313:
	ds_read_b128 v[128:131], v179
	ds_read_b128 v[132:135], v179 offset:1024
	ds_read_b128 v[136:139], v179 offset:2048
	ds_read_b128 v[140:143], v179 offset:3072
	ds_read_b128 v[188:191], v181
	ds_read_b128 v[192:195], v181 offset:1024
	ds_read_b128 v[196:199], v181 offset:2048
	ds_read_b128 v[200:203], v181 offset:3072
	s_add_u32 s54, s52, 0xfffc0080
	s_addc_u32 s55, s53, -1
	s_cmp_eq_u32 s69, 12
	s_cselect_b32 s57, s10, s55
	s_cselect_b32 s56, s43, s54
	s_cselect_b32 s55, s45, s68
	s_cselect_b32 s54, s51, s67
	v_lshl_add_u64 v[238:239], s[52:53], 0, v[162:163]
	s_add_i32 m0, s75, 0xc000
	ds_read_b128 v[204:207], v183
	ds_read_b128 v[208:211], v183 offset:1024
	ds_read_b128 v[212:215], v183 offset:2048
	ds_read_b128 v[216:219], v183 offset:3072
	ds_read_b128 v[220:223], v183 offset:4096
	ds_read_b128 v[224:227], v183 offset:5120
	ds_read_b128 v[230:233], v183 offset:6144
	ds_read_b128 v[234:237], v183 offset:7168
	global_load_lds_dwordx4 v[238:239], off
	v_lshl_add_u64 v[238:239], s[52:53], 0, v[164:165]
	s_add_i32 m0, s75, 0xe000
	s_nop 0
	global_load_lds_dwordx4 v[238:239], off
	s_waitcnt vmcnt(8)
	s_waitcnt lgkmcnt(0)
	s_setprio 1
	s_barrier
	v_mfma_f32_16x16x32_bf16 v[124:127], v[128:131], v[204:207], v[124:127]
	v_mfma_f32_16x16x32_bf16 v[124:127], v[132:135], v[208:211], v[124:127]
	v_mfma_f32_16x16x32_bf16 v[120:123], v[140:143], v[208:211], v[120:123]
	v_mfma_f32_16x16x32_bf16 v[120:123], v[136:139], v[204:207], v[120:123]
	v_mfma_f32_16x16x32_bf16 v[104:107], v[136:139], v[212:215], v[104:107]
	v_mfma_f32_16x16x32_bf16 v[104:107], v[140:143], v[216:219], v[104:107]
	v_mfma_f32_16x16x32_bf16 v[108:111], v[132:135], v[216:219], v[108:111]
	v_mfma_f32_16x16x32_bf16 v[108:111], v[128:131], v[212:215], v[108:111]
	v_mfma_f32_16x16x32_bf16 v[92:95], v[128:131], v[220:223], v[92:95]
	v_mfma_f32_16x16x32_bf16 v[92:95], v[132:135], v[224:227], v[92:95]
	v_mfma_f32_16x16x32_bf16 v[88:91], v[140:143], v[224:227], v[88:91]
	v_mfma_f32_16x16x32_bf16 v[88:91], v[136:139], v[220:223], v[88:91]
	v_mfma_f32_16x16x32_bf16 v[72:75], v[136:139], v[230:233], v[72:75]
	v_mfma_f32_16x16x32_bf16 v[72:75], v[140:143], v[234:237], v[72:75]
	v_mfma_f32_16x16x32_bf16 v[76:79], v[132:135], v[234:237], v[76:79]
	v_mfma_f32_16x16x32_bf16 v[76:79], v[128:131], v[230:233], v[76:79]
	v_mfma_f32_16x16x32_bf16 v[68:71], v[188:191], v[230:233], v[68:71]
	v_mfma_f32_16x16x32_bf16 v[68:71], v[192:195], v[234:237], v[68:71]
	v_mfma_f32_16x16x32_bf16 v[64:67], v[200:203], v[234:237], v[64:67]
	v_mfma_f32_16x16x32_bf16 v[64:67], v[196:199], v[230:233], v[64:67]
	v_mfma_f32_16x16x32_bf16 v[80:83], v[196:199], v[220:223], v[80:83]
	v_mfma_f32_16x16x32_bf16 v[80:83], v[200:203], v[224:227], v[80:83]
	v_mfma_f32_16x16x32_bf16 v[84:87], v[192:195], v[224:227], v[84:87]
	v_mfma_f32_16x16x32_bf16 v[84:87], v[188:191], v[220:223], v[84:87]
	v_mfma_f32_16x16x32_bf16 v[100:103], v[188:191], v[212:215], v[100:103]
	v_mfma_f32_16x16x32_bf16 v[100:103], v[192:195], v[216:219], v[100:103]
	v_mfma_f32_16x16x32_bf16 v[96:99], v[200:203], v[216:219], v[96:99]
	v_mfma_f32_16x16x32_bf16 v[96:99], v[196:199], v[212:215], v[96:99]
	v_mfma_f32_16x16x32_bf16 v[112:115], v[196:199], v[204:207], v[112:115]
	v_mfma_f32_16x16x32_bf16 v[112:115], v[200:203], v[208:211], v[112:115]
	v_mfma_f32_16x16x32_bf16 v[116:119], v[192:195], v[208:211], v[116:119]
	v_mfma_f32_16x16x32_bf16 v[116:119], v[188:191], v[204:207], v[116:119]
	s_barrier
	s_setprio 0
	s_add_i32 vcc_lo, s92, s72
	v_lshl_add_u64 v[238:239], s[54:55], 0, v[148:149]
	s_mov_b32 m0, vcc_lo
	ds_read_b128 v[204:207], v183 offset:16384
	ds_read_b128 v[208:211], v183 offset:17408
	ds_read_b128 v[212:215], v183 offset:18432
	ds_read_b128 v[216:219], v183 offset:19456
	ds_read_b128 v[220:223], v183 offset:20480
	ds_read_b128 v[224:227], v183 offset:21504
	ds_read_b128 v[230:233], v183 offset:22528
	ds_read_b128 v[234:237], v183 offset:23552
	global_load_lds_dwordx4 v[238:239], off
	s_add_i32 m0, vcc_lo, 0x2000
	s_add_u32 vcc_lo, s54, 0x40000
	v_lshl_add_u64 v[240:241], s[54:55], 0, v[144:145]
	s_addc_u32 vcc_hi, s55, 0
	s_add_i32 s83, s93, s72
	global_load_lds_dwordx4 v[240:241], off
	v_lshl_add_u64 v[242:243], vcc, 0, v[148:149]
	s_mov_b32 m0, s83
	v_lshl_add_u64 v[244:245], s[56:57], 0, v[146:147]
	global_load_lds_dwordx4 v[242:243], off
	v_lshl_add_u64 v[242:243], vcc, 0, v[144:145]
	s_add_i32 m0, s83, 0x2000
	s_nop 0
	global_load_lds_dwordx4 v[242:243], off
	v_lshl_add_u64 v[242:243], s[56:57], 0, v[150:151]
	s_mov_b32 m0, s75
	s_nop 0
	global_load_lds_dwordx4 v[242:243], off
	s_mov_b32 m0, s76
	s_nop 0
	global_load_lds_dwordx4 v[244:245], off
	s_waitcnt vmcnt(8)
	s_waitcnt lgkmcnt(0)
	s_setprio 1
	s_barrier
	v_mfma_f32_16x16x32_bf16 v[60:63], v[128:131], v[204:207], v[60:63]
	v_mfma_f32_16x16x32_bf16 v[60:63], v[132:135], v[208:211], v[60:63]
	v_mfma_f32_16x16x32_bf16 v[56:59], v[140:143], v[208:211], v[56:59]
	v_mfma_f32_16x16x32_bf16 v[56:59], v[136:139], v[204:207], v[56:59]
	v_mfma_f32_16x16x32_bf16 v[40:43], v[136:139], v[212:215], v[40:43]
	v_mfma_f32_16x16x32_bf16 v[40:43], v[140:143], v[216:219], v[40:43]
	v_mfma_f32_16x16x32_bf16 v[44:47], v[132:135], v[216:219], v[44:47]
	v_mfma_f32_16x16x32_bf16 v[44:47], v[128:131], v[212:215], v[44:47]
	v_mfma_f32_16x16x32_bf16 v[28:31], v[128:131], v[220:223], v[28:31]
	v_mfma_f32_16x16x32_bf16 v[28:31], v[132:135], v[224:227], v[28:31]
	v_mfma_f32_16x16x32_bf16 v[24:27], v[140:143], v[224:227], v[24:27]
	v_mfma_f32_16x16x32_bf16 v[24:27], v[136:139], v[220:223], v[24:27]
	v_mfma_f32_16x16x32_bf16 v[8:11], v[136:139], v[230:233], v[8:11]
	v_mfma_f32_16x16x32_bf16 v[8:11], v[140:143], v[234:237], v[8:11]
	v_mfma_f32_16x16x32_bf16 v[12:15], v[132:135], v[234:237], v[12:15]
	v_mfma_f32_16x16x32_bf16 v[12:15], v[128:131], v[230:233], v[12:15]
	v_mfma_f32_16x16x32_bf16 v[4:7], v[188:191], v[230:233], v[4:7]
	v_mfma_f32_16x16x32_bf16 v[4:7], v[192:195], v[234:237], v[4:7]
	v_mfma_f32_16x16x32_bf16 v[0:3], v[200:203], v[234:237], v[0:3]
	v_mfma_f32_16x16x32_bf16 v[0:3], v[196:199], v[230:233], v[0:3]
	v_mfma_f32_16x16x32_bf16 v[16:19], v[196:199], v[220:223], v[16:19]
	v_mfma_f32_16x16x32_bf16 v[16:19], v[200:203], v[224:227], v[16:19]
	v_mfma_f32_16x16x32_bf16 v[20:23], v[192:195], v[224:227], v[20:23]
	v_mfma_f32_16x16x32_bf16 v[20:23], v[188:191], v[220:223], v[20:23]
	v_mfma_f32_16x16x32_bf16 v[36:39], v[188:191], v[212:215], v[36:39]
	v_mfma_f32_16x16x32_bf16 v[36:39], v[192:195], v[216:219], v[36:39]
	v_mfma_f32_16x16x32_bf16 v[32:35], v[200:203], v[216:219], v[32:35]
	v_mfma_f32_16x16x32_bf16 v[32:35], v[196:199], v[212:215], v[32:35]
	v_mfma_f32_16x16x32_bf16 v[48:51], v[196:199], v[204:207], v[48:51]
	v_mfma_f32_16x16x32_bf16 v[48:51], v[200:203], v[208:211], v[48:51]
	v_mfma_f32_16x16x32_bf16 v[52:55], v[192:195], v[208:211], v[52:55]
	v_mfma_f32_16x16x32_bf16 v[52:55], v[188:191], v[204:207], v[52:55]
	s_barrier
	s_setprio 0
	s_add_i32 s83, 0, 0x18000
	s_add_i32 vcc_lo, 0, 0x1c000
	v_add_u32_e32 v140, s83, v157
	v_add_u32_e32 v171, vcc_lo, v157
	ds_read_b128 v[128:131], v140
	ds_read_b128 v[132:135], v140 offset:1024
	ds_read_b128 v[136:139], v140 offset:2048
	ds_read_b128 v[140:143], v140 offset:3072
	ds_read_b128 v[188:191], v171
	ds_read_b128 v[192:195], v171 offset:1024
	ds_read_b128 v[196:199], v171 offset:2048
	ds_read_b128 v[200:203], v171 offset:3072
	s_add_u32 s56, s56, 0x40000
	s_addc_u32 s57, s57, 0
	s_mov_b32 m0, s77
	v_lshl_add_u64 v[246:247], s[56:57], 0, v[150:151]
	ds_read_b128 v[204:207], v183 offset:32768
	ds_read_b128 v[208:211], v183 offset:33792
	ds_read_b128 v[212:215], v183 offset:34816
	ds_read_b128 v[216:219], v183 offset:35840
	ds_read_b128 v[220:223], v183 offset:36864
	ds_read_b128 v[224:227], v183 offset:37888
	ds_read_b128 v[230:233], v183 offset:38912
	ds_read_b128 v[234:237], v183 offset:39936
	global_load_lds_dwordx4 v[246:247], off
	v_lshl_add_u64 v[246:247], s[56:57], 0, v[146:147]
	s_mov_b32 m0, s78
	s_nop 0
	global_load_lds_dwordx4 v[246:247], off
	s_waitcnt vmcnt(8)
	s_waitcnt lgkmcnt(0)
	s_setprio 1
	s_barrier
	v_mfma_f32_16x16x32_bf16 v[124:127], v[128:131], v[204:207], v[124:127]
	v_mfma_f32_16x16x32_bf16 v[124:127], v[132:135], v[208:211], v[124:127]
	v_mfma_f32_16x16x32_bf16 v[120:123], v[140:143], v[208:211], v[120:123]
	v_mfma_f32_16x16x32_bf16 v[120:123], v[136:139], v[204:207], v[120:123]
	v_mfma_f32_16x16x32_bf16 v[104:107], v[136:139], v[212:215], v[104:107]
	v_mfma_f32_16x16x32_bf16 v[104:107], v[140:143], v[216:219], v[104:107]
	v_mfma_f32_16x16x32_bf16 v[108:111], v[132:135], v[216:219], v[108:111]
	v_mfma_f32_16x16x32_bf16 v[108:111], v[128:131], v[212:215], v[108:111]
	v_mfma_f32_16x16x32_bf16 v[92:95], v[128:131], v[220:223], v[92:95]
	v_mfma_f32_16x16x32_bf16 v[92:95], v[132:135], v[224:227], v[92:95]
	v_mfma_f32_16x16x32_bf16 v[88:91], v[140:143], v[224:227], v[88:91]
	v_mfma_f32_16x16x32_bf16 v[88:91], v[136:139], v[220:223], v[88:91]
	v_mfma_f32_16x16x32_bf16 v[72:75], v[136:139], v[230:233], v[72:75]
	v_mfma_f32_16x16x32_bf16 v[72:75], v[140:143], v[234:237], v[72:75]
	v_mfma_f32_16x16x32_bf16 v[76:79], v[132:135], v[234:237], v[76:79]
	v_mfma_f32_16x16x32_bf16 v[76:79], v[128:131], v[230:233], v[76:79]
	v_mfma_f32_16x16x32_bf16 v[68:71], v[188:191], v[230:233], v[68:71]
	v_mfma_f32_16x16x32_bf16 v[68:71], v[192:195], v[234:237], v[68:71]
	v_mfma_f32_16x16x32_bf16 v[64:67], v[200:203], v[234:237], v[64:67]
	v_mfma_f32_16x16x32_bf16 v[64:67], v[196:199], v[230:233], v[64:67]
	v_mfma_f32_16x16x32_bf16 v[80:83], v[196:199], v[220:223], v[80:83]
	v_mfma_f32_16x16x32_bf16 v[80:83], v[200:203], v[224:227], v[80:83]
	v_mfma_f32_16x16x32_bf16 v[84:87], v[192:195], v[224:227], v[84:87]
	v_mfma_f32_16x16x32_bf16 v[84:87], v[188:191], v[220:223], v[84:87]
	v_mfma_f32_16x16x32_bf16 v[100:103], v[188:191], v[212:215], v[100:103]
	v_mfma_f32_16x16x32_bf16 v[100:103], v[192:195], v[216:219], v[100:103]
	v_mfma_f32_16x16x32_bf16 v[96:99], v[200:203], v[216:219], v[96:99]
	v_mfma_f32_16x16x32_bf16 v[96:99], v[196:199], v[212:215], v[96:99]
	v_mfma_f32_16x16x32_bf16 v[112:115], v[196:199], v[204:207], v[112:115]
	v_mfma_f32_16x16x32_bf16 v[112:115], v[200:203], v[208:211], v[112:115]
	v_mfma_f32_16x16x32_bf16 v[116:119], v[192:195], v[208:211], v[116:119]
	v_mfma_f32_16x16x32_bf16 v[116:119], v[188:191], v[204:207], v[116:119]
	s_barrier
	s_setprio 0
	s_add_i32 s56, s83, s72
	v_lshl_add_u64 v[238:239], v[238:239], 0, s[38:39]
	s_mov_b32 m0, s56
	ds_read_b128 v[204:207], v183 offset:49152
	ds_read_b128 v[208:211], v183 offset:50176
	ds_read_b128 v[212:215], v183 offset:51200
	ds_read_b128 v[216:219], v183 offset:52224
	ds_read_b128 v[220:223], v183 offset:53248
	ds_read_b128 v[224:227], v183 offset:54272
	ds_read_b128 v[230:233], v183 offset:55296
	ds_read_b128 v[234:237], v183 offset:56320
	global_load_lds_dwordx4 v[238:239], off
	s_add_i32 m0, s56, 0x2000
	s_add_u32 s54, s54, 0x40080
	v_lshl_add_u64 v[238:239], v[240:241], 0, s[38:39]
	s_addc_u32 s55, s55, 0
	s_add_i32 s56, vcc_lo, s72
	global_load_lds_dwordx4 v[238:239], off
	v_lshl_add_u64 v[238:239], s[54:55], 0, v[148:149]
	s_mov_b32 m0, s56
	s_nop 0
	global_load_lds_dwordx4 v[238:239], off
	v_lshl_add_u64 v[238:239], s[54:55], 0, v[144:145]
	s_add_i32 m0, s56, 0x2000
	s_nop 0
	global_load_lds_dwordx4 v[238:239], off
	v_lshl_add_u64 v[238:239], v[242:243], 0, s[38:39]
	s_mov_b32 m0, s87
	s_nop 0
	global_load_lds_dwordx4 v[238:239], off
	v_lshl_add_u64 v[238:239], v[244:245], 0, s[38:39]
	s_mov_b32 m0, s88
	s_nop 0
	global_load_lds_dwordx4 v[238:239], off
	s_waitcnt vmcnt(8)
	s_waitcnt lgkmcnt(0)
	s_setprio 1
	s_barrier
	v_mfma_f32_16x16x32_bf16 v[60:63], v[128:131], v[204:207], v[60:63]
	v_mfma_f32_16x16x32_bf16 v[60:63], v[132:135], v[208:211], v[60:63]
	v_mfma_f32_16x16x32_bf16 v[56:59], v[140:143], v[208:211], v[56:59]
	v_mfma_f32_16x16x32_bf16 v[56:59], v[136:139], v[204:207], v[56:59]
	v_mfma_f32_16x16x32_bf16 v[40:43], v[136:139], v[212:215], v[40:43]
	v_mfma_f32_16x16x32_bf16 v[40:43], v[140:143], v[216:219], v[40:43]
	v_mfma_f32_16x16x32_bf16 v[44:47], v[132:135], v[216:219], v[44:47]
	v_mfma_f32_16x16x32_bf16 v[44:47], v[128:131], v[212:215], v[44:47]
	v_mfma_f32_16x16x32_bf16 v[28:31], v[128:131], v[220:223], v[28:31]
	v_mfma_f32_16x16x32_bf16 v[28:31], v[132:135], v[224:227], v[28:31]
	v_mfma_f32_16x16x32_bf16 v[24:27], v[140:143], v[224:227], v[24:27]
	v_mfma_f32_16x16x32_bf16 v[24:27], v[136:139], v[220:223], v[24:27]
	v_mfma_f32_16x16x32_bf16 v[8:11], v[136:139], v[230:233], v[8:11]
	v_mfma_f32_16x16x32_bf16 v[8:11], v[140:143], v[234:237], v[8:11]
	v_mfma_f32_16x16x32_bf16 v[12:15], v[132:135], v[234:237], v[12:15]
	v_mfma_f32_16x16x32_bf16 v[12:15], v[128:131], v[230:233], v[12:15]
	v_mfma_f32_16x16x32_bf16 v[4:7], v[188:191], v[230:233], v[4:7]
	v_mfma_f32_16x16x32_bf16 v[4:7], v[192:195], v[234:237], v[4:7]
	v_mfma_f32_16x16x32_bf16 v[0:3], v[200:203], v[234:237], v[0:3]
	v_mfma_f32_16x16x32_bf16 v[0:3], v[196:199], v[230:233], v[0:3]
	v_mfma_f32_16x16x32_bf16 v[16:19], v[196:199], v[220:223], v[16:19]
	v_mfma_f32_16x16x32_bf16 v[16:19], v[200:203], v[224:227], v[16:19]
	v_mfma_f32_16x16x32_bf16 v[20:23], v[192:195], v[224:227], v[20:23]
	v_mfma_f32_16x16x32_bf16 v[20:23], v[188:191], v[220:223], v[20:23]
	v_mfma_f32_16x16x32_bf16 v[36:39], v[188:191], v[212:215], v[36:39]
	v_mfma_f32_16x16x32_bf16 v[36:39], v[192:195], v[216:219], v[36:39]
	v_mfma_f32_16x16x32_bf16 v[32:35], v[200:203], v[216:219], v[32:35]
	v_mfma_f32_16x16x32_bf16 v[32:35], v[196:199], v[212:215], v[32:35]
	v_mfma_f32_16x16x32_bf16 v[48:51], v[196:199], v[204:207], v[48:51]
	v_mfma_f32_16x16x32_bf16 v[48:51], v[200:203], v[208:211], v[48:51]
	v_mfma_f32_16x16x32_bf16 v[52:55], v[192:195], v[208:211], v[52:55]
	v_mfma_f32_16x16x32_bf16 v[52:55], v[188:191], v[204:207], v[52:55]
	s_barrier
	s_setprio 0
	s_add_i32 s69, s69, 2
	s_add_u32 s52, s52, 0x100
	s_addc_u32 s53, s53, 0
	s_add_u32 s67, s67, 0x100
	s_addc_u32 s68, s68, 0
	s_cmp_gt_u32 s69, 13
	s_cbranch_scc0 .LBB0_313
	s_and_b64 vcc, exec, s[40:41]
	s_cbranch_vccz .LBB0_316
	s_barrier

.LBB0_667:
	s_ashr_i32 s23, s22, 31
	s_lshl_b64 s[38:39], s[22:23], 19
	s_add_u32 s38, s26, s38
	s_addc_u32 s39, s27, s39
	s_and_b64 s[40:41], s[6:7], exec
	s_cselect_b32 s23, s39, s45
	s_cselect_b32 s43, s38, s44
	s_ashr_i32 s37, s36, 31
	s_lshl_b64 s[40:41], s[36:37], 19
	s_add_u32 s40, s50, s40
	s_addc_u32 s41, s51, s41
	s_and_b64 s[48:49], s[6:7], exec
	s_cselect_b32 s37, s41, s47
	s_cselect_b32 s92, s40, s46
	s_add_u32 s44, s44, 0x40080
	s_addc_u32 s45, s45, 0
	s_add_u32 s93, s46, 0x100
	s_addc_u32 s94, s47, 0
	s_mov_b32 s95, -2
	s_waitcnt lgkmcnt(0)
	ds_read_b128 v[80:83], v216
	ds_read_b128 v[84:87], v216 offset:1024
	ds_read_b128 v[104:107], v216 offset:2048
	ds_read_b128 v[108:111], v216 offset:3072
	ds_read_b128 v[128:131], v217
	ds_read_b128 v[132:135], v217 offset:1024
	ds_read_b128 v[152:155], v217 offset:2048
	ds_read_b128 v[156:159], v217 offset:3072
	s_add_u32 s46, s44, 0xfffc0080
	s_addc_u32 s47, s45, -1
	s_cmp_eq_u32 s95, 12
	s_cselect_b32 s49, s23, s47
	s_cselect_b32 s48, s43, s46
	s_cselect_b32 s47, s37, s94
	s_cselect_b32 s46, s92, s93
	v_lshl_add_u64 v[224:225], s[44:45], 0, v[194:195]
	s_add_i32 m0, s53, 0xc000
	ds_read_b128 v[160:163], v218
	ds_read_b128 v[164:167], v218 offset:1024
	ds_read_b128 v[168:171], v218 offset:2048
	ds_read_b128 v[172:175], v218 offset:3072
	ds_read_b128 v[176:179], v218 offset:4096
	ds_read_b128 v[180:183], v218 offset:5120
	ds_read_b128 v[208:211], v218 offset:6144
	ds_read_b128 v[220:223], v218 offset:7168
	global_load_lds_dwordx4 v[224:225], off
	v_lshl_add_u64 v[224:225], s[44:45], 0, v[196:197]
	s_add_i32 m0, s53, 0xe000
	s_nop 0
	global_load_lds_dwordx4 v[224:225], off
	s_waitcnt vmcnt(8)
	s_waitcnt lgkmcnt(0)
	s_setprio 1
	s_barrier
	v_mfma_f32_16x16x32_bf16 v[148:151], v[80:83], v[160:163], 0
	v_mfma_f32_16x16x32_bf16 v[148:151], v[84:87], v[164:167], v[148:151]
	v_mfma_f32_16x16x32_bf16 v[144:147], v[108:111], v[164:167], 0
	v_mfma_f32_16x16x32_bf16 v[144:147], v[104:107], v[160:163], v[144:147]
	v_mfma_f32_16x16x32_bf16 v[120:123], v[104:107], v[168:171], 0
	v_mfma_f32_16x16x32_bf16 v[120:123], v[108:111], v[172:175], v[120:123]
	v_mfma_f32_16x16x32_bf16 v[124:127], v[84:87], v[172:175], 0
	v_mfma_f32_16x16x32_bf16 v[124:127], v[80:83], v[168:171], v[124:127]
	v_mfma_f32_16x16x32_bf16 v[100:103], v[80:83], v[176:179], 0
	v_mfma_f32_16x16x32_bf16 v[100:103], v[84:87], v[180:183], v[100:103]
	v_mfma_f32_16x16x32_bf16 v[96:99], v[108:111], v[180:183], 0
	v_mfma_f32_16x16x32_bf16 v[96:99], v[104:107], v[176:179], v[96:99]
	v_mfma_f32_16x16x32_bf16 v[72:75], v[104:107], v[208:211], 0
	v_mfma_f32_16x16x32_bf16 v[72:75], v[108:111], v[220:223], v[72:75]
	v_mfma_f32_16x16x32_bf16 v[76:79], v[84:87], v[220:223], 0
	v_mfma_f32_16x16x32_bf16 v[76:79], v[80:83], v[208:211], v[76:79]
	v_mfma_f32_16x16x32_bf16 v[68:71], v[128:131], v[208:211], 0
	v_mfma_f32_16x16x32_bf16 v[68:71], v[132:135], v[220:223], v[68:71]
	v_mfma_f32_16x16x32_bf16 v[64:67], v[156:159], v[220:223], 0
	v_mfma_f32_16x16x32_bf16 v[64:67], v[152:155], v[208:211], v[64:67]
	v_mfma_f32_16x16x32_bf16 v[88:91], v[152:155], v[176:179], 0
	v_mfma_f32_16x16x32_bf16 v[88:91], v[156:159], v[180:183], v[88:91]
	v_mfma_f32_16x16x32_bf16 v[92:95], v[132:135], v[180:183], 0
	v_mfma_f32_16x16x32_bf16 v[92:95], v[128:131], v[176:179], v[92:95]
	v_mfma_f32_16x16x32_bf16 v[116:119], v[128:131], v[168:171], 0
	v_mfma_f32_16x16x32_bf16 v[116:119], v[132:135], v[172:175], v[116:119]
	v_mfma_f32_16x16x32_bf16 v[112:115], v[156:159], v[172:175], 0
	v_mfma_f32_16x16x32_bf16 v[112:115], v[152:155], v[168:171], v[112:115]
	v_mfma_f32_16x16x32_bf16 v[136:139], v[152:155], v[160:163], 0
	v_mfma_f32_16x16x32_bf16 v[136:139], v[156:159], v[164:167], v[136:139]
	v_mfma_f32_16x16x32_bf16 v[140:143], v[132:135], v[164:167], 0
	v_mfma_f32_16x16x32_bf16 v[140:143], v[128:131], v[160:163], v[140:143]
	s_barrier
	s_setprio 0
	s_add_i32 s83, s78, s52
	v_lshl_add_u64 v[224:225], s[46:47], 0, v[186:187]
	s_mov_b32 m0, s83
	ds_read_b128 v[160:163], v218 offset:16384
	ds_read_b128 v[164:167], v218 offset:17408
	ds_read_b128 v[168:171], v218 offset:18432
	ds_read_b128 v[172:175], v218 offset:19456
	ds_read_b128 v[176:179], v218 offset:20480
	ds_read_b128 v[180:183], v218 offset:21504
	ds_read_b128 v[208:211], v218 offset:22528
	ds_read_b128 v[220:223], v218 offset:23552
	global_load_lds_dwordx4 v[224:225], off
	s_add_i32 m0, s83, 0x2000
	s_add_u32 s96, s46, 0x40000
	v_lshl_add_u64 v[226:227], s[46:47], 0, v[190:191]
	s_addc_u32 s97, s47, 0
	s_add_i32 s83, s79, s52
	global_load_lds_dwordx4 v[226:227], off
	v_lshl_add_u64 v[230:231], s[96:97], 0, v[186:187]
	s_mov_b32 m0, s83
	v_lshl_add_u64 v[232:233], s[48:49], 0, v[188:189]
	global_load_lds_dwordx4 v[230:231], off
	v_lshl_add_u64 v[230:231], s[96:97], 0, v[190:191]
	s_add_i32 m0, s83, 0x2000
	s_nop 0
	global_load_lds_dwordx4 v[230:231], off
	v_lshl_add_u64 v[230:231], s[48:49], 0, v[184:185]
	s_mov_b32 m0, s53
	s_nop 0
	global_load_lds_dwordx4 v[230:231], off
	s_mov_b32 m0, s54
	s_nop 0
	global_load_lds_dwordx4 v[232:233], off
	s_waitcnt vmcnt(8)
	s_waitcnt lgkmcnt(0)
	s_setprio 1
	s_barrier
	v_mfma_f32_16x16x32_bf16 v[60:63], v[80:83], v[160:163], 0
	v_mfma_f32_16x16x32_bf16 v[60:63], v[84:87], v[164:167], v[60:63]
	v_mfma_f32_16x16x32_bf16 v[56:59], v[108:111], v[164:167], 0
	v_mfma_f32_16x16x32_bf16 v[56:59], v[104:107], v[160:163], v[56:59]
	v_mfma_f32_16x16x32_bf16 v[40:43], v[104:107], v[168:171], 0
	v_mfma_f32_16x16x32_bf16 v[40:43], v[108:111], v[172:175], v[40:43]
	v_mfma_f32_16x16x32_bf16 v[44:47], v[84:87], v[172:175], 0
	v_mfma_f32_16x16x32_bf16 v[44:47], v[80:83], v[168:171], v[44:47]
	v_mfma_f32_16x16x32_bf16 v[28:31], v[80:83], v[176:179], 0
	v_mfma_f32_16x16x32_bf16 v[28:31], v[84:87], v[180:183], v[28:31]
	v_mfma_f32_16x16x32_bf16 v[24:27], v[108:111], v[180:183], 0
	v_mfma_f32_16x16x32_bf16 v[24:27], v[104:107], v[176:179], v[24:27]
	v_mfma_f32_16x16x32_bf16 v[8:11], v[104:107], v[208:211], 0
	v_mfma_f32_16x16x32_bf16 v[8:11], v[108:111], v[220:223], v[8:11]
	v_mfma_f32_16x16x32_bf16 v[12:15], v[84:87], v[220:223], 0
	v_mfma_f32_16x16x32_bf16 v[12:15], v[80:83], v[208:211], v[12:15]
	v_mfma_f32_16x16x32_bf16 v[4:7], v[128:131], v[208:211], 0
	v_mfma_f32_16x16x32_bf16 v[4:7], v[132:135], v[220:223], v[4:7]
	v_mfma_f32_16x16x32_bf16 v[0:3], v[156:159], v[220:223], 0
	v_mfma_f32_16x16x32_bf16 v[0:3], v[152:155], v[208:211], v[0:3]
	v_mfma_f32_16x16x32_bf16 v[16:19], v[152:155], v[176:179], 0
	v_mfma_f32_16x16x32_bf16 v[16:19], v[156:159], v[180:183], v[16:19]
	v_mfma_f32_16x16x32_bf16 v[20:23], v[132:135], v[180:183], 0
	v_mfma_f32_16x16x32_bf16 v[20:23], v[128:131], v[176:179], v[20:23]
	v_mfma_f32_16x16x32_bf16 v[36:39], v[128:131], v[168:171], 0
	v_mfma_f32_16x16x32_bf16 v[36:39], v[132:135], v[172:175], v[36:39]
	v_mfma_f32_16x16x32_bf16 v[32:35], v[156:159], v[172:175], 0
	v_mfma_f32_16x16x32_bf16 v[32:35], v[152:155], v[168:171], v[32:35]
	v_mfma_f32_16x16x32_bf16 v[48:51], v[152:155], v[160:163], 0
	v_mfma_f32_16x16x32_bf16 v[48:51], v[156:159], v[164:167], v[48:51]
	v_mfma_f32_16x16x32_bf16 v[52:55], v[132:135], v[164:167], 0
	v_mfma_f32_16x16x32_bf16 v[52:55], v[128:131], v[160:163], v[52:55]
	s_barrier
	s_setprio 0
	s_add_i32 s83, 0, 0x18000
	s_add_i32 s96, 0, 0x1c000
	v_add_u32_e32 v108, s83, v213
	v_add_u32_e32 v156, s96, v213
	ds_read_b128 v[80:83], v108
	ds_read_b128 v[84:87], v108 offset:1024
	ds_read_b128 v[104:107], v108 offset:2048
	ds_read_b128 v[108:111], v108 offset:3072
	ds_read_b128 v[128:131], v156
	ds_read_b128 v[132:135], v156 offset:1024
	ds_read_b128 v[152:155], v156 offset:2048
	ds_read_b128 v[156:159], v156 offset:3072
	s_add_u32 s48, s48, 0x40000
	s_addc_u32 s49, s49, 0
	s_mov_b32 m0, s55
	v_lshl_add_u64 v[234:235], s[48:49], 0, v[184:185]
	ds_read_b128 v[160:163], v218 offset:32768
	ds_read_b128 v[164:167], v218 offset:33792
	ds_read_b128 v[168:171], v218 offset:34816
	ds_read_b128 v[172:175], v218 offset:35840
	ds_read_b128 v[176:179], v218 offset:36864
	ds_read_b128 v[180:183], v218 offset:37888
	ds_read_b128 v[208:211], v218 offset:38912
	ds_read_b128 v[220:223], v218 offset:39936
	global_load_lds_dwordx4 v[234:235], off
	v_lshl_add_u64 v[234:235], s[48:49], 0, v[188:189]
	s_mov_b32 m0, s56
	s_nop 0
	global_load_lds_dwordx4 v[234:235], off
	s_waitcnt vmcnt(8)
	s_waitcnt lgkmcnt(0)
	s_setprio 1
	s_barrier
	v_mfma_f32_16x16x32_bf16 v[148:151], v[80:83], v[160:163], v[148:151]
	v_mfma_f32_16x16x32_bf16 v[148:151], v[84:87], v[164:167], v[148:151]
	v_mfma_f32_16x16x32_bf16 v[144:147], v[108:111], v[164:167], v[144:147]
	v_mfma_f32_16x16x32_bf16 v[144:147], v[104:107], v[160:163], v[144:147]
	v_mfma_f32_16x16x32_bf16 v[120:123], v[104:107], v[168:171], v[120:123]
	v_mfma_f32_16x16x32_bf16 v[120:123], v[108:111], v[172:175], v[120:123]
	v_mfma_f32_16x16x32_bf16 v[124:127], v[84:87], v[172:175], v[124:127]
	v_mfma_f32_16x16x32_bf16 v[124:127], v[80:83], v[168:171], v[124:127]
	v_mfma_f32_16x16x32_bf16 v[100:103], v[80:83], v[176:179], v[100:103]
	v_mfma_f32_16x16x32_bf16 v[100:103], v[84:87], v[180:183], v[100:103]
	v_mfma_f32_16x16x32_bf16 v[96:99], v[108:111], v[180:183], v[96:99]
	v_mfma_f32_16x16x32_bf16 v[96:99], v[104:107], v[176:179], v[96:99]
	v_mfma_f32_16x16x32_bf16 v[72:75], v[104:107], v[208:211], v[72:75]
	v_mfma_f32_16x16x32_bf16 v[72:75], v[108:111], v[220:223], v[72:75]
	v_mfma_f32_16x16x32_bf16 v[76:79], v[84:87], v[220:223], v[76:79]
	v_mfma_f32_16x16x32_bf16 v[76:79], v[80:83], v[208:211], v[76:79]
	v_mfma_f32_16x16x32_bf16 v[68:71], v[128:131], v[208:211], v[68:71]
	v_mfma_f32_16x16x32_bf16 v[68:71], v[132:135], v[220:223], v[68:71]
	v_mfma_f32_16x16x32_bf16 v[64:67], v[156:159], v[220:223], v[64:67]
	v_mfma_f32_16x16x32_bf16 v[64:67], v[152:155], v[208:211], v[64:67]
	v_mfma_f32_16x16x32_bf16 v[88:91], v[152:155], v[176:179], v[88:91]
	v_mfma_f32_16x16x32_bf16 v[88:91], v[156:159], v[180:183], v[88:91]
	v_mfma_f32_16x16x32_bf16 v[92:95], v[132:135], v[180:183], v[92:95]
	v_mfma_f32_16x16x32_bf16 v[92:95], v[128:131], v[176:179], v[92:95]
	v_mfma_f32_16x16x32_bf16 v[116:119], v[128:131], v[168:171], v[116:119]
	v_mfma_f32_16x16x32_bf16 v[116:119], v[132:135], v[172:175], v[116:119]
	v_mfma_f32_16x16x32_bf16 v[112:115], v[156:159], v[172:175], v[112:115]
	v_mfma_f32_16x16x32_bf16 v[112:115], v[152:155], v[168:171], v[112:115]
	v_mfma_f32_16x16x32_bf16 v[136:139], v[152:155], v[160:163], v[136:139]
	v_mfma_f32_16x16x32_bf16 v[136:139], v[156:159], v[164:167], v[136:139]
	v_mfma_f32_16x16x32_bf16 v[140:143], v[132:135], v[164:167], v[140:143]
	v_mfma_f32_16x16x32_bf16 v[140:143], v[128:131], v[160:163], v[140:143]
	s_barrier
	s_setprio 0
	s_add_i32 s48, s83, s52
	v_lshl_add_u64 v[224:225], v[224:225], 0, s[18:19]
	s_mov_b32 m0, s48
	ds_read_b128 v[160:163], v218 offset:49152
	ds_read_b128 v[164:167], v218 offset:50176
	ds_read_b128 v[168:171], v218 offset:51200
	ds_read_b128 v[172:175], v218 offset:52224
	ds_read_b128 v[176:179], v218 offset:53248
	ds_read_b128 v[180:183], v218 offset:54272
	ds_read_b128 v[208:211], v218 offset:55296
	ds_read_b128 v[220:223], v218 offset:56320
	global_load_lds_dwordx4 v[224:225], off
	s_add_i32 m0, s48, 0x2000
	s_add_u32 s46, s46, 0x40080
	v_lshl_add_u64 v[224:225], v[226:227], 0, s[18:19]
	s_addc_u32 s47, s47, 0
	s_add_i32 s48, s96, s52
	global_load_lds_dwordx4 v[224:225], off
	v_lshl_add_u64 v[224:225], s[46:47], 0, v[186:187]
	s_mov_b32 m0, s48
	s_nop 0
	global_load_lds_dwordx4 v[224:225], off
	v_lshl_add_u64 v[224:225], s[46:47], 0, v[190:191]
	s_add_i32 m0, s48, 0x2000
	s_nop 0
	global_load_lds_dwordx4 v[224:225], off
	v_lshl_add_u64 v[224:225], v[230:231], 0, s[18:19]
	s_mov_b32 m0, s68
	s_nop 0
	global_load_lds_dwordx4 v[224:225], off
	v_lshl_add_u64 v[224:225], v[232:233], 0, s[18:19]
	s_mov_b32 m0, s69
	s_nop 0
	global_load_lds_dwordx4 v[224:225], off
	s_waitcnt vmcnt(8)
	s_waitcnt lgkmcnt(0)
	s_setprio 1
	s_barrier
	v_mfma_f32_16x16x32_bf16 v[60:63], v[80:83], v[160:163], v[60:63]
	v_mfma_f32_16x16x32_bf16 v[60:63], v[84:87], v[164:167], v[60:63]
	v_mfma_f32_16x16x32_bf16 v[56:59], v[108:111], v[164:167], v[56:59]
	v_mfma_f32_16x16x32_bf16 v[56:59], v[104:107], v[160:163], v[56:59]
	v_mfma_f32_16x16x32_bf16 v[40:43], v[104:107], v[168:171], v[40:43]
	v_mfma_f32_16x16x32_bf16 v[40:43], v[108:111], v[172:175], v[40:43]
	v_mfma_f32_16x16x32_bf16 v[44:47], v[84:87], v[172:175], v[44:47]
	v_mfma_f32_16x16x32_bf16 v[44:47], v[80:83], v[168:171], v[44:47]
	v_mfma_f32_16x16x32_bf16 v[28:31], v[80:83], v[176:179], v[28:31]
	v_mfma_f32_16x16x32_bf16 v[28:31], v[84:87], v[180:183], v[28:31]
	v_mfma_f32_16x16x32_bf16 v[24:27], v[108:111], v[180:183], v[24:27]
	v_mfma_f32_16x16x32_bf16 v[24:27], v[104:107], v[176:179], v[24:27]
	v_mfma_f32_16x16x32_bf16 v[8:11], v[104:107], v[208:211], v[8:11]
	v_mfma_f32_16x16x32_bf16 v[8:11], v[108:111], v[220:223], v[8:11]
	v_mfma_f32_16x16x32_bf16 v[12:15], v[84:87], v[220:223], v[12:15]
	v_mfma_f32_16x16x32_bf16 v[12:15], v[80:83], v[208:211], v[12:15]
	v_mfma_f32_16x16x32_bf16 v[4:7], v[128:131], v[208:211], v[4:7]
	v_mfma_f32_16x16x32_bf16 v[4:7], v[132:135], v[220:223], v[4:7]
	v_mfma_f32_16x16x32_bf16 v[0:3], v[156:159], v[220:223], v[0:3]
	v_mfma_f32_16x16x32_bf16 v[0:3], v[152:155], v[208:211], v[0:3]
	v_mfma_f32_16x16x32_bf16 v[16:19], v[152:155], v[176:179], v[16:19]
	v_mfma_f32_16x16x32_bf16 v[16:19], v[156:159], v[180:183], v[16:19]
	v_mfma_f32_16x16x32_bf16 v[20:23], v[132:135], v[180:183], v[20:23]
	v_mfma_f32_16x16x32_bf16 v[20:23], v[128:131], v[176:179], v[20:23]
	v_mfma_f32_16x16x32_bf16 v[36:39], v[128:131], v[168:171], v[36:39]
	v_mfma_f32_16x16x32_bf16 v[36:39], v[132:135], v[172:175], v[36:39]
	v_mfma_f32_16x16x32_bf16 v[32:35], v[156:159], v[172:175], v[32:35]
	v_mfma_f32_16x16x32_bf16 v[32:35], v[152:155], v[168:171], v[32:35]
	v_mfma_f32_16x16x32_bf16 v[48:51], v[152:155], v[160:163], v[48:51]
	v_mfma_f32_16x16x32_bf16 v[48:51], v[156:159], v[164:167], v[48:51]
	v_mfma_f32_16x16x32_bf16 v[52:55], v[132:135], v[164:167], v[52:55]
	v_mfma_f32_16x16x32_bf16 v[52:55], v[128:131], v[160:163], v[52:55]
	s_barrier
	s_setprio 0
	s_add_i32 s95, s95, 2
	s_add_u32 s44, s44, 0x100
	s_addc_u32 s45, s45, 0
	s_add_u32 s93, s93, 0x100
	s_addc_u32 s94, s94, 0
	s_cmp_gt_u32 s95, 13
.LBB0_668:
	ds_read_b128 v[80:83], v216
	ds_read_b128 v[84:87], v216 offset:1024
	ds_read_b128 v[104:107], v216 offset:2048
	ds_read_b128 v[108:111], v216 offset:3072
	ds_read_b128 v[128:131], v217
	ds_read_b128 v[132:135], v217 offset:1024
	ds_read_b128 v[152:155], v217 offset:2048
	ds_read_b128 v[156:159], v217 offset:3072
	s_add_u32 s46, s44, 0xfffc0080
	s_addc_u32 s47, s45, -1
	s_cmp_eq_u32 s95, 12
	s_cselect_b32 s49, s23, s47
	s_cselect_b32 s48, s43, s46
	s_cselect_b32 s47, s37, s94
	s_cselect_b32 s46, s92, s93
	v_lshl_add_u64 v[224:225], s[44:45], 0, v[194:195]
	s_add_i32 m0, s53, 0xc000
	ds_read_b128 v[160:163], v218
	ds_read_b128 v[164:167], v218 offset:1024
	ds_read_b128 v[168:171], v218 offset:2048
	ds_read_b128 v[172:175], v218 offset:3072
	ds_read_b128 v[176:179], v218 offset:4096
	ds_read_b128 v[180:183], v218 offset:5120
	ds_read_b128 v[208:211], v218 offset:6144
	ds_read_b128 v[220:223], v218 offset:7168
	global_load_lds_dwordx4 v[224:225], off
	v_lshl_add_u64 v[224:225], s[44:45], 0, v[196:197]
	s_add_i32 m0, s53, 0xe000
	s_nop 0
	global_load_lds_dwordx4 v[224:225], off
	s_waitcnt vmcnt(8)
	s_waitcnt lgkmcnt(0)
	s_setprio 1
	s_barrier
	v_mfma_f32_16x16x32_bf16 v[148:151], v[80:83], v[160:163], v[148:151]
	v_mfma_f32_16x16x32_bf16 v[148:151], v[84:87], v[164:167], v[148:151]
	v_mfma_f32_16x16x32_bf16 v[144:147], v[108:111], v[164:167], v[144:147]
	v_mfma_f32_16x16x32_bf16 v[144:147], v[104:107], v[160:163], v[144:147]
	v_mfma_f32_16x16x32_bf16 v[120:123], v[104:107], v[168:171], v[120:123]
	v_mfma_f32_16x16x32_bf16 v[120:123], v[108:111], v[172:175], v[120:123]
	v_mfma_f32_16x16x32_bf16 v[124:127], v[84:87], v[172:175], v[124:127]
	v_mfma_f32_16x16x32_bf16 v[124:127], v[80:83], v[168:171], v[124:127]
	v_mfma_f32_16x16x32_bf16 v[100:103], v[80:83], v[176:179], v[100:103]
	v_mfma_f32_16x16x32_bf16 v[100:103], v[84:87], v[180:183], v[100:103]
	v_mfma_f32_16x16x32_bf16 v[96:99], v[108:111], v[180:183], v[96:99]
	v_mfma_f32_16x16x32_bf16 v[96:99], v[104:107], v[176:179], v[96:99]
	v_mfma_f32_16x16x32_bf16 v[72:75], v[104:107], v[208:211], v[72:75]
	v_mfma_f32_16x16x32_bf16 v[72:75], v[108:111], v[220:223], v[72:75]
	v_mfma_f32_16x16x32_bf16 v[76:79], v[84:87], v[220:223], v[76:79]
	v_mfma_f32_16x16x32_bf16 v[76:79], v[80:83], v[208:211], v[76:79]
	v_mfma_f32_16x16x32_bf16 v[68:71], v[128:131], v[208:211], v[68:71]
	v_mfma_f32_16x16x32_bf16 v[68:71], v[132:135], v[220:223], v[68:71]
	v_mfma_f32_16x16x32_bf16 v[64:67], v[156:159], v[220:223], v[64:67]
	v_mfma_f32_16x16x32_bf16 v[64:67], v[152:155], v[208:211], v[64:67]
	v_mfma_f32_16x16x32_bf16 v[88:91], v[152:155], v[176:179], v[88:91]
	v_mfma_f32_16x16x32_bf16 v[88:91], v[156:159], v[180:183], v[88:91]
	v_mfma_f32_16x16x32_bf16 v[92:95], v[132:135], v[180:183], v[92:95]
	v_mfma_f32_16x16x32_bf16 v[92:95], v[128:131], v[176:179], v[92:95]
	v_mfma_f32_16x16x32_bf16 v[116:119], v[128:131], v[168:171], v[116:119]
	v_mfma_f32_16x16x32_bf16 v[116:119], v[132:135], v[172:175], v[116:119]
	v_mfma_f32_16x16x32_bf16 v[112:115], v[156:159], v[172:175], v[112:115]
	v_mfma_f32_16x16x32_bf16 v[112:115], v[152:155], v[168:171], v[112:115]
	v_mfma_f32_16x16x32_bf16 v[136:139], v[152:155], v[160:163], v[136:139]
	v_mfma_f32_16x16x32_bf16 v[136:139], v[156:159], v[164:167], v[136:139]
	v_mfma_f32_16x16x32_bf16 v[140:143], v[132:135], v[164:167], v[140:143]
	v_mfma_f32_16x16x32_bf16 v[140:143], v[128:131], v[160:163], v[140:143]
	s_barrier
	s_setprio 0
	s_add_i32 s83, s78, s52
	v_lshl_add_u64 v[224:225], s[46:47], 0, v[186:187]
	s_mov_b32 m0, s83
	ds_read_b128 v[160:163], v218 offset:16384
	ds_read_b128 v[164:167], v218 offset:17408
	ds_read_b128 v[168:171], v218 offset:18432
	ds_read_b128 v[172:175], v218 offset:19456
	ds_read_b128 v[176:179], v218 offset:20480
	ds_read_b128 v[180:183], v218 offset:21504
	ds_read_b128 v[208:211], v218 offset:22528
	ds_read_b128 v[220:223], v218 offset:23552
	global_load_lds_dwordx4 v[224:225], off
	s_add_i32 m0, s83, 0x2000
	s_add_u32 s96, s46, 0x40000
	v_lshl_add_u64 v[226:227], s[46:47], 0, v[190:191]
	s_addc_u32 s97, s47, 0
	s_add_i32 s83, s79, s52
	global_load_lds_dwordx4 v[226:227], off
	v_lshl_add_u64 v[230:231], s[96:97], 0, v[186:187]
	s_mov_b32 m0, s83
	v_lshl_add_u64 v[232:233], s[48:49], 0, v[188:189]
	global_load_lds_dwordx4 v[230:231], off
	v_lshl_add_u64 v[230:231], s[96:97], 0, v[190:191]
	s_add_i32 m0, s83, 0x2000
	s_nop 0
	global_load_lds_dwordx4 v[230:231], off
	v_lshl_add_u64 v[230:231], s[48:49], 0, v[184:185]
	s_mov_b32 m0, s53
	s_nop 0
	global_load_lds_dwordx4 v[230:231], off
	s_mov_b32 m0, s54
	s_nop 0
	global_load_lds_dwordx4 v[232:233], off
	s_waitcnt vmcnt(8)
	s_waitcnt lgkmcnt(0)
	s_setprio 1
	s_barrier
	v_mfma_f32_16x16x32_bf16 v[60:63], v[80:83], v[160:163], v[60:63]
	v_mfma_f32_16x16x32_bf16 v[60:63], v[84:87], v[164:167], v[60:63]
	v_mfma_f32_16x16x32_bf16 v[56:59], v[108:111], v[164:167], v[56:59]
	v_mfma_f32_16x16x32_bf16 v[56:59], v[104:107], v[160:163], v[56:59]
	v_mfma_f32_16x16x32_bf16 v[40:43], v[104:107], v[168:171], v[40:43]
	v_mfma_f32_16x16x32_bf16 v[40:43], v[108:111], v[172:175], v[40:43]
	v_mfma_f32_16x16x32_bf16 v[44:47], v[84:87], v[172:175], v[44:47]
	v_mfma_f32_16x16x32_bf16 v[44:47], v[80:83], v[168:171], v[44:47]
	v_mfma_f32_16x16x32_bf16 v[28:31], v[80:83], v[176:179], v[28:31]
	v_mfma_f32_16x16x32_bf16 v[28:31], v[84:87], v[180:183], v[28:31]
	v_mfma_f32_16x16x32_bf16 v[24:27], v[108:111], v[180:183], v[24:27]
	v_mfma_f32_16x16x32_bf16 v[24:27], v[104:107], v[176:179], v[24:27]
	v_mfma_f32_16x16x32_bf16 v[8:11], v[104:107], v[208:211], v[8:11]
	v_mfma_f32_16x16x32_bf16 v[8:11], v[108:111], v[220:223], v[8:11]
	v_mfma_f32_16x16x32_bf16 v[12:15], v[84:87], v[220:223], v[12:15]
	v_mfma_f32_16x16x32_bf16 v[12:15], v[80:83], v[208:211], v[12:15]
	v_mfma_f32_16x16x32_bf16 v[4:7], v[128:131], v[208:211], v[4:7]
	v_mfma_f32_16x16x32_bf16 v[4:7], v[132:135], v[220:223], v[4:7]
	v_mfma_f32_16x16x32_bf16 v[0:3], v[156:159], v[220:223], v[0:3]
	v_mfma_f32_16x16x32_bf16 v[0:3], v[152:155], v[208:211], v[0:3]
	v_mfma_f32_16x16x32_bf16 v[16:19], v[152:155], v[176:179], v[16:19]
	v_mfma_f32_16x16x32_bf16 v[16:19], v[156:159], v[180:183], v[16:19]
	v_mfma_f32_16x16x32_bf16 v[20:23], v[132:135], v[180:183], v[20:23]
	v_mfma_f32_16x16x32_bf16 v[20:23], v[128:131], v[176:179], v[20:23]
	v_mfma_f32_16x16x32_bf16 v[36:39], v[128:131], v[168:171], v[36:39]
	v_mfma_f32_16x16x32_bf16 v[36:39], v[132:135], v[172:175], v[36:39]
	v_mfma_f32_16x16x32_bf16 v[32:35], v[156:159], v[172:175], v[32:35]
	v_mfma_f32_16x16x32_bf16 v[32:35], v[152:155], v[168:171], v[32:35]
	v_mfma_f32_16x16x32_bf16 v[48:51], v[152:155], v[160:163], v[48:51]
	v_mfma_f32_16x16x32_bf16 v[48:51], v[156:159], v[164:167], v[48:51]
	v_mfma_f32_16x16x32_bf16 v[52:55], v[132:135], v[164:167], v[52:55]
	v_mfma_f32_16x16x32_bf16 v[52:55], v[128:131], v[160:163], v[52:55]
	s_barrier
	s_setprio 0
	s_add_i32 s83, 0, 0x18000
	s_add_i32 s96, 0, 0x1c000
	v_add_u32_e32 v108, s83, v213
	v_add_u32_e32 v156, s96, v213
	ds_read_b128 v[80:83], v108
	ds_read_b128 v[84:87], v108 offset:1024
	ds_read_b128 v[104:107], v108 offset:2048
	ds_read_b128 v[108:111], v108 offset:3072
	ds_read_b128 v[128:131], v156
	ds_read_b128 v[132:135], v156 offset:1024
	ds_read_b128 v[152:155], v156 offset:2048
	ds_read_b128 v[156:159], v156 offset:3072
	s_add_u32 s48, s48, 0x40000
	s_addc_u32 s49, s49, 0
	s_mov_b32 m0, s55
	v_lshl_add_u64 v[234:235], s[48:49], 0, v[184:185]
	ds_read_b128 v[160:163], v218 offset:32768
	ds_read_b128 v[164:167], v218 offset:33792
	ds_read_b128 v[168:171], v218 offset:34816
	ds_read_b128 v[172:175], v218 offset:35840
	ds_read_b128 v[176:179], v218 offset:36864
	ds_read_b128 v[180:183], v218 offset:37888
	ds_read_b128 v[208:211], v218 offset:38912
	ds_read_b128 v[220:223], v218 offset:39936
	global_load_lds_dwordx4 v[234:235], off
	v_lshl_add_u64 v[234:235], s[48:49], 0, v[188:189]
	s_mov_b32 m0, s56
	s_nop 0
	global_load_lds_dwordx4 v[234:235], off
	s_waitcnt vmcnt(8)
	s_waitcnt lgkmcnt(0)
	s_setprio 1
	s_barrier
	v_mfma_f32_16x16x32_bf16 v[148:151], v[80:83], v[160:163], v[148:151]
	v_mfma_f32_16x16x32_bf16 v[148:151], v[84:87], v[164:167], v[148:151]
	v_mfma_f32_16x16x32_bf16 v[144:147], v[108:111], v[164:167], v[144:147]
	v_mfma_f32_16x16x32_bf16 v[144:147], v[104:107], v[160:163], v[144:147]
	v_mfma_f32_16x16x32_bf16 v[120:123], v[104:107], v[168:171], v[120:123]
	v_mfma_f32_16x16x32_bf16 v[120:123], v[108:111], v[172:175], v[120:123]
	v_mfma_f32_16x16x32_bf16 v[124:127], v[84:87], v[172:175], v[124:127]
	v_mfma_f32_16x16x32_bf16 v[124:127], v[80:83], v[168:171], v[124:127]
	v_mfma_f32_16x16x32_bf16 v[100:103], v[80:83], v[176:179], v[100:103]
	v_mfma_f32_16x16x32_bf16 v[100:103], v[84:87], v[180:183], v[100:103]
	v_mfma_f32_16x16x32_bf16 v[96:99], v[108:111], v[180:183], v[96:99]
	v_mfma_f32_16x16x32_bf16 v[96:99], v[104:107], v[176:179], v[96:99]
	v_mfma_f32_16x16x32_bf16 v[72:75], v[104:107], v[208:211], v[72:75]
	v_mfma_f32_16x16x32_bf16 v[72:75], v[108:111], v[220:223], v[72:75]
	v_mfma_f32_16x16x32_bf16 v[76:79], v[84:87], v[220:223], v[76:79]
	v_mfma_f32_16x16x32_bf16 v[76:79], v[80:83], v[208:211], v[76:79]
	v_mfma_f32_16x16x32_bf16 v[68:71], v[128:131], v[208:211], v[68:71]
	v_mfma_f32_16x16x32_bf16 v[68:71], v[132:135], v[220:223], v[68:71]
	v_mfma_f32_16x16x32_bf16 v[64:67], v[156:159], v[220:223], v[64:67]
	v_mfma_f32_16x16x32_bf16 v[64:67], v[152:155], v[208:211], v[64:67]
	v_mfma_f32_16x16x32_bf16 v[88:91], v[152:155], v[176:179], v[88:91]
	v_mfma_f32_16x16x32_bf16 v[88:91], v[156:159], v[180:183], v[88:91]
	v_mfma_f32_16x16x32_bf16 v[92:95], v[132:135], v[180:183], v[92:95]
	v_mfma_f32_16x16x32_bf16 v[92:95], v[128:131], v[176:179], v[92:95]
	v_mfma_f32_16x16x32_bf16 v[116:119], v[128:131], v[168:171], v[116:119]
	v_mfma_f32_16x16x32_bf16 v[116:119], v[132:135], v[172:175], v[116:119]
	v_mfma_f32_16x16x32_bf16 v[112:115], v[156:159], v[172:175], v[112:115]
	v_mfma_f32_16x16x32_bf16 v[112:115], v[152:155], v[168:171], v[112:115]
	v_mfma_f32_16x16x32_bf16 v[136:139], v[152:155], v[160:163], v[136:139]
	v_mfma_f32_16x16x32_bf16 v[136:139], v[156:159], v[164:167], v[136:139]
	v_mfma_f32_16x16x32_bf16 v[140:143], v[132:135], v[164:167], v[140:143]
	v_mfma_f32_16x16x32_bf16 v[140:143], v[128:131], v[160:163], v[140:143]
	s_barrier
	s_setprio 0
	s_add_i32 s48, s83, s52
	v_lshl_add_u64 v[224:225], v[224:225], 0, s[18:19]
	s_mov_b32 m0, s48
	ds_read_b128 v[160:163], v218 offset:49152
	ds_read_b128 v[164:167], v218 offset:50176
	ds_read_b128 v[168:171], v218 offset:51200
	ds_read_b128 v[172:175], v218 offset:52224
	ds_read_b128 v[176:179], v218 offset:53248
	ds_read_b128 v[180:183], v218 offset:54272
	ds_read_b128 v[208:211], v218 offset:55296
	ds_read_b128 v[220:223], v218 offset:56320
	global_load_lds_dwordx4 v[224:225], off
	s_add_i32 m0, s48, 0x2000
	s_add_u32 s46, s46, 0x40080
	v_lshl_add_u64 v[224:225], v[226:227], 0, s[18:19]
	s_addc_u32 s47, s47, 0
	s_add_i32 s48, s96, s52
	global_load_lds_dwordx4 v[224:225], off
	v_lshl_add_u64 v[224:225], s[46:47], 0, v[186:187]
	s_mov_b32 m0, s48
	s_nop 0
	global_load_lds_dwordx4 v[224:225], off
	v_lshl_add_u64 v[224:225], s[46:47], 0, v[190:191]
	s_add_i32 m0, s48, 0x2000
	s_nop 0
	global_load_lds_dwordx4 v[224:225], off
	v_lshl_add_u64 v[224:225], v[230:231], 0, s[18:19]
	s_mov_b32 m0, s68
	s_nop 0
	global_load_lds_dwordx4 v[224:225], off
	v_lshl_add_u64 v[224:225], v[232:233], 0, s[18:19]
	s_mov_b32 m0, s69
	s_nop 0
	global_load_lds_dwordx4 v[224:225], off
	s_waitcnt vmcnt(8)
	s_waitcnt lgkmcnt(0)
	s_setprio 1
	s_barrier
	v_mfma_f32_16x16x32_bf16 v[60:63], v[80:83], v[160:163], v[60:63]
	v_mfma_f32_16x16x32_bf16 v[60:63], v[84:87], v[164:167], v[60:63]
	v_mfma_f32_16x16x32_bf16 v[56:59], v[108:111], v[164:167], v[56:59]
	v_mfma_f32_16x16x32_bf16 v[56:59], v[104:107], v[160:163], v[56:59]
	v_mfma_f32_16x16x32_bf16 v[40:43], v[104:107], v[168:171], v[40:43]
	v_mfma_f32_16x16x32_bf16 v[40:43], v[108:111], v[172:175], v[40:43]
	v_mfma_f32_16x16x32_bf16 v[44:47], v[84:87], v[172:175], v[44:47]
	v_mfma_f32_16x16x32_bf16 v[44:47], v[80:83], v[168:171], v[44:47]
	v_mfma_f32_16x16x32_bf16 v[28:31], v[80:83], v[176:179], v[28:31]
	v_mfma_f32_16x16x32_bf16 v[28:31], v[84:87], v[180:183], v[28:31]
	v_mfma_f32_16x16x32_bf16 v[24:27], v[108:111], v[180:183], v[24:27]
	v_mfma_f32_16x16x32_bf16 v[24:27], v[104:107], v[176:179], v[24:27]
	v_mfma_f32_16x16x32_bf16 v[8:11], v[104:107], v[208:211], v[8:11]
	v_mfma_f32_16x16x32_bf16 v[8:11], v[108:111], v[220:223], v[8:11]
	v_mfma_f32_16x16x32_bf16 v[12:15], v[84:87], v[220:223], v[12:15]
	v_mfma_f32_16x16x32_bf16 v[12:15], v[80:83], v[208:211], v[12:15]
	v_mfma_f32_16x16x32_bf16 v[4:7], v[128:131], v[208:211], v[4:7]
	v_mfma_f32_16x16x32_bf16 v[4:7], v[132:135], v[220:223], v[4:7]
	v_mfma_f32_16x16x32_bf16 v[0:3], v[156:159], v[220:223], v[0:3]
	v_mfma_f32_16x16x32_bf16 v[0:3], v[152:155], v[208:211], v[0:3]
	v_mfma_f32_16x16x32_bf16 v[16:19], v[152:155], v[176:179], v[16:19]
	v_mfma_f32_16x16x32_bf16 v[16:19], v[156:159], v[180:183], v[16:19]
	v_mfma_f32_16x16x32_bf16 v[20:23], v[132:135], v[180:183], v[20:23]
	v_mfma_f32_16x16x32_bf16 v[20:23], v[128:131], v[176:179], v[20:23]
	v_mfma_f32_16x16x32_bf16 v[36:39], v[128:131], v[168:171], v[36:39]
	v_mfma_f32_16x16x32_bf16 v[36:39], v[132:135], v[172:175], v[36:39]
	v_mfma_f32_16x16x32_bf16 v[32:35], v[156:159], v[172:175], v[32:35]
	v_mfma_f32_16x16x32_bf16 v[32:35], v[152:155], v[168:171], v[32:35]
	v_mfma_f32_16x16x32_bf16 v[48:51], v[152:155], v[160:163], v[48:51]
	v_mfma_f32_16x16x32_bf16 v[48:51], v[156:159], v[164:167], v[48:51]
	v_mfma_f32_16x16x32_bf16 v[52:55], v[132:135], v[164:167], v[52:55]
	v_mfma_f32_16x16x32_bf16 v[52:55], v[128:131], v[160:163], v[52:55]
	s_barrier
	s_setprio 0
	s_add_i32 s95, s95, 2
	s_add_u32 s44, s44, 0x100
	s_addc_u32 s45, s45, 0
	s_add_u32 s93, s93, 0x100
	s_addc_u32 s94, s94, 0
	s_cmp_gt_u32 s95, 13
	s_cbranch_scc0 .LBB0_668
	s_and_b64 vcc, exec, s[20:21]
	s_cbranch_vccz .LBB0_671
	s_barrier

.LBB0_758:
	s_ashr_i32 s19, s18, 31
	s_lshl_b64 s[20:21], s[18:19], 19
	s_add_u32 s20, s62, s20
	s_addc_u32 s21, s63, s21
	s_and_b64 s[22:23], s[4:5], exec
	s_cselect_b32 s19, s21, s39
	s_cselect_b32 s57, s20, s38
	s_ashr_i32 s11, s10, 31
	s_lshl_b64 s[22:23], s[10:11], 19
	s_add_u32 s22, s40, s22
	s_addc_u32 s23, s41, s23
	s_and_b64 s[4:5], s[4:5], exec
	s_cselect_b32 s11, s23, s37
	s_cselect_b32 s58, s22, s36
	s_add_u32 s4, s38, 0x40080
	s_addc_u32 s5, s39, 0
	s_add_u32 s59, s36, 0x100
	s_addc_u32 s66, s37, 0
	s_mov_b32 s67, -2
	ds_read_b128 v[146:149], v172
	ds_read_b128 v[166:169], v172 offset:1024
	ds_read_b128 v[176:179], v172 offset:2048
	ds_read_b128 v[180:183], v172 offset:3072
	ds_read_b128 v[184:187], v173
	ds_read_b128 v[188:191], v173 offset:1024
	ds_read_b128 v[192:195], v173 offset:2048
	ds_read_b128 v[196:199], v173 offset:3072
	s_add_u32 s36, s4, 0xfffc0080
	s_addc_u32 s37, s5, -1
	s_cmp_eq_u32 s67, 12
	s_cselect_b32 s39, s19, s37
	s_cselect_b32 s38, s57, s36
	s_cselect_b32 s37, s11, s66
	s_cselect_b32 s36, s58, s59
	v_lshl_add_u64 v[150:151], s[4:5], 0, v[138:139]
	s_add_i32 m0, s27, 0xc000
	ds_read_b128 v[200:203], v174
	ds_read_b128 v[204:207], v174 offset:1024
	ds_read_b128 v[208:211], v174 offset:2048
	ds_read_b128 v[212:215], v174 offset:3072
	ds_read_b128 v[216:219], v174 offset:4096
	ds_read_b128 v[220:223], v174 offset:5120
	ds_read_b128 v[224:227], v174 offset:6144
	ds_read_b128 v[230:233], v174 offset:7168
	global_load_lds_dwordx4 v[150:151], off
	v_lshl_add_u64 v[150:151], s[4:5], 0, v[140:141]
	s_add_i32 m0, s27, 0xe000
	s_nop 0
	global_load_lds_dwordx4 v[150:151], off
	s_waitcnt vmcnt(8)
	s_waitcnt lgkmcnt(0)
	s_setprio 1
	s_barrier
	v_mfma_f32_16x16x32_bf16 v[124:127], v[146:149], v[200:203], 0
	v_mfma_f32_16x16x32_bf16 v[124:127], v[166:169], v[204:207], v[124:127]
	v_mfma_f32_16x16x32_bf16 v[120:123], v[180:183], v[204:207], 0
	v_mfma_f32_16x16x32_bf16 v[120:123], v[176:179], v[200:203], v[120:123]
	v_mfma_f32_16x16x32_bf16 v[104:107], v[176:179], v[208:211], 0
	v_mfma_f32_16x16x32_bf16 v[104:107], v[180:183], v[212:215], v[104:107]
	v_mfma_f32_16x16x32_bf16 v[108:111], v[166:169], v[212:215], 0
	v_mfma_f32_16x16x32_bf16 v[108:111], v[146:149], v[208:211], v[108:111]
	v_mfma_f32_16x16x32_bf16 v[92:95], v[146:149], v[216:219], 0
	v_mfma_f32_16x16x32_bf16 v[92:95], v[166:169], v[220:223], v[92:95]
	v_mfma_f32_16x16x32_bf16 v[88:91], v[180:183], v[220:223], 0
	v_mfma_f32_16x16x32_bf16 v[88:91], v[176:179], v[216:219], v[88:91]
	v_mfma_f32_16x16x32_bf16 v[72:75], v[176:179], v[224:227], 0
	v_mfma_f32_16x16x32_bf16 v[72:75], v[180:183], v[230:233], v[72:75]
	v_mfma_f32_16x16x32_bf16 v[76:79], v[166:169], v[230:233], 0
	v_mfma_f32_16x16x32_bf16 v[76:79], v[146:149], v[224:227], v[76:79]
	v_mfma_f32_16x16x32_bf16 v[68:71], v[184:187], v[224:227], 0
	v_mfma_f32_16x16x32_bf16 v[68:71], v[188:191], v[230:233], v[68:71]
	v_mfma_f32_16x16x32_bf16 v[64:67], v[196:199], v[230:233], 0
	v_mfma_f32_16x16x32_bf16 v[64:67], v[192:195], v[224:227], v[64:67]
	v_mfma_f32_16x16x32_bf16 v[80:83], v[192:195], v[216:219], 0
	v_mfma_f32_16x16x32_bf16 v[80:83], v[196:199], v[220:223], v[80:83]
	v_mfma_f32_16x16x32_bf16 v[84:87], v[188:191], v[220:223], 0
	v_mfma_f32_16x16x32_bf16 v[84:87], v[184:187], v[216:219], v[84:87]
	v_mfma_f32_16x16x32_bf16 v[100:103], v[184:187], v[208:211], 0
	v_mfma_f32_16x16x32_bf16 v[100:103], v[188:191], v[212:215], v[100:103]
	v_mfma_f32_16x16x32_bf16 v[96:99], v[196:199], v[212:215], 0
	v_mfma_f32_16x16x32_bf16 v[96:99], v[192:195], v[208:211], v[96:99]
	v_mfma_f32_16x16x32_bf16 v[112:115], v[192:195], v[200:203], 0
	v_mfma_f32_16x16x32_bf16 v[112:115], v[196:199], v[204:207], v[112:115]
	v_mfma_f32_16x16x32_bf16 v[116:119], v[188:191], v[204:207], 0
	v_mfma_f32_16x16x32_bf16 v[116:119], v[184:187], v[200:203], v[116:119]
	s_barrier
	s_setprio 0
	s_add_i32 s68, s53, s42
	v_lshl_add_u64 v[150:151], s[36:37], 0, v[132:133]
	s_mov_b32 m0, s68
	ds_read_b128 v[200:203], v174 offset:16384
	ds_read_b128 v[204:207], v174 offset:17408
	ds_read_b128 v[208:211], v174 offset:18432
	ds_read_b128 v[212:215], v174 offset:19456
	ds_read_b128 v[216:219], v174 offset:20480
	ds_read_b128 v[220:223], v174 offset:21504
	ds_read_b128 v[224:227], v174 offset:22528
	ds_read_b128 v[230:233], v174 offset:23552
	global_load_lds_dwordx4 v[150:151], off
	s_add_i32 m0, s68, 0x2000
	s_add_u32 s68, s36, 0x40000
	v_lshl_add_u64 v[154:155], s[36:37], 0, v[128:129]
	s_addc_u32 s69, s37, 0
	s_add_i32 s70, s54, s42
	global_load_lds_dwordx4 v[154:155], off
	v_lshl_add_u64 v[158:159], s[68:69], 0, v[132:133]
	s_mov_b32 m0, s70
	v_lshl_add_u64 v[162:163], s[38:39], 0, v[130:131]
	global_load_lds_dwordx4 v[158:159], off
	v_lshl_add_u64 v[158:159], s[68:69], 0, v[128:129]
	s_add_i32 m0, s70, 0x2000
	s_nop 0
	global_load_lds_dwordx4 v[158:159], off
	v_lshl_add_u64 v[158:159], s[38:39], 0, v[134:135]
	s_mov_b32 m0, s27
	s_nop 0
	global_load_lds_dwordx4 v[158:159], off
	s_mov_b32 m0, s45
	s_nop 0
	global_load_lds_dwordx4 v[162:163], off
	s_waitcnt vmcnt(8)
	s_waitcnt lgkmcnt(0)
	s_setprio 1
	s_barrier
	v_mfma_f32_16x16x32_bf16 v[60:63], v[146:149], v[200:203], 0
	v_mfma_f32_16x16x32_bf16 v[60:63], v[166:169], v[204:207], v[60:63]
	v_mfma_f32_16x16x32_bf16 v[56:59], v[180:183], v[204:207], 0
	v_mfma_f32_16x16x32_bf16 v[56:59], v[176:179], v[200:203], v[56:59]
	v_mfma_f32_16x16x32_bf16 v[40:43], v[176:179], v[208:211], 0
	v_mfma_f32_16x16x32_bf16 v[40:43], v[180:183], v[212:215], v[40:43]
	v_mfma_f32_16x16x32_bf16 v[44:47], v[166:169], v[212:215], 0
	v_mfma_f32_16x16x32_bf16 v[44:47], v[146:149], v[208:211], v[44:47]
	v_mfma_f32_16x16x32_bf16 v[28:31], v[146:149], v[216:219], 0
	v_mfma_f32_16x16x32_bf16 v[28:31], v[166:169], v[220:223], v[28:31]
	v_mfma_f32_16x16x32_bf16 v[24:27], v[180:183], v[220:223], 0
	v_mfma_f32_16x16x32_bf16 v[24:27], v[176:179], v[216:219], v[24:27]
	v_mfma_f32_16x16x32_bf16 v[8:11], v[176:179], v[224:227], 0
	v_mfma_f32_16x16x32_bf16 v[8:11], v[180:183], v[230:233], v[8:11]
	v_mfma_f32_16x16x32_bf16 v[12:15], v[166:169], v[230:233], 0
	v_mfma_f32_16x16x32_bf16 v[12:15], v[146:149], v[224:227], v[12:15]
	v_mfma_f32_16x16x32_bf16 v[4:7], v[184:187], v[224:227], 0
	v_mfma_f32_16x16x32_bf16 v[4:7], v[188:191], v[230:233], v[4:7]
	v_mfma_f32_16x16x32_bf16 v[0:3], v[196:199], v[230:233], 0
	v_mfma_f32_16x16x32_bf16 v[0:3], v[192:195], v[224:227], v[0:3]
	v_mfma_f32_16x16x32_bf16 v[16:19], v[192:195], v[216:219], 0
	v_mfma_f32_16x16x32_bf16 v[16:19], v[196:199], v[220:223], v[16:19]
	v_mfma_f32_16x16x32_bf16 v[20:23], v[188:191], v[220:223], 0
	v_mfma_f32_16x16x32_bf16 v[20:23], v[184:187], v[216:219], v[20:23]
	v_mfma_f32_16x16x32_bf16 v[36:39], v[184:187], v[208:211], 0
	v_mfma_f32_16x16x32_bf16 v[36:39], v[188:191], v[212:215], v[36:39]
	v_mfma_f32_16x16x32_bf16 v[32:35], v[196:199], v[212:215], 0
	v_mfma_f32_16x16x32_bf16 v[32:35], v[192:195], v[208:211], v[32:35]
	v_mfma_f32_16x16x32_bf16 v[48:51], v[192:195], v[200:203], 0
	v_mfma_f32_16x16x32_bf16 v[48:51], v[196:199], v[204:207], v[48:51]
	v_mfma_f32_16x16x32_bf16 v[52:55], v[188:191], v[204:207], 0
	v_mfma_f32_16x16x32_bf16 v[52:55], v[184:187], v[200:203], v[52:55]
	s_barrier
	s_setprio 0
	s_add_i32 s68, 0, 0x18000
	v_add_u32_e32 v152, s68, v157
	s_add_i32 s69, 0, 0x1c000
	ds_read_b128 v[146:149], v152
	ds_read_b128 v[166:169], v152 offset:1024
	ds_read_b128 v[176:179], v152 offset:2048
	ds_read_b128 v[180:183], v152 offset:3072
	v_add_u32_e32 v152, s69, v157
	ds_read_b128 v[184:187], v152
	ds_read_b128 v[188:191], v152 offset:1024
	ds_read_b128 v[192:195], v152 offset:2048
	ds_read_b128 v[196:199], v152 offset:3072
	s_add_u32 s38, s38, 0x40000
	s_addc_u32 s39, s39, 0
	s_mov_b32 m0, s46
	v_lshl_add_u64 v[234:235], s[38:39], 0, v[134:135]
	ds_read_b128 v[200:203], v174 offset:32768
	ds_read_b128 v[204:207], v174 offset:33792
	ds_read_b128 v[208:211], v174 offset:34816
	ds_read_b128 v[212:215], v174 offset:35840
	ds_read_b128 v[216:219], v174 offset:36864
	ds_read_b128 v[220:223], v174 offset:37888
	ds_read_b128 v[224:227], v174 offset:38912
	ds_read_b128 v[230:233], v174 offset:39936
	global_load_lds_dwordx4 v[234:235], off
	v_lshl_add_u64 v[234:235], s[38:39], 0, v[130:131]
	s_mov_b32 m0, s47
	s_nop 0
	global_load_lds_dwordx4 v[234:235], off
	s_waitcnt vmcnt(8)
	s_waitcnt lgkmcnt(0)
	s_setprio 1
	s_barrier
	v_mfma_f32_16x16x32_bf16 v[124:127], v[146:149], v[200:203], v[124:127]
	v_mfma_f32_16x16x32_bf16 v[124:127], v[166:169], v[204:207], v[124:127]
	v_mfma_f32_16x16x32_bf16 v[120:123], v[180:183], v[204:207], v[120:123]
	v_mfma_f32_16x16x32_bf16 v[120:123], v[176:179], v[200:203], v[120:123]
	v_mfma_f32_16x16x32_bf16 v[104:107], v[176:179], v[208:211], v[104:107]
	v_mfma_f32_16x16x32_bf16 v[104:107], v[180:183], v[212:215], v[104:107]
	v_mfma_f32_16x16x32_bf16 v[108:111], v[166:169], v[212:215], v[108:111]
	v_mfma_f32_16x16x32_bf16 v[108:111], v[146:149], v[208:211], v[108:111]
	v_mfma_f32_16x16x32_bf16 v[92:95], v[146:149], v[216:219], v[92:95]
	v_mfma_f32_16x16x32_bf16 v[92:95], v[166:169], v[220:223], v[92:95]
	v_mfma_f32_16x16x32_bf16 v[88:91], v[180:183], v[220:223], v[88:91]
	v_mfma_f32_16x16x32_bf16 v[88:91], v[176:179], v[216:219], v[88:91]
	v_mfma_f32_16x16x32_bf16 v[72:75], v[176:179], v[224:227], v[72:75]
	v_mfma_f32_16x16x32_bf16 v[72:75], v[180:183], v[230:233], v[72:75]
	v_mfma_f32_16x16x32_bf16 v[76:79], v[166:169], v[230:233], v[76:79]
	v_mfma_f32_16x16x32_bf16 v[76:79], v[146:149], v[224:227], v[76:79]
	v_mfma_f32_16x16x32_bf16 v[68:71], v[184:187], v[224:227], v[68:71]
	v_mfma_f32_16x16x32_bf16 v[68:71], v[188:191], v[230:233], v[68:71]
	v_mfma_f32_16x16x32_bf16 v[64:67], v[196:199], v[230:233], v[64:67]
	v_mfma_f32_16x16x32_bf16 v[64:67], v[192:195], v[224:227], v[64:67]
	v_mfma_f32_16x16x32_bf16 v[80:83], v[192:195], v[216:219], v[80:83]
	v_mfma_f32_16x16x32_bf16 v[80:83], v[196:199], v[220:223], v[80:83]
	v_mfma_f32_16x16x32_bf16 v[84:87], v[188:191], v[220:223], v[84:87]
	v_mfma_f32_16x16x32_bf16 v[84:87], v[184:187], v[216:219], v[84:87]
	v_mfma_f32_16x16x32_bf16 v[100:103], v[184:187], v[208:211], v[100:103]
	v_mfma_f32_16x16x32_bf16 v[100:103], v[188:191], v[212:215], v[100:103]
	v_mfma_f32_16x16x32_bf16 v[96:99], v[196:199], v[212:215], v[96:99]
	v_mfma_f32_16x16x32_bf16 v[96:99], v[192:195], v[208:211], v[96:99]
	v_mfma_f32_16x16x32_bf16 v[112:115], v[192:195], v[200:203], v[112:115]
	v_mfma_f32_16x16x32_bf16 v[112:115], v[196:199], v[204:207], v[112:115]
	v_mfma_f32_16x16x32_bf16 v[116:119], v[188:191], v[204:207], v[116:119]
	v_mfma_f32_16x16x32_bf16 v[116:119], v[184:187], v[200:203], v[116:119]
	s_barrier
	s_setprio 0
	s_add_i32 s38, s68, s42
	v_lshl_add_u64 v[150:151], v[150:151], 0, s[14:15]
	s_mov_b32 m0, s38
	ds_read_b128 v[200:203], v174 offset:49152
	ds_read_b128 v[204:207], v174 offset:50176
	ds_read_b128 v[208:211], v174 offset:51200
	ds_read_b128 v[212:215], v174 offset:52224
	ds_read_b128 v[216:219], v174 offset:53248
	ds_read_b128 v[220:223], v174 offset:54272
	ds_read_b128 v[224:227], v174 offset:55296
	ds_read_b128 v[230:233], v174 offset:56320
	global_load_lds_dwordx4 v[150:151], off
	s_add_i32 m0, s38, 0x2000
	s_add_u32 s36, s36, 0x40080
	v_lshl_add_u64 v[150:151], v[154:155], 0, s[14:15]
	s_addc_u32 s37, s37, 0
	s_add_i32 s38, s69, s42
	global_load_lds_dwordx4 v[150:151], off
	v_lshl_add_u64 v[150:151], s[36:37], 0, v[132:133]
	s_mov_b32 m0, s38
	s_nop 0
	global_load_lds_dwordx4 v[150:151], off
	v_lshl_add_u64 v[150:151], s[36:37], 0, v[128:129]
	s_add_i32 m0, s38, 0x2000
	s_nop 0
	global_load_lds_dwordx4 v[150:151], off
	v_lshl_add_u64 v[150:151], v[158:159], 0, s[14:15]
	s_mov_b32 m0, s49
	s_nop 0
	global_load_lds_dwordx4 v[150:151], off
	v_lshl_add_u64 v[150:151], v[162:163], 0, s[14:15]
	s_mov_b32 m0, s50
	s_nop 0
	global_load_lds_dwordx4 v[150:151], off
	s_waitcnt vmcnt(8)
	s_waitcnt lgkmcnt(0)
	s_setprio 1
	s_barrier
	v_mfma_f32_16x16x32_bf16 v[60:63], v[146:149], v[200:203], v[60:63]
	v_mfma_f32_16x16x32_bf16 v[60:63], v[166:169], v[204:207], v[60:63]
	v_mfma_f32_16x16x32_bf16 v[56:59], v[180:183], v[204:207], v[56:59]
	v_mfma_f32_16x16x32_bf16 v[56:59], v[176:179], v[200:203], v[56:59]
	v_mfma_f32_16x16x32_bf16 v[40:43], v[176:179], v[208:211], v[40:43]
	v_mfma_f32_16x16x32_bf16 v[40:43], v[180:183], v[212:215], v[40:43]
	v_mfma_f32_16x16x32_bf16 v[44:47], v[166:169], v[212:215], v[44:47]
	v_mfma_f32_16x16x32_bf16 v[44:47], v[146:149], v[208:211], v[44:47]
	v_mfma_f32_16x16x32_bf16 v[28:31], v[146:149], v[216:219], v[28:31]
	v_mfma_f32_16x16x32_bf16 v[28:31], v[166:169], v[220:223], v[28:31]
	v_mfma_f32_16x16x32_bf16 v[24:27], v[180:183], v[220:223], v[24:27]
	v_mfma_f32_16x16x32_bf16 v[24:27], v[176:179], v[216:219], v[24:27]
	v_mfma_f32_16x16x32_bf16 v[8:11], v[176:179], v[224:227], v[8:11]
	v_mfma_f32_16x16x32_bf16 v[8:11], v[180:183], v[230:233], v[8:11]
	v_mfma_f32_16x16x32_bf16 v[12:15], v[166:169], v[230:233], v[12:15]
	v_mfma_f32_16x16x32_bf16 v[12:15], v[146:149], v[224:227], v[12:15]
	v_mfma_f32_16x16x32_bf16 v[4:7], v[184:187], v[224:227], v[4:7]
	v_mfma_f32_16x16x32_bf16 v[4:7], v[188:191], v[230:233], v[4:7]
	v_mfma_f32_16x16x32_bf16 v[0:3], v[196:199], v[230:233], v[0:3]
	v_mfma_f32_16x16x32_bf16 v[0:3], v[192:195], v[224:227], v[0:3]
	v_mfma_f32_16x16x32_bf16 v[16:19], v[192:195], v[216:219], v[16:19]
	v_mfma_f32_16x16x32_bf16 v[16:19], v[196:199], v[220:223], v[16:19]
	v_mfma_f32_16x16x32_bf16 v[20:23], v[188:191], v[220:223], v[20:23]
	v_mfma_f32_16x16x32_bf16 v[20:23], v[184:187], v[216:219], v[20:23]
	v_mfma_f32_16x16x32_bf16 v[36:39], v[184:187], v[208:211], v[36:39]
	v_mfma_f32_16x16x32_bf16 v[36:39], v[188:191], v[212:215], v[36:39]
	v_mfma_f32_16x16x32_bf16 v[32:35], v[196:199], v[212:215], v[32:35]
	v_mfma_f32_16x16x32_bf16 v[32:35], v[192:195], v[208:211], v[32:35]
	v_mfma_f32_16x16x32_bf16 v[48:51], v[192:195], v[200:203], v[48:51]
	v_mfma_f32_16x16x32_bf16 v[48:51], v[196:199], v[204:207], v[48:51]
	v_mfma_f32_16x16x32_bf16 v[52:55], v[188:191], v[204:207], v[52:55]
	v_mfma_f32_16x16x32_bf16 v[52:55], v[184:187], v[200:203], v[52:55]
	s_barrier
	s_setprio 0
	s_add_i32 s67, s67, 2
	s_add_u32 s4, s4, 0x100
	s_addc_u32 s5, s5, 0
	s_add_u32 s59, s59, 0x100
	s_addc_u32 s66, s66, 0
	s_cmp_gt_u32 s67, 13
.LBB0_759:
	ds_read_b128 v[146:149], v172
	ds_read_b128 v[166:169], v172 offset:1024
	ds_read_b128 v[176:179], v172 offset:2048
	ds_read_b128 v[180:183], v172 offset:3072
	ds_read_b128 v[184:187], v173
	ds_read_b128 v[188:191], v173 offset:1024
	ds_read_b128 v[192:195], v173 offset:2048
	ds_read_b128 v[196:199], v173 offset:3072
	s_add_u32 s36, s4, 0xfffc0080
	s_addc_u32 s37, s5, -1
	s_cmp_eq_u32 s67, 12
	s_cselect_b32 s39, s19, s37
	s_cselect_b32 s38, s57, s36
	s_cselect_b32 s37, s11, s66
	s_cselect_b32 s36, s58, s59
	v_lshl_add_u64 v[150:151], s[4:5], 0, v[138:139]
	s_add_i32 m0, s27, 0xc000
	ds_read_b128 v[200:203], v174
	ds_read_b128 v[204:207], v174 offset:1024
	ds_read_b128 v[208:211], v174 offset:2048
	ds_read_b128 v[212:215], v174 offset:3072
	ds_read_b128 v[216:219], v174 offset:4096
	ds_read_b128 v[220:223], v174 offset:5120
	ds_read_b128 v[224:227], v174 offset:6144
	ds_read_b128 v[230:233], v174 offset:7168
	global_load_lds_dwordx4 v[150:151], off
	v_lshl_add_u64 v[150:151], s[4:5], 0, v[140:141]
	s_add_i32 m0, s27, 0xe000
	s_nop 0
	global_load_lds_dwordx4 v[150:151], off
	s_waitcnt vmcnt(8)
	s_waitcnt lgkmcnt(0)
	s_setprio 1
	s_barrier
	v_mfma_f32_16x16x32_bf16 v[124:127], v[146:149], v[200:203], v[124:127]
	v_mfma_f32_16x16x32_bf16 v[124:127], v[166:169], v[204:207], v[124:127]
	v_mfma_f32_16x16x32_bf16 v[120:123], v[180:183], v[204:207], v[120:123]
	v_mfma_f32_16x16x32_bf16 v[120:123], v[176:179], v[200:203], v[120:123]
	v_mfma_f32_16x16x32_bf16 v[104:107], v[176:179], v[208:211], v[104:107]
	v_mfma_f32_16x16x32_bf16 v[104:107], v[180:183], v[212:215], v[104:107]
	v_mfma_f32_16x16x32_bf16 v[108:111], v[166:169], v[212:215], v[108:111]
	v_mfma_f32_16x16x32_bf16 v[108:111], v[146:149], v[208:211], v[108:111]
	v_mfma_f32_16x16x32_bf16 v[92:95], v[146:149], v[216:219], v[92:95]
	v_mfma_f32_16x16x32_bf16 v[92:95], v[166:169], v[220:223], v[92:95]
	v_mfma_f32_16x16x32_bf16 v[88:91], v[180:183], v[220:223], v[88:91]
	v_mfma_f32_16x16x32_bf16 v[88:91], v[176:179], v[216:219], v[88:91]
	v_mfma_f32_16x16x32_bf16 v[72:75], v[176:179], v[224:227], v[72:75]
	v_mfma_f32_16x16x32_bf16 v[72:75], v[180:183], v[230:233], v[72:75]
	v_mfma_f32_16x16x32_bf16 v[76:79], v[166:169], v[230:233], v[76:79]
	v_mfma_f32_16x16x32_bf16 v[76:79], v[146:149], v[224:227], v[76:79]
	v_mfma_f32_16x16x32_bf16 v[68:71], v[184:187], v[224:227], v[68:71]
	v_mfma_f32_16x16x32_bf16 v[68:71], v[188:191], v[230:233], v[68:71]
	v_mfma_f32_16x16x32_bf16 v[64:67], v[196:199], v[230:233], v[64:67]
	v_mfma_f32_16x16x32_bf16 v[64:67], v[192:195], v[224:227], v[64:67]
	v_mfma_f32_16x16x32_bf16 v[80:83], v[192:195], v[216:219], v[80:83]
	v_mfma_f32_16x16x32_bf16 v[80:83], v[196:199], v[220:223], v[80:83]
	v_mfma_f32_16x16x32_bf16 v[84:87], v[188:191], v[220:223], v[84:87]
	v_mfma_f32_16x16x32_bf16 v[84:87], v[184:187], v[216:219], v[84:87]
	v_mfma_f32_16x16x32_bf16 v[100:103], v[184:187], v[208:211], v[100:103]
	v_mfma_f32_16x16x32_bf16 v[100:103], v[188:191], v[212:215], v[100:103]
	v_mfma_f32_16x16x32_bf16 v[96:99], v[196:199], v[212:215], v[96:99]
	v_mfma_f32_16x16x32_bf16 v[96:99], v[192:195], v[208:211], v[96:99]
	v_mfma_f32_16x16x32_bf16 v[112:115], v[192:195], v[200:203], v[112:115]
	v_mfma_f32_16x16x32_bf16 v[112:115], v[196:199], v[204:207], v[112:115]
	v_mfma_f32_16x16x32_bf16 v[116:119], v[188:191], v[204:207], v[116:119]
	v_mfma_f32_16x16x32_bf16 v[116:119], v[184:187], v[200:203], v[116:119]
	s_barrier
	s_setprio 0
	s_add_i32 s68, s53, s42
	v_lshl_add_u64 v[150:151], s[36:37], 0, v[132:133]
	s_mov_b32 m0, s68
	ds_read_b128 v[200:203], v174 offset:16384
	ds_read_b128 v[204:207], v174 offset:17408
	ds_read_b128 v[208:211], v174 offset:18432
	ds_read_b128 v[212:215], v174 offset:19456
	ds_read_b128 v[216:219], v174 offset:20480
	ds_read_b128 v[220:223], v174 offset:21504
	ds_read_b128 v[224:227], v174 offset:22528
	ds_read_b128 v[230:233], v174 offset:23552
	global_load_lds_dwordx4 v[150:151], off
	s_add_i32 m0, s68, 0x2000
	s_add_u32 s68, s36, 0x40000
	v_lshl_add_u64 v[154:155], s[36:37], 0, v[128:129]
	s_addc_u32 s69, s37, 0
	s_add_i32 s70, s54, s42
	global_load_lds_dwordx4 v[154:155], off
	v_lshl_add_u64 v[158:159], s[68:69], 0, v[132:133]
	s_mov_b32 m0, s70
	v_lshl_add_u64 v[162:163], s[38:39], 0, v[130:131]
	global_load_lds_dwordx4 v[158:159], off
	v_lshl_add_u64 v[158:159], s[68:69], 0, v[128:129]
	s_add_i32 m0, s70, 0x2000
	s_nop 0
	global_load_lds_dwordx4 v[158:159], off
	v_lshl_add_u64 v[158:159], s[38:39], 0, v[134:135]
	s_mov_b32 m0, s27
	s_nop 0
	global_load_lds_dwordx4 v[158:159], off
	s_mov_b32 m0, s45
	s_nop 0
	global_load_lds_dwordx4 v[162:163], off
	s_waitcnt vmcnt(8)
	s_waitcnt lgkmcnt(0)
	s_setprio 1
	s_barrier
	v_mfma_f32_16x16x32_bf16 v[60:63], v[146:149], v[200:203], v[60:63]
	v_mfma_f32_16x16x32_bf16 v[60:63], v[166:169], v[204:207], v[60:63]
	v_mfma_f32_16x16x32_bf16 v[56:59], v[180:183], v[204:207], v[56:59]
	v_mfma_f32_16x16x32_bf16 v[56:59], v[176:179], v[200:203], v[56:59]
	v_mfma_f32_16x16x32_bf16 v[40:43], v[176:179], v[208:211], v[40:43]
	v_mfma_f32_16x16x32_bf16 v[40:43], v[180:183], v[212:215], v[40:43]
	v_mfma_f32_16x16x32_bf16 v[44:47], v[166:169], v[212:215], v[44:47]
	v_mfma_f32_16x16x32_bf16 v[44:47], v[146:149], v[208:211], v[44:47]
	v_mfma_f32_16x16x32_bf16 v[28:31], v[146:149], v[216:219], v[28:31]
	v_mfma_f32_16x16x32_bf16 v[28:31], v[166:169], v[220:223], v[28:31]
	v_mfma_f32_16x16x32_bf16 v[24:27], v[180:183], v[220:223], v[24:27]
	v_mfma_f32_16x16x32_bf16 v[24:27], v[176:179], v[216:219], v[24:27]
	v_mfma_f32_16x16x32_bf16 v[8:11], v[176:179], v[224:227], v[8:11]
	v_mfma_f32_16x16x32_bf16 v[8:11], v[180:183], v[230:233], v[8:11]
	v_mfma_f32_16x16x32_bf16 v[12:15], v[166:169], v[230:233], v[12:15]
	v_mfma_f32_16x16x32_bf16 v[12:15], v[146:149], v[224:227], v[12:15]
	v_mfma_f32_16x16x32_bf16 v[4:7], v[184:187], v[224:227], v[4:7]
	v_mfma_f32_16x16x32_bf16 v[4:7], v[188:191], v[230:233], v[4:7]
	v_mfma_f32_16x16x32_bf16 v[0:3], v[196:199], v[230:233], v[0:3]
	v_mfma_f32_16x16x32_bf16 v[0:3], v[192:195], v[224:227], v[0:3]
	v_mfma_f32_16x16x32_bf16 v[16:19], v[192:195], v[216:219], v[16:19]
	v_mfma_f32_16x16x32_bf16 v[16:19], v[196:199], v[220:223], v[16:19]
	v_mfma_f32_16x16x32_bf16 v[20:23], v[188:191], v[220:223], v[20:23]
	v_mfma_f32_16x16x32_bf16 v[20:23], v[184:187], v[216:219], v[20:23]
	v_mfma_f32_16x16x32_bf16 v[36:39], v[184:187], v[208:211], v[36:39]
	v_mfma_f32_16x16x32_bf16 v[36:39], v[188:191], v[212:215], v[36:39]
	v_mfma_f32_16x16x32_bf16 v[32:35], v[196:199], v[212:215], v[32:35]
	v_mfma_f32_16x16x32_bf16 v[32:35], v[192:195], v[208:211], v[32:35]
	v_mfma_f32_16x16x32_bf16 v[48:51], v[192:195], v[200:203], v[48:51]
	v_mfma_f32_16x16x32_bf16 v[48:51], v[196:199], v[204:207], v[48:51]
	v_mfma_f32_16x16x32_bf16 v[52:55], v[188:191], v[204:207], v[52:55]
	v_mfma_f32_16x16x32_bf16 v[52:55], v[184:187], v[200:203], v[52:55]
	s_barrier
	s_setprio 0
	s_add_i32 s68, 0, 0x18000
	v_add_u32_e32 v152, s68, v157
	s_add_i32 s69, 0, 0x1c000
	ds_read_b128 v[146:149], v152
	ds_read_b128 v[166:169], v152 offset:1024
	ds_read_b128 v[176:179], v152 offset:2048
	ds_read_b128 v[180:183], v152 offset:3072
	v_add_u32_e32 v152, s69, v157
	ds_read_b128 v[184:187], v152
	ds_read_b128 v[188:191], v152 offset:1024
	ds_read_b128 v[192:195], v152 offset:2048
	ds_read_b128 v[196:199], v152 offset:3072
	s_add_u32 s38, s38, 0x40000
	s_addc_u32 s39, s39, 0
	s_mov_b32 m0, s46
	v_lshl_add_u64 v[234:235], s[38:39], 0, v[134:135]
	ds_read_b128 v[200:203], v174 offset:32768
	ds_read_b128 v[204:207], v174 offset:33792
	ds_read_b128 v[208:211], v174 offset:34816
	ds_read_b128 v[212:215], v174 offset:35840
	ds_read_b128 v[216:219], v174 offset:36864
	ds_read_b128 v[220:223], v174 offset:37888
	ds_read_b128 v[224:227], v174 offset:38912
	ds_read_b128 v[230:233], v174 offset:39936
	global_load_lds_dwordx4 v[234:235], off
	v_lshl_add_u64 v[234:235], s[38:39], 0, v[130:131]
	s_mov_b32 m0, s47
	s_nop 0
	global_load_lds_dwordx4 v[234:235], off
	s_waitcnt vmcnt(8)
	s_waitcnt lgkmcnt(0)
	s_setprio 1
	s_barrier
	v_mfma_f32_16x16x32_bf16 v[124:127], v[146:149], v[200:203], v[124:127]
	v_mfma_f32_16x16x32_bf16 v[124:127], v[166:169], v[204:207], v[124:127]
	v_mfma_f32_16x16x32_bf16 v[120:123], v[180:183], v[204:207], v[120:123]
	v_mfma_f32_16x16x32_bf16 v[120:123], v[176:179], v[200:203], v[120:123]
	v_mfma_f32_16x16x32_bf16 v[104:107], v[176:179], v[208:211], v[104:107]
	v_mfma_f32_16x16x32_bf16 v[104:107], v[180:183], v[212:215], v[104:107]
	v_mfma_f32_16x16x32_bf16 v[108:111], v[166:169], v[212:215], v[108:111]
	v_mfma_f32_16x16x32_bf16 v[108:111], v[146:149], v[208:211], v[108:111]
	v_mfma_f32_16x16x32_bf16 v[92:95], v[146:149], v[216:219], v[92:95]
	v_mfma_f32_16x16x32_bf16 v[92:95], v[166:169], v[220:223], v[92:95]
	v_mfma_f32_16x16x32_bf16 v[88:91], v[180:183], v[220:223], v[88:91]
	v_mfma_f32_16x16x32_bf16 v[88:91], v[176:179], v[216:219], v[88:91]
	v_mfma_f32_16x16x32_bf16 v[72:75], v[176:179], v[224:227], v[72:75]
	v_mfma_f32_16x16x32_bf16 v[72:75], v[180:183], v[230:233], v[72:75]
	v_mfma_f32_16x16x32_bf16 v[76:79], v[166:169], v[230:233], v[76:79]
	v_mfma_f32_16x16x32_bf16 v[76:79], v[146:149], v[224:227], v[76:79]
	v_mfma_f32_16x16x32_bf16 v[68:71], v[184:187], v[224:227], v[68:71]
	v_mfma_f32_16x16x32_bf16 v[68:71], v[188:191], v[230:233], v[68:71]
	v_mfma_f32_16x16x32_bf16 v[64:67], v[196:199], v[230:233], v[64:67]
	v_mfma_f32_16x16x32_bf16 v[64:67], v[192:195], v[224:227], v[64:67]
	v_mfma_f32_16x16x32_bf16 v[80:83], v[192:195], v[216:219], v[80:83]
	v_mfma_f32_16x16x32_bf16 v[80:83], v[196:199], v[220:223], v[80:83]
	v_mfma_f32_16x16x32_bf16 v[84:87], v[188:191], v[220:223], v[84:87]
	v_mfma_f32_16x16x32_bf16 v[84:87], v[184:187], v[216:219], v[84:87]
	v_mfma_f32_16x16x32_bf16 v[100:103], v[184:187], v[208:211], v[100:103]
	v_mfma_f32_16x16x32_bf16 v[100:103], v[188:191], v[212:215], v[100:103]
	v_mfma_f32_16x16x32_bf16 v[96:99], v[196:199], v[212:215], v[96:99]
	v_mfma_f32_16x16x32_bf16 v[96:99], v[192:195], v[208:211], v[96:99]
	v_mfma_f32_16x16x32_bf16 v[112:115], v[192:195], v[200:203], v[112:115]
	v_mfma_f32_16x16x32_bf16 v[112:115], v[196:199], v[204:207], v[112:115]
	v_mfma_f32_16x16x32_bf16 v[116:119], v[188:191], v[204:207], v[116:119]
	v_mfma_f32_16x16x32_bf16 v[116:119], v[184:187], v[200:203], v[116:119]
	s_barrier
	s_setprio 0
	s_add_i32 s38, s68, s42
	v_lshl_add_u64 v[150:151], v[150:151], 0, s[14:15]
	s_mov_b32 m0, s38
	ds_read_b128 v[200:203], v174 offset:49152
	ds_read_b128 v[204:207], v174 offset:50176
	ds_read_b128 v[208:211], v174 offset:51200
	ds_read_b128 v[212:215], v174 offset:52224
	ds_read_b128 v[216:219], v174 offset:53248
	ds_read_b128 v[220:223], v174 offset:54272
	ds_read_b128 v[224:227], v174 offset:55296
	ds_read_b128 v[230:233], v174 offset:56320
	global_load_lds_dwordx4 v[150:151], off
	s_add_i32 m0, s38, 0x2000
	s_add_u32 s36, s36, 0x40080
	v_lshl_add_u64 v[150:151], v[154:155], 0, s[14:15]
	s_addc_u32 s37, s37, 0
	s_add_i32 s38, s69, s42
	global_load_lds_dwordx4 v[150:151], off
	v_lshl_add_u64 v[150:151], s[36:37], 0, v[132:133]
	s_mov_b32 m0, s38
	s_nop 0
	global_load_lds_dwordx4 v[150:151], off
	v_lshl_add_u64 v[150:151], s[36:37], 0, v[128:129]
	s_add_i32 m0, s38, 0x2000
	s_nop 0
	global_load_lds_dwordx4 v[150:151], off
	v_lshl_add_u64 v[150:151], v[158:159], 0, s[14:15]
	s_mov_b32 m0, s49
	s_nop 0
	global_load_lds_dwordx4 v[150:151], off
	v_lshl_add_u64 v[150:151], v[162:163], 0, s[14:15]
	s_mov_b32 m0, s50
	s_nop 0
	global_load_lds_dwordx4 v[150:151], off
	s_waitcnt vmcnt(8)
	s_waitcnt lgkmcnt(0)
	s_setprio 1
	s_barrier
	v_mfma_f32_16x16x32_bf16 v[60:63], v[146:149], v[200:203], v[60:63]
	v_mfma_f32_16x16x32_bf16 v[60:63], v[166:169], v[204:207], v[60:63]
	v_mfma_f32_16x16x32_bf16 v[56:59], v[180:183], v[204:207], v[56:59]
	v_mfma_f32_16x16x32_bf16 v[56:59], v[176:179], v[200:203], v[56:59]
	v_mfma_f32_16x16x32_bf16 v[40:43], v[176:179], v[208:211], v[40:43]
	v_mfma_f32_16x16x32_bf16 v[40:43], v[180:183], v[212:215], v[40:43]
	v_mfma_f32_16x16x32_bf16 v[44:47], v[166:169], v[212:215], v[44:47]
	v_mfma_f32_16x16x32_bf16 v[44:47], v[146:149], v[208:211], v[44:47]
	v_mfma_f32_16x16x32_bf16 v[28:31], v[146:149], v[216:219], v[28:31]
	v_mfma_f32_16x16x32_bf16 v[28:31], v[166:169], v[220:223], v[28:31]
	v_mfma_f32_16x16x32_bf16 v[24:27], v[180:183], v[220:223], v[24:27]
	v_mfma_f32_16x16x32_bf16 v[24:27], v[176:179], v[216:219], v[24:27]
	v_mfma_f32_16x16x32_bf16 v[8:11], v[176:179], v[224:227], v[8:11]
	v_mfma_f32_16x16x32_bf16 v[8:11], v[180:183], v[230:233], v[8:11]
	v_mfma_f32_16x16x32_bf16 v[12:15], v[166:169], v[230:233], v[12:15]
	v_mfma_f32_16x16x32_bf16 v[12:15], v[146:149], v[224:227], v[12:15]
	v_mfma_f32_16x16x32_bf16 v[4:7], v[184:187], v[224:227], v[4:7]
	v_mfma_f32_16x16x32_bf16 v[4:7], v[188:191], v[230:233], v[4:7]
	v_mfma_f32_16x16x32_bf16 v[0:3], v[196:199], v[230:233], v[0:3]
	v_mfma_f32_16x16x32_bf16 v[0:3], v[192:195], v[224:227], v[0:3]
	v_mfma_f32_16x16x32_bf16 v[16:19], v[192:195], v[216:219], v[16:19]
	v_mfma_f32_16x16x32_bf16 v[16:19], v[196:199], v[220:223], v[16:19]
	v_mfma_f32_16x16x32_bf16 v[20:23], v[188:191], v[220:223], v[20:23]
	v_mfma_f32_16x16x32_bf16 v[20:23], v[184:187], v[216:219], v[20:23]
	v_mfma_f32_16x16x32_bf16 v[36:39], v[184:187], v[208:211], v[36:39]
	v_mfma_f32_16x16x32_bf16 v[36:39], v[188:191], v[212:215], v[36:39]
	v_mfma_f32_16x16x32_bf16 v[32:35], v[196:199], v[212:215], v[32:35]
	v_mfma_f32_16x16x32_bf16 v[32:35], v[192:195], v[208:211], v[32:35]
	v_mfma_f32_16x16x32_bf16 v[48:51], v[192:195], v[200:203], v[48:51]
	v_mfma_f32_16x16x32_bf16 v[48:51], v[196:199], v[204:207], v[48:51]
	v_mfma_f32_16x16x32_bf16 v[52:55], v[188:191], v[204:207], v[52:55]
	v_mfma_f32_16x16x32_bf16 v[52:55], v[184:187], v[200:203], v[52:55]
	s_barrier
	s_setprio 0
	s_add_i32 s67, s67, 2
	s_add_u32 s4, s4, 0x100
	s_addc_u32 s5, s5, 0
	s_add_u32 s59, s59, 0x100
	s_addc_u32 s66, s66, 0
	s_cmp_gt_u32 s67, 13
	s_cbranch_scc0 .LBB0_759
	s_and_b64 vcc, exec, s[16:17]
	s_cbranch_vccz .LBB0_762
	s_barrier

.LBB0_835:
	s_add_u32 s80, s22, 0x100
	s_addc_u32 s81, s23, 0
	s_mov_b32 s82, -2
	ds_read_b128 v[112:115], v203
	ds_read_b128 v[116:119], v203 offset:1024
	ds_read_b128 v[136:139], v203 offset:2048
	ds_read_b128 v[140:143], v203 offset:3072
	ds_read_b128 v[144:147], v204
	ds_read_b128 v[148:151], v204 offset:1024
	ds_read_b128 v[152:155], v204 offset:2048
	ds_read_b128 v[156:159], v204 offset:3072
	s_add_u32 s22, s20, 0x100
	s_addc_u32 s23, s21, 0
	s_cmp_eq_u32 s82, 40
	s_cselect_b32 s37, s7, s23
	s_cselect_b32 s36, s6, s22
	s_cselect_b32 s27, s19, s81
	s_cselect_b32 s26, s18, s80
	v_lshl_add_u64 v[200:201], s[20:21], 0, v[186:187]
	s_add_i32 m0, s43, 0xc000
	ds_read_b128 v[160:163], v205
	ds_read_b128 v[164:167], v205 offset:1024
	ds_read_b128 v[168:171], v205 offset:2048
	ds_read_b128 v[172:175], v205 offset:3072
	ds_read_b128 v[206:209], v205 offset:4096
	ds_read_b128 v[210:213], v205 offset:5120
	ds_read_b128 v[214:217], v205 offset:6144
	ds_read_b128 v[218:221], v205 offset:7168
	global_load_lds_dwordx4 v[200:201], off
	v_lshl_add_u64 v[200:201], s[20:21], 0, v[188:189]
	s_add_i32 m0, s43, 0xe000
	s_nop 0
	global_load_lds_dwordx4 v[200:201], off
	s_waitcnt vmcnt(8)
	s_waitcnt lgkmcnt(0)
	s_setprio 1
	s_barrier
	v_mfma_f32_16x16x32_bf16 v[132:135], v[112:115], v[160:163], 0
	v_mfma_f32_16x16x32_bf16 v[132:135], v[116:119], v[164:167], v[132:135]
	v_mfma_f32_16x16x32_bf16 v[128:131], v[140:143], v[164:167], 0
	v_mfma_f32_16x16x32_bf16 v[128:131], v[136:139], v[160:163], v[128:131]
	v_mfma_f32_16x16x32_bf16 v[104:107], v[136:139], v[168:171], 0
	v_mfma_f32_16x16x32_bf16 v[104:107], v[140:143], v[172:175], v[104:107]
	v_mfma_f32_16x16x32_bf16 v[108:111], v[116:119], v[172:175], 0
	v_mfma_f32_16x16x32_bf16 v[108:111], v[112:115], v[168:171], v[108:111]
	v_mfma_f32_16x16x32_bf16 v[92:95], v[112:115], v[206:209], 0
	v_mfma_f32_16x16x32_bf16 v[92:95], v[116:119], v[210:213], v[92:95]
	v_mfma_f32_16x16x32_bf16 v[88:91], v[140:143], v[210:213], 0
	v_mfma_f32_16x16x32_bf16 v[88:91], v[136:139], v[206:209], v[88:91]
	v_mfma_f32_16x16x32_bf16 v[72:75], v[136:139], v[214:217], 0
	v_mfma_f32_16x16x32_bf16 v[72:75], v[140:143], v[218:221], v[72:75]
	v_mfma_f32_16x16x32_bf16 v[76:79], v[116:119], v[218:221], 0
	v_mfma_f32_16x16x32_bf16 v[76:79], v[112:115], v[214:217], v[76:79]
	v_mfma_f32_16x16x32_bf16 v[68:71], v[144:147], v[214:217], 0
	v_mfma_f32_16x16x32_bf16 v[68:71], v[148:151], v[218:221], v[68:71]
	v_mfma_f32_16x16x32_bf16 v[64:67], v[156:159], v[218:221], 0
	v_mfma_f32_16x16x32_bf16 v[64:67], v[152:155], v[214:217], v[64:67]
	v_mfma_f32_16x16x32_bf16 v[80:83], v[152:155], v[206:209], 0
	v_mfma_f32_16x16x32_bf16 v[80:83], v[156:159], v[210:213], v[80:83]
	v_mfma_f32_16x16x32_bf16 v[84:87], v[148:151], v[210:213], 0
	v_mfma_f32_16x16x32_bf16 v[84:87], v[144:147], v[206:209], v[84:87]
	v_mfma_f32_16x16x32_bf16 v[100:103], v[144:147], v[168:171], 0
	v_mfma_f32_16x16x32_bf16 v[100:103], v[148:151], v[172:175], v[100:103]
	v_mfma_f32_16x16x32_bf16 v[96:99], v[156:159], v[172:175], 0
	v_mfma_f32_16x16x32_bf16 v[96:99], v[152:155], v[168:171], v[96:99]
	v_mfma_f32_16x16x32_bf16 v[120:123], v[152:155], v[160:163], 0
	v_mfma_f32_16x16x32_bf16 v[120:123], v[156:159], v[164:167], v[120:123]
	v_mfma_f32_16x16x32_bf16 v[124:127], v[148:151], v[164:167], 0
	v_mfma_f32_16x16x32_bf16 v[124:127], v[144:147], v[160:163], v[124:127]
	s_barrier
	s_setprio 0
	s_add_i32 s20, s59, s40
	v_lshl_add_u64 v[200:201], s[26:27], 0, v[180:181]
	s_mov_b32 m0, s20
	ds_read_b128 v[160:163], v205 offset:16384
	ds_read_b128 v[164:167], v205 offset:17408
	ds_read_b128 v[168:171], v205 offset:18432
	ds_read_b128 v[172:175], v205 offset:19456
	ds_read_b128 v[206:209], v205 offset:20480
	ds_read_b128 v[210:213], v205 offset:21504
	ds_read_b128 v[214:217], v205 offset:22528
	ds_read_b128 v[218:221], v205 offset:23552
	global_load_lds_dwordx4 v[200:201], off
	s_add_i32 m0, s20, 0x2000
	s_add_u32 s20, s26, 0xb0000
	v_lshl_add_u64 v[222:223], s[26:27], 0, v[176:177]
	s_addc_u32 s21, s27, 0
	s_add_i32 s83, s66, s40
	global_load_lds_dwordx4 v[222:223], off
	v_lshl_add_u64 v[224:225], s[20:21], 0, v[180:181]
	s_mov_b32 m0, s83
	v_lshl_add_u64 v[226:227], s[36:37], 0, v[178:179]
	global_load_lds_dwordx4 v[224:225], off
	v_lshl_add_u64 v[224:225], s[20:21], 0, v[176:177]
	s_add_i32 m0, s83, 0x2000
	s_nop 0
	global_load_lds_dwordx4 v[224:225], off
	v_lshl_add_u64 v[224:225], s[36:37], 0, v[182:183]
	s_mov_b32 m0, s43
	s_nop 0
	global_load_lds_dwordx4 v[224:225], off
	s_mov_b32 m0, s44
	s_nop 0
	global_load_lds_dwordx4 v[226:227], off
	s_waitcnt vmcnt(8)
	s_waitcnt lgkmcnt(0)
	s_setprio 1
	s_barrier
	v_mfma_f32_16x16x32_bf16 v[60:63], v[112:115], v[160:163], 0
	v_mfma_f32_16x16x32_bf16 v[60:63], v[116:119], v[164:167], v[60:63]
	v_mfma_f32_16x16x32_bf16 v[56:59], v[140:143], v[164:167], 0
	v_mfma_f32_16x16x32_bf16 v[56:59], v[136:139], v[160:163], v[56:59]
	v_mfma_f32_16x16x32_bf16 v[40:43], v[136:139], v[168:171], 0
	v_mfma_f32_16x16x32_bf16 v[40:43], v[140:143], v[172:175], v[40:43]
	v_mfma_f32_16x16x32_bf16 v[44:47], v[116:119], v[172:175], 0
	v_mfma_f32_16x16x32_bf16 v[44:47], v[112:115], v[168:171], v[44:47]
	v_mfma_f32_16x16x32_bf16 v[28:31], v[112:115], v[206:209], 0
	v_mfma_f32_16x16x32_bf16 v[28:31], v[116:119], v[210:213], v[28:31]
	v_mfma_f32_16x16x32_bf16 v[24:27], v[140:143], v[210:213], 0
	v_mfma_f32_16x16x32_bf16 v[24:27], v[136:139], v[206:209], v[24:27]
	v_mfma_f32_16x16x32_bf16 v[8:11], v[136:139], v[214:217], 0
	v_mfma_f32_16x16x32_bf16 v[8:11], v[140:143], v[218:221], v[8:11]
	v_mfma_f32_16x16x32_bf16 v[12:15], v[116:119], v[218:221], 0
	v_mfma_f32_16x16x32_bf16 v[12:15], v[112:115], v[214:217], v[12:15]
	v_mfma_f32_16x16x32_bf16 v[4:7], v[144:147], v[214:217], 0
	v_mfma_f32_16x16x32_bf16 v[4:7], v[148:151], v[218:221], v[4:7]
	v_mfma_f32_16x16x32_bf16 v[0:3], v[156:159], v[218:221], 0
	v_mfma_f32_16x16x32_bf16 v[0:3], v[152:155], v[214:217], v[0:3]
	v_mfma_f32_16x16x32_bf16 v[16:19], v[152:155], v[206:209], 0
	v_mfma_f32_16x16x32_bf16 v[16:19], v[156:159], v[210:213], v[16:19]
	v_mfma_f32_16x16x32_bf16 v[20:23], v[148:151], v[210:213], 0
	v_mfma_f32_16x16x32_bf16 v[20:23], v[144:147], v[206:209], v[20:23]
	v_mfma_f32_16x16x32_bf16 v[36:39], v[144:147], v[168:171], 0
	v_mfma_f32_16x16x32_bf16 v[36:39], v[148:151], v[172:175], v[36:39]
	v_mfma_f32_16x16x32_bf16 v[32:35], v[156:159], v[172:175], 0
	v_mfma_f32_16x16x32_bf16 v[32:35], v[152:155], v[168:171], v[32:35]
	v_mfma_f32_16x16x32_bf16 v[48:51], v[152:155], v[160:163], 0
	v_mfma_f32_16x16x32_bf16 v[48:51], v[156:159], v[164:167], v[48:51]
	v_mfma_f32_16x16x32_bf16 v[52:55], v[148:151], v[164:167], 0
	v_mfma_f32_16x16x32_bf16 v[52:55], v[144:147], v[160:163], v[52:55]
	s_barrier
	s_setprio 0
	s_add_i32 s83, 0, 0x18000
	s_add_i32 s85, 0, 0x1c000
	v_add_u32_e32 v140, s83, v202
	v_add_u32_e32 v156, s85, v202
	ds_read_b128 v[112:115], v140
	ds_read_b128 v[116:119], v140 offset:1024
	ds_read_b128 v[136:139], v140 offset:2048
	ds_read_b128 v[140:143], v140 offset:3072
	ds_read_b128 v[144:147], v156
	ds_read_b128 v[148:151], v156 offset:1024
	ds_read_b128 v[152:155], v156 offset:2048
	ds_read_b128 v[156:159], v156 offset:3072
	s_add_u32 s20, s36, 0xb0000
	s_addc_u32 s21, s37, 0
	s_mov_b32 m0, s45
	v_lshl_add_u64 v[230:231], s[20:21], 0, v[182:183]
	ds_read_b128 v[160:163], v205 offset:32768
	ds_read_b128 v[164:167], v205 offset:33792
	ds_read_b128 v[168:171], v205 offset:34816
	ds_read_b128 v[172:175], v205 offset:35840
	ds_read_b128 v[206:209], v205 offset:36864
	ds_read_b128 v[210:213], v205 offset:37888
	ds_read_b128 v[214:217], v205 offset:38912
	ds_read_b128 v[218:221], v205 offset:39936
	global_load_lds_dwordx4 v[230:231], off
	v_lshl_add_u64 v[230:231], s[20:21], 0, v[178:179]
	s_mov_b32 m0, s46
	s_nop 0
	global_load_lds_dwordx4 v[230:231], off
	s_waitcnt vmcnt(8)
	s_waitcnt lgkmcnt(0)
	s_setprio 1
	s_barrier
	v_mfma_f32_16x16x32_bf16 v[132:135], v[112:115], v[160:163], v[132:135]
	v_mfma_f32_16x16x32_bf16 v[132:135], v[116:119], v[164:167], v[132:135]
	v_mfma_f32_16x16x32_bf16 v[128:131], v[140:143], v[164:167], v[128:131]
	v_mfma_f32_16x16x32_bf16 v[128:131], v[136:139], v[160:163], v[128:131]
	v_mfma_f32_16x16x32_bf16 v[104:107], v[136:139], v[168:171], v[104:107]
	v_mfma_f32_16x16x32_bf16 v[104:107], v[140:143], v[172:175], v[104:107]
	v_mfma_f32_16x16x32_bf16 v[108:111], v[116:119], v[172:175], v[108:111]
	v_mfma_f32_16x16x32_bf16 v[108:111], v[112:115], v[168:171], v[108:111]
	v_mfma_f32_16x16x32_bf16 v[92:95], v[112:115], v[206:209], v[92:95]
	v_mfma_f32_16x16x32_bf16 v[92:95], v[116:119], v[210:213], v[92:95]
	v_mfma_f32_16x16x32_bf16 v[88:91], v[140:143], v[210:213], v[88:91]
	v_mfma_f32_16x16x32_bf16 v[88:91], v[136:139], v[206:209], v[88:91]
	v_mfma_f32_16x16x32_bf16 v[72:75], v[136:139], v[214:217], v[72:75]
	v_mfma_f32_16x16x32_bf16 v[72:75], v[140:143], v[218:221], v[72:75]
	v_mfma_f32_16x16x32_bf16 v[76:79], v[116:119], v[218:221], v[76:79]
	v_mfma_f32_16x16x32_bf16 v[76:79], v[112:115], v[214:217], v[76:79]
	v_mfma_f32_16x16x32_bf16 v[68:71], v[144:147], v[214:217], v[68:71]
	v_mfma_f32_16x16x32_bf16 v[68:71], v[148:151], v[218:221], v[68:71]
	v_mfma_f32_16x16x32_bf16 v[64:67], v[156:159], v[218:221], v[64:67]
	v_mfma_f32_16x16x32_bf16 v[64:67], v[152:155], v[214:217], v[64:67]
	v_mfma_f32_16x16x32_bf16 v[80:83], v[152:155], v[206:209], v[80:83]
	v_mfma_f32_16x16x32_bf16 v[80:83], v[156:159], v[210:213], v[80:83]
	v_mfma_f32_16x16x32_bf16 v[84:87], v[148:151], v[210:213], v[84:87]
	v_mfma_f32_16x16x32_bf16 v[84:87], v[144:147], v[206:209], v[84:87]
	v_mfma_f32_16x16x32_bf16 v[100:103], v[144:147], v[168:171], v[100:103]
	v_mfma_f32_16x16x32_bf16 v[100:103], v[148:151], v[172:175], v[100:103]
	v_mfma_f32_16x16x32_bf16 v[96:99], v[156:159], v[172:175], v[96:99]
	v_mfma_f32_16x16x32_bf16 v[96:99], v[152:155], v[168:171], v[96:99]
	v_mfma_f32_16x16x32_bf16 v[120:123], v[152:155], v[160:163], v[120:123]
	v_mfma_f32_16x16x32_bf16 v[120:123], v[156:159], v[164:167], v[120:123]
	v_mfma_f32_16x16x32_bf16 v[124:127], v[148:151], v[164:167], v[124:127]
	v_mfma_f32_16x16x32_bf16 v[124:127], v[144:147], v[160:163], v[124:127]
	s_barrier
	s_setprio 0
	s_add_i32 s20, s83, s40
	v_lshl_add_u64 v[200:201], v[200:201], 0, s[14:15]
	s_mov_b32 m0, s20
	ds_read_b128 v[160:163], v205 offset:49152
	ds_read_b128 v[164:167], v205 offset:50176
	ds_read_b128 v[168:171], v205 offset:51200
	ds_read_b128 v[172:175], v205 offset:52224
	ds_read_b128 v[206:209], v205 offset:53248
	ds_read_b128 v[210:213], v205 offset:54272
	ds_read_b128 v[214:217], v205 offset:55296
	ds_read_b128 v[218:221], v205 offset:56320
	global_load_lds_dwordx4 v[200:201], off
	s_add_i32 m0, s20, 0x2000
	s_add_u32 s20, s26, 0xb0080
	v_lshl_add_u64 v[200:201], v[222:223], 0, s[14:15]
	s_addc_u32 s21, s27, 0
	s_add_i32 s26, s85, s40
	global_load_lds_dwordx4 v[200:201], off
	v_lshl_add_u64 v[200:201], s[20:21], 0, v[180:181]
	s_mov_b32 m0, s26
	s_nop 0
	global_load_lds_dwordx4 v[200:201], off
	v_lshl_add_u64 v[200:201], s[20:21], 0, v[176:177]
	s_add_i32 m0, s26, 0x2000
	s_nop 0
	global_load_lds_dwordx4 v[200:201], off
	v_lshl_add_u64 v[200:201], v[224:225], 0, s[14:15]
	s_mov_b32 m0, s52
	s_nop 0
	global_load_lds_dwordx4 v[200:201], off
	v_lshl_add_u64 v[200:201], v[226:227], 0, s[14:15]
	s_mov_b32 m0, s53
	s_nop 0
	global_load_lds_dwordx4 v[200:201], off
	s_waitcnt vmcnt(8)
	s_waitcnt lgkmcnt(0)
	s_setprio 1
	s_barrier
	v_mfma_f32_16x16x32_bf16 v[60:63], v[112:115], v[160:163], v[60:63]
	v_mfma_f32_16x16x32_bf16 v[60:63], v[116:119], v[164:167], v[60:63]
	v_mfma_f32_16x16x32_bf16 v[56:59], v[140:143], v[164:167], v[56:59]
	v_mfma_f32_16x16x32_bf16 v[56:59], v[136:139], v[160:163], v[56:59]
	v_mfma_f32_16x16x32_bf16 v[40:43], v[136:139], v[168:171], v[40:43]
	v_mfma_f32_16x16x32_bf16 v[40:43], v[140:143], v[172:175], v[40:43]
	v_mfma_f32_16x16x32_bf16 v[44:47], v[116:119], v[172:175], v[44:47]
	v_mfma_f32_16x16x32_bf16 v[44:47], v[112:115], v[168:171], v[44:47]
	v_mfma_f32_16x16x32_bf16 v[28:31], v[112:115], v[206:209], v[28:31]
	v_mfma_f32_16x16x32_bf16 v[28:31], v[116:119], v[210:213], v[28:31]
	v_mfma_f32_16x16x32_bf16 v[24:27], v[140:143], v[210:213], v[24:27]
	v_mfma_f32_16x16x32_bf16 v[24:27], v[136:139], v[206:209], v[24:27]
	v_mfma_f32_16x16x32_bf16 v[8:11], v[136:139], v[214:217], v[8:11]
	v_mfma_f32_16x16x32_bf16 v[8:11], v[140:143], v[218:221], v[8:11]
	v_mfma_f32_16x16x32_bf16 v[12:15], v[116:119], v[218:221], v[12:15]
	v_mfma_f32_16x16x32_bf16 v[12:15], v[112:115], v[214:217], v[12:15]
	v_mfma_f32_16x16x32_bf16 v[4:7], v[144:147], v[214:217], v[4:7]
	v_mfma_f32_16x16x32_bf16 v[4:7], v[148:151], v[218:221], v[4:7]
	v_mfma_f32_16x16x32_bf16 v[0:3], v[156:159], v[218:221], v[0:3]
	v_mfma_f32_16x16x32_bf16 v[0:3], v[152:155], v[214:217], v[0:3]
	v_mfma_f32_16x16x32_bf16 v[16:19], v[152:155], v[206:209], v[16:19]
	v_mfma_f32_16x16x32_bf16 v[16:19], v[156:159], v[210:213], v[16:19]
	v_mfma_f32_16x16x32_bf16 v[20:23], v[148:151], v[210:213], v[20:23]
	v_mfma_f32_16x16x32_bf16 v[20:23], v[144:147], v[206:209], v[20:23]
	v_mfma_f32_16x16x32_bf16 v[36:39], v[144:147], v[168:171], v[36:39]
	v_mfma_f32_16x16x32_bf16 v[36:39], v[148:151], v[172:175], v[36:39]
	v_mfma_f32_16x16x32_bf16 v[32:35], v[156:159], v[172:175], v[32:35]
	v_mfma_f32_16x16x32_bf16 v[32:35], v[152:155], v[168:171], v[32:35]
	v_mfma_f32_16x16x32_bf16 v[48:51], v[152:155], v[160:163], v[48:51]
	v_mfma_f32_16x16x32_bf16 v[48:51], v[156:159], v[164:167], v[48:51]
	v_mfma_f32_16x16x32_bf16 v[52:55], v[148:151], v[164:167], v[52:55]
	v_mfma_f32_16x16x32_bf16 v[52:55], v[144:147], v[160:163], v[52:55]
	s_barrier
	s_setprio 0
	s_add_i32 s82, s82, 2
	s_add_u32 s80, s80, 0x100
	s_addc_u32 s81, s81, 0
	s_cmp_gt_u32 s82, 41
	s_mov_b64 s[20:21], s[22:23]
.LBB0_836:
	ds_read_b128 v[112:115], v203
	ds_read_b128 v[116:119], v203 offset:1024
	ds_read_b128 v[136:139], v203 offset:2048
	ds_read_b128 v[140:143], v203 offset:3072
	ds_read_b128 v[144:147], v204
	ds_read_b128 v[148:151], v204 offset:1024
	ds_read_b128 v[152:155], v204 offset:2048
	ds_read_b128 v[156:159], v204 offset:3072
	s_add_u32 s22, s20, 0x100
	s_addc_u32 s23, s21, 0
	s_cmp_eq_u32 s82, 40
	s_cselect_b32 s37, s7, s23
	s_cselect_b32 s36, s6, s22
	s_cselect_b32 s27, s19, s81
	s_cselect_b32 s26, s18, s80
	v_lshl_add_u64 v[200:201], s[20:21], 0, v[186:187]
	s_add_i32 m0, s43, 0xc000
	ds_read_b128 v[160:163], v205
	ds_read_b128 v[164:167], v205 offset:1024
	ds_read_b128 v[168:171], v205 offset:2048
	ds_read_b128 v[172:175], v205 offset:3072
	ds_read_b128 v[206:209], v205 offset:4096
	ds_read_b128 v[210:213], v205 offset:5120
	ds_read_b128 v[214:217], v205 offset:6144
	ds_read_b128 v[218:221], v205 offset:7168
	global_load_lds_dwordx4 v[200:201], off
	v_lshl_add_u64 v[200:201], s[20:21], 0, v[188:189]
	s_add_i32 m0, s43, 0xe000
	s_nop 0
	global_load_lds_dwordx4 v[200:201], off
	s_waitcnt vmcnt(8)
	s_waitcnt lgkmcnt(0)
	s_setprio 1
	s_barrier
	v_mfma_f32_16x16x32_bf16 v[132:135], v[112:115], v[160:163], v[132:135]
	v_mfma_f32_16x16x32_bf16 v[132:135], v[116:119], v[164:167], v[132:135]
	v_mfma_f32_16x16x32_bf16 v[128:131], v[140:143], v[164:167], v[128:131]
	v_mfma_f32_16x16x32_bf16 v[128:131], v[136:139], v[160:163], v[128:131]
	v_mfma_f32_16x16x32_bf16 v[104:107], v[136:139], v[168:171], v[104:107]
	v_mfma_f32_16x16x32_bf16 v[104:107], v[140:143], v[172:175], v[104:107]
	v_mfma_f32_16x16x32_bf16 v[108:111], v[116:119], v[172:175], v[108:111]
	v_mfma_f32_16x16x32_bf16 v[108:111], v[112:115], v[168:171], v[108:111]
	v_mfma_f32_16x16x32_bf16 v[92:95], v[112:115], v[206:209], v[92:95]
	v_mfma_f32_16x16x32_bf16 v[92:95], v[116:119], v[210:213], v[92:95]
	v_mfma_f32_16x16x32_bf16 v[88:91], v[140:143], v[210:213], v[88:91]
	v_mfma_f32_16x16x32_bf16 v[88:91], v[136:139], v[206:209], v[88:91]
	v_mfma_f32_16x16x32_bf16 v[72:75], v[136:139], v[214:217], v[72:75]
	v_mfma_f32_16x16x32_bf16 v[72:75], v[140:143], v[218:221], v[72:75]
	v_mfma_f32_16x16x32_bf16 v[76:79], v[116:119], v[218:221], v[76:79]
	v_mfma_f32_16x16x32_bf16 v[76:79], v[112:115], v[214:217], v[76:79]
	v_mfma_f32_16x16x32_bf16 v[68:71], v[144:147], v[214:217], v[68:71]
	v_mfma_f32_16x16x32_bf16 v[68:71], v[148:151], v[218:221], v[68:71]
	v_mfma_f32_16x16x32_bf16 v[64:67], v[156:159], v[218:221], v[64:67]
	v_mfma_f32_16x16x32_bf16 v[64:67], v[152:155], v[214:217], v[64:67]
	v_mfma_f32_16x16x32_bf16 v[80:83], v[152:155], v[206:209], v[80:83]
	v_mfma_f32_16x16x32_bf16 v[80:83], v[156:159], v[210:213], v[80:83]
	v_mfma_f32_16x16x32_bf16 v[84:87], v[148:151], v[210:213], v[84:87]
	v_mfma_f32_16x16x32_bf16 v[84:87], v[144:147], v[206:209], v[84:87]
	v_mfma_f32_16x16x32_bf16 v[100:103], v[144:147], v[168:171], v[100:103]
	v_mfma_f32_16x16x32_bf16 v[100:103], v[148:151], v[172:175], v[100:103]
	v_mfma_f32_16x16x32_bf16 v[96:99], v[156:159], v[172:175], v[96:99]
	v_mfma_f32_16x16x32_bf16 v[96:99], v[152:155], v[168:171], v[96:99]
	v_mfma_f32_16x16x32_bf16 v[120:123], v[152:155], v[160:163], v[120:123]
	v_mfma_f32_16x16x32_bf16 v[120:123], v[156:159], v[164:167], v[120:123]
	v_mfma_f32_16x16x32_bf16 v[124:127], v[148:151], v[164:167], v[124:127]
	v_mfma_f32_16x16x32_bf16 v[124:127], v[144:147], v[160:163], v[124:127]
	s_barrier
	s_setprio 0
	s_add_i32 s20, s59, s40
	v_lshl_add_u64 v[200:201], s[26:27], 0, v[180:181]
	s_mov_b32 m0, s20
	ds_read_b128 v[160:163], v205 offset:16384
	ds_read_b128 v[164:167], v205 offset:17408
	ds_read_b128 v[168:171], v205 offset:18432
	ds_read_b128 v[172:175], v205 offset:19456
	ds_read_b128 v[206:209], v205 offset:20480
	ds_read_b128 v[210:213], v205 offset:21504
	ds_read_b128 v[214:217], v205 offset:22528
	ds_read_b128 v[218:221], v205 offset:23552
	global_load_lds_dwordx4 v[200:201], off
	s_add_i32 m0, s20, 0x2000
	s_add_u32 s20, s26, 0xb0000
	v_lshl_add_u64 v[222:223], s[26:27], 0, v[176:177]
	s_addc_u32 s21, s27, 0
	s_add_i32 s83, s66, s40
	global_load_lds_dwordx4 v[222:223], off
	v_lshl_add_u64 v[224:225], s[20:21], 0, v[180:181]
	s_mov_b32 m0, s83
	v_lshl_add_u64 v[226:227], s[36:37], 0, v[178:179]
	global_load_lds_dwordx4 v[224:225], off
	v_lshl_add_u64 v[224:225], s[20:21], 0, v[176:177]
	s_add_i32 m0, s83, 0x2000
	s_nop 0
	global_load_lds_dwordx4 v[224:225], off
	v_lshl_add_u64 v[224:225], s[36:37], 0, v[182:183]
	s_mov_b32 m0, s43
	s_nop 0
	global_load_lds_dwordx4 v[224:225], off
	s_mov_b32 m0, s44
	s_nop 0
	global_load_lds_dwordx4 v[226:227], off
	s_waitcnt vmcnt(8)
	s_waitcnt lgkmcnt(0)
	s_setprio 1
	s_barrier
	v_mfma_f32_16x16x32_bf16 v[60:63], v[112:115], v[160:163], v[60:63]
	v_mfma_f32_16x16x32_bf16 v[60:63], v[116:119], v[164:167], v[60:63]
	v_mfma_f32_16x16x32_bf16 v[56:59], v[140:143], v[164:167], v[56:59]
	v_mfma_f32_16x16x32_bf16 v[56:59], v[136:139], v[160:163], v[56:59]
	v_mfma_f32_16x16x32_bf16 v[40:43], v[136:139], v[168:171], v[40:43]
	v_mfma_f32_16x16x32_bf16 v[40:43], v[140:143], v[172:175], v[40:43]
	v_mfma_f32_16x16x32_bf16 v[44:47], v[116:119], v[172:175], v[44:47]
	v_mfma_f32_16x16x32_bf16 v[44:47], v[112:115], v[168:171], v[44:47]
	v_mfma_f32_16x16x32_bf16 v[28:31], v[112:115], v[206:209], v[28:31]
	v_mfma_f32_16x16x32_bf16 v[28:31], v[116:119], v[210:213], v[28:31]
	v_mfma_f32_16x16x32_bf16 v[24:27], v[140:143], v[210:213], v[24:27]
	v_mfma_f32_16x16x32_bf16 v[24:27], v[136:139], v[206:209], v[24:27]
	v_mfma_f32_16x16x32_bf16 v[8:11], v[136:139], v[214:217], v[8:11]
	v_mfma_f32_16x16x32_bf16 v[8:11], v[140:143], v[218:221], v[8:11]
	v_mfma_f32_16x16x32_bf16 v[12:15], v[116:119], v[218:221], v[12:15]
	v_mfma_f32_16x16x32_bf16 v[12:15], v[112:115], v[214:217], v[12:15]
	v_mfma_f32_16x16x32_bf16 v[4:7], v[144:147], v[214:217], v[4:7]
	v_mfma_f32_16x16x32_bf16 v[4:7], v[148:151], v[218:221], v[4:7]
	v_mfma_f32_16x16x32_bf16 v[0:3], v[156:159], v[218:221], v[0:3]
	v_mfma_f32_16x16x32_bf16 v[0:3], v[152:155], v[214:217], v[0:3]
	v_mfma_f32_16x16x32_bf16 v[16:19], v[152:155], v[206:209], v[16:19]
	v_mfma_f32_16x16x32_bf16 v[16:19], v[156:159], v[210:213], v[16:19]
	v_mfma_f32_16x16x32_bf16 v[20:23], v[148:151], v[210:213], v[20:23]
	v_mfma_f32_16x16x32_bf16 v[20:23], v[144:147], v[206:209], v[20:23]
	v_mfma_f32_16x16x32_bf16 v[36:39], v[144:147], v[168:171], v[36:39]
	v_mfma_f32_16x16x32_bf16 v[36:39], v[148:151], v[172:175], v[36:39]
	v_mfma_f32_16x16x32_bf16 v[32:35], v[156:159], v[172:175], v[32:35]
	v_mfma_f32_16x16x32_bf16 v[32:35], v[152:155], v[168:171], v[32:35]
	v_mfma_f32_16x16x32_bf16 v[48:51], v[152:155], v[160:163], v[48:51]
	v_mfma_f32_16x16x32_bf16 v[48:51], v[156:159], v[164:167], v[48:51]
	v_mfma_f32_16x16x32_bf16 v[52:55], v[148:151], v[164:167], v[52:55]
	v_mfma_f32_16x16x32_bf16 v[52:55], v[144:147], v[160:163], v[52:55]
	s_barrier
	s_setprio 0
	s_add_i32 s83, 0, 0x18000
	s_add_i32 s85, 0, 0x1c000
	v_add_u32_e32 v140, s83, v202
	v_add_u32_e32 v156, s85, v202
	ds_read_b128 v[112:115], v140
	ds_read_b128 v[116:119], v140 offset:1024
	ds_read_b128 v[136:139], v140 offset:2048
	ds_read_b128 v[140:143], v140 offset:3072
	ds_read_b128 v[144:147], v156
	ds_read_b128 v[148:151], v156 offset:1024
	ds_read_b128 v[152:155], v156 offset:2048
	ds_read_b128 v[156:159], v156 offset:3072
	s_add_u32 s20, s36, 0xb0000
	s_addc_u32 s21, s37, 0
	s_mov_b32 m0, s45
	v_lshl_add_u64 v[230:231], s[20:21], 0, v[182:183]
	ds_read_b128 v[160:163], v205 offset:32768
	ds_read_b128 v[164:167], v205 offset:33792
	ds_read_b128 v[168:171], v205 offset:34816
	ds_read_b128 v[172:175], v205 offset:35840
	ds_read_b128 v[206:209], v205 offset:36864
	ds_read_b128 v[210:213], v205 offset:37888
	ds_read_b128 v[214:217], v205 offset:38912
	ds_read_b128 v[218:221], v205 offset:39936
	global_load_lds_dwordx4 v[230:231], off
	v_lshl_add_u64 v[230:231], s[20:21], 0, v[178:179]
	s_mov_b32 m0, s46
	s_nop 0
	global_load_lds_dwordx4 v[230:231], off
	s_waitcnt vmcnt(8)
	s_waitcnt lgkmcnt(0)
	s_setprio 1
	s_barrier
	v_mfma_f32_16x16x32_bf16 v[132:135], v[112:115], v[160:163], v[132:135]
	v_mfma_f32_16x16x32_bf16 v[132:135], v[116:119], v[164:167], v[132:135]
	v_mfma_f32_16x16x32_bf16 v[128:131], v[140:143], v[164:167], v[128:131]
	v_mfma_f32_16x16x32_bf16 v[128:131], v[136:139], v[160:163], v[128:131]
	v_mfma_f32_16x16x32_bf16 v[104:107], v[136:139], v[168:171], v[104:107]
	v_mfma_f32_16x16x32_bf16 v[104:107], v[140:143], v[172:175], v[104:107]
	v_mfma_f32_16x16x32_bf16 v[108:111], v[116:119], v[172:175], v[108:111]
	v_mfma_f32_16x16x32_bf16 v[108:111], v[112:115], v[168:171], v[108:111]
	v_mfma_f32_16x16x32_bf16 v[92:95], v[112:115], v[206:209], v[92:95]
	v_mfma_f32_16x16x32_bf16 v[92:95], v[116:119], v[210:213], v[92:95]
	v_mfma_f32_16x16x32_bf16 v[88:91], v[140:143], v[210:213], v[88:91]
	v_mfma_f32_16x16x32_bf16 v[88:91], v[136:139], v[206:209], v[88:91]
	v_mfma_f32_16x16x32_bf16 v[72:75], v[136:139], v[214:217], v[72:75]
	v_mfma_f32_16x16x32_bf16 v[72:75], v[140:143], v[218:221], v[72:75]
	v_mfma_f32_16x16x32_bf16 v[76:79], v[116:119], v[218:221], v[76:79]
	v_mfma_f32_16x16x32_bf16 v[76:79], v[112:115], v[214:217], v[76:79]
	v_mfma_f32_16x16x32_bf16 v[68:71], v[144:147], v[214:217], v[68:71]
	v_mfma_f32_16x16x32_bf16 v[68:71], v[148:151], v[218:221], v[68:71]
	v_mfma_f32_16x16x32_bf16 v[64:67], v[156:159], v[218:221], v[64:67]
	v_mfma_f32_16x16x32_bf16 v[64:67], v[152:155], v[214:217], v[64:67]
	v_mfma_f32_16x16x32_bf16 v[80:83], v[152:155], v[206:209], v[80:83]
	v_mfma_f32_16x16x32_bf16 v[80:83], v[156:159], v[210:213], v[80:83]
	v_mfma_f32_16x16x32_bf16 v[84:87], v[148:151], v[210:213], v[84:87]
	v_mfma_f32_16x16x32_bf16 v[84:87], v[144:147], v[206:209], v[84:87]
	v_mfma_f32_16x16x32_bf16 v[100:103], v[144:147], v[168:171], v[100:103]
	v_mfma_f32_16x16x32_bf16 v[100:103], v[148:151], v[172:175], v[100:103]
	v_mfma_f32_16x16x32_bf16 v[96:99], v[156:159], v[172:175], v[96:99]
	v_mfma_f32_16x16x32_bf16 v[96:99], v[152:155], v[168:171], v[96:99]
	v_mfma_f32_16x16x32_bf16 v[120:123], v[152:155], v[160:163], v[120:123]
	v_mfma_f32_16x16x32_bf16 v[120:123], v[156:159], v[164:167], v[120:123]
	v_mfma_f32_16x16x32_bf16 v[124:127], v[148:151], v[164:167], v[124:127]
	v_mfma_f32_16x16x32_bf16 v[124:127], v[144:147], v[160:163], v[124:127]
	s_barrier
	s_setprio 0
	s_add_i32 s20, s83, s40
	v_lshl_add_u64 v[200:201], v[200:201], 0, s[14:15]
	s_mov_b32 m0, s20
	ds_read_b128 v[160:163], v205 offset:49152
	ds_read_b128 v[164:167], v205 offset:50176
	ds_read_b128 v[168:171], v205 offset:51200
	ds_read_b128 v[172:175], v205 offset:52224
	ds_read_b128 v[206:209], v205 offset:53248
	ds_read_b128 v[210:213], v205 offset:54272
	ds_read_b128 v[214:217], v205 offset:55296
	ds_read_b128 v[218:221], v205 offset:56320
	global_load_lds_dwordx4 v[200:201], off
	s_add_i32 m0, s20, 0x2000
	s_add_u32 s20, s26, 0xb0080
	v_lshl_add_u64 v[200:201], v[222:223], 0, s[14:15]
	s_addc_u32 s21, s27, 0
	s_add_i32 s26, s85, s40
	global_load_lds_dwordx4 v[200:201], off
	v_lshl_add_u64 v[200:201], s[20:21], 0, v[180:181]
	s_mov_b32 m0, s26
	s_nop 0
	global_load_lds_dwordx4 v[200:201], off
	v_lshl_add_u64 v[200:201], s[20:21], 0, v[176:177]
	s_add_i32 m0, s26, 0x2000
	s_nop 0
	global_load_lds_dwordx4 v[200:201], off
	v_lshl_add_u64 v[200:201], v[224:225], 0, s[14:15]
	s_mov_b32 m0, s52
	s_nop 0
	global_load_lds_dwordx4 v[200:201], off
	v_lshl_add_u64 v[200:201], v[226:227], 0, s[14:15]
	s_mov_b32 m0, s53
	s_nop 0
	global_load_lds_dwordx4 v[200:201], off
	s_waitcnt vmcnt(8)
	s_waitcnt lgkmcnt(0)
	s_setprio 1
	s_barrier
	v_mfma_f32_16x16x32_bf16 v[60:63], v[112:115], v[160:163], v[60:63]
	v_mfma_f32_16x16x32_bf16 v[60:63], v[116:119], v[164:167], v[60:63]
	v_mfma_f32_16x16x32_bf16 v[56:59], v[140:143], v[164:167], v[56:59]
	v_mfma_f32_16x16x32_bf16 v[56:59], v[136:139], v[160:163], v[56:59]
	v_mfma_f32_16x16x32_bf16 v[40:43], v[136:139], v[168:171], v[40:43]
	v_mfma_f32_16x16x32_bf16 v[40:43], v[140:143], v[172:175], v[40:43]
	v_mfma_f32_16x16x32_bf16 v[44:47], v[116:119], v[172:175], v[44:47]
	v_mfma_f32_16x16x32_bf16 v[44:47], v[112:115], v[168:171], v[44:47]
	v_mfma_f32_16x16x32_bf16 v[28:31], v[112:115], v[206:209], v[28:31]
	v_mfma_f32_16x16x32_bf16 v[28:31], v[116:119], v[210:213], v[28:31]
	v_mfma_f32_16x16x32_bf16 v[24:27], v[140:143], v[210:213], v[24:27]
	v_mfma_f32_16x16x32_bf16 v[24:27], v[136:139], v[206:209], v[24:27]
	v_mfma_f32_16x16x32_bf16 v[8:11], v[136:139], v[214:217], v[8:11]
	v_mfma_f32_16x16x32_bf16 v[8:11], v[140:143], v[218:221], v[8:11]
	v_mfma_f32_16x16x32_bf16 v[12:15], v[116:119], v[218:221], v[12:15]
	v_mfma_f32_16x16x32_bf16 v[12:15], v[112:115], v[214:217], v[12:15]
	v_mfma_f32_16x16x32_bf16 v[4:7], v[144:147], v[214:217], v[4:7]
	v_mfma_f32_16x16x32_bf16 v[4:7], v[148:151], v[218:221], v[4:7]
	v_mfma_f32_16x16x32_bf16 v[0:3], v[156:159], v[218:221], v[0:3]
	v_mfma_f32_16x16x32_bf16 v[0:3], v[152:155], v[214:217], v[0:3]
	v_mfma_f32_16x16x32_bf16 v[16:19], v[152:155], v[206:209], v[16:19]
	v_mfma_f32_16x16x32_bf16 v[16:19], v[156:159], v[210:213], v[16:19]
	v_mfma_f32_16x16x32_bf16 v[20:23], v[148:151], v[210:213], v[20:23]
	v_mfma_f32_16x16x32_bf16 v[20:23], v[144:147], v[206:209], v[20:23]
	v_mfma_f32_16x16x32_bf16 v[36:39], v[144:147], v[168:171], v[36:39]
	v_mfma_f32_16x16x32_bf16 v[36:39], v[148:151], v[172:175], v[36:39]
	v_mfma_f32_16x16x32_bf16 v[32:35], v[156:159], v[172:175], v[32:35]
	v_mfma_f32_16x16x32_bf16 v[32:35], v[152:155], v[168:171], v[32:35]
	v_mfma_f32_16x16x32_bf16 v[48:51], v[152:155], v[160:163], v[48:51]
	v_mfma_f32_16x16x32_bf16 v[48:51], v[156:159], v[164:167], v[48:51]
	v_mfma_f32_16x16x32_bf16 v[52:55], v[148:151], v[164:167], v[52:55]
	v_mfma_f32_16x16x32_bf16 v[52:55], v[144:147], v[160:163], v[52:55]
	s_barrier
	s_setprio 0
	s_add_i32 s82, s82, 2
	s_add_u32 s80, s80, 0x100
	s_addc_u32 s81, s81, 0
	s_cmp_gt_u32 s82, 41
	s_mov_b64 s[20:21], s[22:23]
	s_cbranch_scc0 .LBB0_836
	s_and_b64 vcc, exec, s[16:17]
	s_cbranch_vccz .LBB0_839
	s_barrier
